# main loops: removed all s_setprio toggles around the MMA sections (on top of v3)
# speedup vs baseline: 1.0078x; 1.0078x over previous
; #define LAS __attribute__((address_space(3)))
; #define PG8_STAGE(bufoff, gbase, voff) do { _Pragma("unroll") for (int _i = 0; _i < 2; ++_i) \
;         __builtin_amdgcn_global_load_lds((const unsigned*)((const char*)(gbase) + (voff)[_i]), (LAS unsigned*)(lds + (bufoff) + ldsw + _i * 8192), 16, 0, 0); } while (0)
; #define PG8_LDA(dst, b, h) do { _Pragma("unroll") for (int m = 0; m < 4; ++m) _Pragma("unroll") for (int k = 0; k < 2; ++k) dst[m][k] = *(const LAS bf16x8*)(lds + PG8_SA(b, h) + aoff + m * 2048 + k * 1024); } while (0)
; #define PG8_LDB(dst, b, h) do { _Pragma("unroll") for (int n = 0; n < 2; ++n) _Pragma("unroll") for (int k = 0; k < 2; ++k) dst[n][k] = *(const LAS bf16x8*)(lds + PG8_SB(b, h) + boff + n * 2048 + k * 1024); } while (0)
; #define PG8_WAIT_V(n) asm volatile("s_waitcnt vmcnt(" #n ")" ::: "memory")
; #define PG8_WAIT_L(n) asm volatile("s_waitcnt lgkmcnt(" #n ")" ::: "memory")
; template <class Epi>
; __device__ __forceinline__ void gemm_phase(LAS unsigned char* lds, const int tid, const Gemm g, const StaticOrder& S, const Epi& E) {
;     ...
;         for (int t = 0; t < nt; t += 2) {
;             const bool last = (t == nt - 2);
;             const char* a1 = cA + (size_t)(t + 1) * kstep;
;             const char* a2 = last ? nA : cA + (size_t)(t + 2) * kstep; const char* b2 = last ? nB : cB + (size_t)(t + 2) * kstep;
;             const char* a3 = a2 + kstep; const char* b3 = b2 + kstep;
;             if constexpr (Epi::SS_LDS) { if (last) {
;                 const char* sp = (const char*)E.ss + (size_t)cur.pm * (256 * 64) + (size_t)tid * 16;
;                 __builtin_amdgcn_global_load_lds((const unsigned*)sp, (LAS unsigned*)(lds + RS_OFF + ldsw), 16, 0, 0);
;                 __builtin_amdgcn_global_load_lds((const unsigned*)(sp + 8192), (LAS unsigned*)(lds + RS_OFF + 8192 + ldsw), 16, 0, 0); } }
;     ...
;             PG8_LDB(B0, 0, 0); PG8_LDB(B1, 0, 1); PG8_SCHED; PG8_LDA(At, 0, 0); PG8_STAGE(PG8_SA(1, 1), a1 + hstepA, voffA);
;             PG8_WAIT_V(8); PG8_WAIT_L(0); PG8_BAR; PG8_MMA(0, 0, At, B0); PG8_MMA(0, 1, At, B1); PG8_BAR; PG8_SCHED;
;             PG8_LDA(At, 0, 1); PG8_STAGE(PG8_SB(0, 0), b2, voffB); PG8_STAGE(PG8_SB(0, 1), b2 + hstepB, voffB); PG8_STAGE(PG8_SA(0, 0), a2, voffA);
;             PG8_WAIT_V(8); PG8_WAIT_L(0); PG8_BAR; PG8_MMA(1, 0, At, B0); PG8_MMA(1, 1, At, B1); PG8_BAR; PG8_SCHED;
.LBB0_263:
	v_add_u32_e32 v168, s51, v151
	v_add_u32_e32 v184, s52, v151
	ds_read_b128 v[156:159], v168
	ds_read_b128 v[160:163], v168 offset:1024
	ds_read_b128 v[164:167], v168 offset:2048
	ds_read_b128 v[168:171], v168 offset:3072
	ds_read_b128 v[172:175], v184
	ds_read_b128 v[176:179], v184 offset:1024
	ds_read_b128 v[180:183], v184 offset:2048
	ds_read_b128 v[184:187], v184 offset:3072
	s_add_i32 s58, s58, 2
	s_add_u32 s30, s26, 0xfffc0080
	s_addc_u32 s31, s27, -1
	s_and_b64 s[28:29], s[28:29], exec
	s_cselect_b32 s31, s17, s31
	s_cselect_b32 s30, s19, s30
	s_cselect_b32 s29, s55, s57
	s_cselect_b32 s28, s56, s25
	v_lshl_add_u64 v[220:221], s[26:27], 0, v[140:141]
	s_add_i32 m0, s41, 0xc000
	ds_read_b128 v[188:191], v153
	ds_read_b128 v[192:195], v153 offset:1024
	ds_read_b128 v[196:199], v153 offset:2048
	ds_read_b128 v[200:203], v153 offset:3072
	ds_read_b128 v[204:207], v153 offset:4096
	ds_read_b128 v[208:211], v153 offset:5120
	ds_read_b128 v[212:215], v153 offset:6144
	ds_read_b128 v[216:219], v153 offset:7168
	global_load_lds_dwordx4 v[220:221], off
	v_lshl_add_u64 v[220:221], s[26:27], 0, v[138:139]
	s_add_i32 m0, s41, 0xe000
	s_nop 0
	global_load_lds_dwordx4 v[220:221], off
	s_waitcnt vmcnt(8)
	s_waitcnt lgkmcnt(0)
	s_barrier
	v_mfma_f32_16x16x32_bf16 v[120:123], v[156:159], v[188:191], v[120:123]
	v_mfma_f32_16x16x32_bf16 v[116:119], v[164:167], v[188:191], v[116:119]
	v_mfma_f32_16x16x32_bf16 v[108:111], v[156:159], v[196:199], v[108:111]
	v_mfma_f32_16x16x32_bf16 v[100:103], v[164:167], v[196:199], v[100:103]
	v_mfma_f32_16x16x32_bf16 v[92:95], v[156:159], v[204:207], v[92:95]
	v_mfma_f32_16x16x32_bf16 v[84:87], v[164:167], v[204:207], v[84:87]
	v_mfma_f32_16x16x32_bf16 v[76:79], v[156:159], v[212:215], v[76:79]
	v_mfma_f32_16x16x32_bf16 v[68:71], v[164:167], v[212:215], v[68:71]
	v_mfma_f32_16x16x32_bf16 v[120:123], v[160:163], v[192:195], v[120:123]
	v_mfma_f32_16x16x32_bf16 v[116:119], v[168:171], v[192:195], v[116:119]
	v_mfma_f32_16x16x32_bf16 v[108:111], v[160:163], v[200:203], v[108:111]
	v_mfma_f32_16x16x32_bf16 v[100:103], v[168:171], v[200:203], v[100:103]
	v_mfma_f32_16x16x32_bf16 v[92:95], v[160:163], v[208:211], v[92:95]
	v_mfma_f32_16x16x32_bf16 v[84:87], v[168:171], v[208:211], v[84:87]
	v_mfma_f32_16x16x32_bf16 v[76:79], v[160:163], v[216:219], v[76:79]
	v_mfma_f32_16x16x32_bf16 v[68:71], v[168:171], v[216:219], v[68:71]
	v_mfma_f32_16x16x32_bf16 v[124:127], v[172:175], v[188:191], v[124:127]
	v_mfma_f32_16x16x32_bf16 v[112:115], v[180:183], v[188:191], v[112:115]
	v_mfma_f32_16x16x32_bf16 v[104:107], v[172:175], v[196:199], v[104:107]
	v_mfma_f32_16x16x32_bf16 v[96:99], v[180:183], v[196:199], v[96:99]
	v_mfma_f32_16x16x32_bf16 v[88:91], v[172:175], v[204:207], v[88:91]
	v_mfma_f32_16x16x32_bf16 v[80:83], v[180:183], v[204:207], v[80:83]
	v_mfma_f32_16x16x32_bf16 v[72:75], v[172:175], v[212:215], v[72:75]
	v_mfma_f32_16x16x32_bf16 v[64:67], v[180:183], v[212:215], v[64:67]
	v_mfma_f32_16x16x32_bf16 v[124:127], v[176:179], v[192:195], v[124:127]
	v_mfma_f32_16x16x32_bf16 v[112:115], v[184:187], v[192:195], v[112:115]
	v_mfma_f32_16x16x32_bf16 v[104:107], v[176:179], v[200:203], v[104:107]
	v_mfma_f32_16x16x32_bf16 v[96:99], v[184:187], v[200:203], v[96:99]
	v_mfma_f32_16x16x32_bf16 v[88:91], v[176:179], v[208:211], v[88:91]
	v_mfma_f32_16x16x32_bf16 v[80:83], v[184:187], v[208:211], v[80:83]
	v_mfma_f32_16x16x32_bf16 v[72:75], v[176:179], v[216:219], v[72:75]
	v_mfma_f32_16x16x32_bf16 v[64:67], v[184:187], v[216:219], v[64:67]
	s_barrier
	s_add_i32 s59, s51, s38
	v_lshl_add_u64 v[220:221], s[28:29], 0, v[132:133]
	s_mov_b32 m0, s59
	ds_read_b128 v[188:191], v153 offset:16384
	ds_read_b128 v[192:195], v153 offset:17408
	ds_read_b128 v[196:199], v153 offset:18432
	ds_read_b128 v[200:203], v153 offset:19456
	ds_read_b128 v[204:207], v153 offset:20480
	ds_read_b128 v[208:211], v153 offset:21504
	ds_read_b128 v[212:215], v153 offset:22528
	ds_read_b128 v[216:219], v153 offset:23552
	global_load_lds_dwordx4 v[220:221], off
	s_add_i32 m0, s59, 0x2000
	s_add_u32 s60, s28, 0x40000
	v_lshl_add_u64 v[222:223], s[28:29], 0, v[128:129]
	s_addc_u32 s61, s29, 0
	s_add_i32 s59, s52, s38
	global_load_lds_dwordx4 v[222:223], off
	v_lshl_add_u64 v[224:225], s[60:61], 0, v[132:133]
	s_mov_b32 m0, s59
	v_lshl_add_u64 v[226:227], s[30:31], 0, v[130:131]
	global_load_lds_dwordx4 v[224:225], off
	v_lshl_add_u64 v[224:225], s[60:61], 0, v[128:129]
	s_add_i32 m0, s59, 0x2000
	s_nop 0
	global_load_lds_dwordx4 v[224:225], off
	v_lshl_add_u64 v[224:225], s[30:31], 0, v[134:135]
	s_mov_b32 m0, s41
	s_nop 0
	global_load_lds_dwordx4 v[224:225], off
	s_mov_b32 m0, s42
	s_nop 0
	global_load_lds_dwordx4 v[226:227], off
	s_waitcnt vmcnt(8)
	s_waitcnt lgkmcnt(0)
	s_barrier
; #define PG8_STAGE(bufoff, gbase, voff) do { _Pragma("unroll") for (int _i = 0; _i < 2; ++_i) \
;         __builtin_amdgcn_global_load_lds((const unsigned*)((const char*)(gbase) + (voff)[_i]), (LAS unsigned*)(lds + (bufoff) + ldsw + _i * 8192), 16, 0, 0); } while (0)
; #define PG8_LDA(dst, b, h) do { _Pragma("unroll") for (int m = 0; m < 4; ++m) _Pragma("unroll") for (int k = 0; k < 2; ++k) dst[m][k] = *(const LAS bf16x8*)(lds + PG8_SA(b, h) + aoff + m * 2048 + k * 1024); } while (0)
; #define PG8_LDB(dst, b, h) do { _Pragma("unroll") for (int n = 0; n < 2; ++n) _Pragma("unroll") for (int k = 0; k < 2; ++k) dst[n][k] = *(const LAS bf16x8*)(lds + PG8_SB(b, h) + boff + n * 2048 + k * 1024); } while (0)
; #define PG8_MMA(ai, bj, At, Bt) do { __builtin_amdgcn_s_setprio(1); _Pragma("unroll") for (int m = 0; m < 4; ++m) _Pragma("unroll") for (int n = 0; n < 2; ++n) _Pragma("unroll") for (int k = 0; k < 2; ++k) \
;         acc[ai][bj][m][n] = __builtin_amdgcn_mfma_f32_16x16x32_bf16(Bt[n][k], At[m][k], acc[ai][bj][m][n], 0, 0, 0); __builtin_amdgcn_s_setprio(0); } while (0)
; #define PG8_WAIT_V(n) asm volatile("s_waitcnt vmcnt(" #n ")" ::: "memory")
; #define PG8_WAIT_L(n) asm volatile("s_waitcnt lgkmcnt(" #n ")" ::: "memory")
; #define PG8_BAR __builtin_amdgcn_s_barrier()
; #define PG8_SCHED __builtin_amdgcn_sched_barrier(0)
; template <class Epi>
; __device__ __forceinline__ void gemm_phase(LAS unsigned char* lds, const int tid, const Gemm g, const StaticOrder& S, const Epi& E) {
;     ...
;             PG8_WAIT_V(8); PG8_WAIT_L(0); PG8_BAR; PG8_MMA(1, 0, At, B0); PG8_MMA(1, 1, At, B1); PG8_BAR; PG8_SCHED;
;             PG8_LDB(B0, 1, 0); PG8_LDB(B1, 1, 1); PG8_SCHED; PG8_LDA(At, 1, 0); PG8_STAGE(PG8_SA(0, 1), a2 + hstepA, voffA);
;             PG8_WAIT_V(8); PG8_WAIT_L(0); PG8_BAR; PG8_MMA(0, 0, At, B0); PG8_MMA(0, 1, At, B1); PG8_BAR; PG8_SCHED;
	v_mfma_f32_16x16x32_bf16 v[60:63], v[156:159], v[188:191], v[60:63]
	v_mfma_f32_16x16x32_bf16 v[52:55], v[164:167], v[188:191], v[52:55]
	v_mfma_f32_16x16x32_bf16 v[44:47], v[156:159], v[196:199], v[44:47]
	v_mfma_f32_16x16x32_bf16 v[36:39], v[164:167], v[196:199], v[36:39]
	v_mfma_f32_16x16x32_bf16 v[28:31], v[156:159], v[204:207], v[28:31]
	v_mfma_f32_16x16x32_bf16 v[20:23], v[164:167], v[204:207], v[20:23]
	v_mfma_f32_16x16x32_bf16 v[12:15], v[156:159], v[212:215], v[12:15]
	v_mfma_f32_16x16x32_bf16 v[4:7], v[164:167], v[212:215], v[4:7]
	v_mfma_f32_16x16x32_bf16 v[60:63], v[160:163], v[192:195], v[60:63]
	v_mfma_f32_16x16x32_bf16 v[52:55], v[168:171], v[192:195], v[52:55]
	v_mfma_f32_16x16x32_bf16 v[44:47], v[160:163], v[200:203], v[44:47]
	v_mfma_f32_16x16x32_bf16 v[36:39], v[168:171], v[200:203], v[36:39]
	v_mfma_f32_16x16x32_bf16 v[28:31], v[160:163], v[208:211], v[28:31]
	v_mfma_f32_16x16x32_bf16 v[20:23], v[168:171], v[208:211], v[20:23]
	v_mfma_f32_16x16x32_bf16 v[12:15], v[160:163], v[216:219], v[12:15]
	v_mfma_f32_16x16x32_bf16 v[4:7], v[168:171], v[216:219], v[4:7]
	v_mfma_f32_16x16x32_bf16 v[56:59], v[172:175], v[188:191], v[56:59]
	v_mfma_f32_16x16x32_bf16 v[48:51], v[180:183], v[188:191], v[48:51]
	v_mfma_f32_16x16x32_bf16 v[40:43], v[172:175], v[196:199], v[40:43]
	v_mfma_f32_16x16x32_bf16 v[32:35], v[180:183], v[196:199], v[32:35]
	v_mfma_f32_16x16x32_bf16 v[24:27], v[172:175], v[204:207], v[24:27]
	v_mfma_f32_16x16x32_bf16 v[16:19], v[180:183], v[204:207], v[16:19]
	v_mfma_f32_16x16x32_bf16 v[8:11], v[172:175], v[212:215], v[8:11]
	v_mfma_f32_16x16x32_bf16 v[0:3], v[180:183], v[212:215], v[0:3]
	v_mfma_f32_16x16x32_bf16 v[56:59], v[176:179], v[192:195], v[56:59]
	v_mfma_f32_16x16x32_bf16 v[48:51], v[184:187], v[192:195], v[48:51]
	v_mfma_f32_16x16x32_bf16 v[40:43], v[176:179], v[200:203], v[40:43]
	v_mfma_f32_16x16x32_bf16 v[32:35], v[184:187], v[200:203], v[32:35]
	v_mfma_f32_16x16x32_bf16 v[24:27], v[176:179], v[208:211], v[24:27]
	v_mfma_f32_16x16x32_bf16 v[16:19], v[184:187], v[208:211], v[16:19]
	v_mfma_f32_16x16x32_bf16 v[8:11], v[176:179], v[216:219], v[8:11]
	v_mfma_f32_16x16x32_bf16 v[0:3], v[184:187], v[216:219], v[0:3]
	s_barrier
	s_add_i32 s59, 0, 0x18000
	s_add_i32 s60, 0, 0x1c000
	v_add_u32_e32 v168, s59, v151
	v_add_u32_e32 v184, s60, v151
	ds_read_b128 v[156:159], v168
	ds_read_b128 v[160:163], v168 offset:1024
	ds_read_b128 v[164:167], v168 offset:2048
	ds_read_b128 v[168:171], v168 offset:3072
	ds_read_b128 v[172:175], v184
	ds_read_b128 v[176:179], v184 offset:1024
	ds_read_b128 v[180:183], v184 offset:2048
	ds_read_b128 v[184:187], v184 offset:3072
	s_add_u32 s30, s30, 0x40000
	s_addc_u32 s31, s31, 0
	s_mov_b32 m0, s43
	v_lshl_add_u64 v[228:229], s[30:31], 0, v[134:135]
	ds_read_b128 v[188:191], v153 offset:32768
	ds_read_b128 v[192:195], v153 offset:33792
	ds_read_b128 v[196:199], v153 offset:34816
	ds_read_b128 v[200:203], v153 offset:35840
	ds_read_b128 v[204:207], v153 offset:36864
	ds_read_b128 v[208:211], v153 offset:37888
	ds_read_b128 v[212:215], v153 offset:38912
	ds_read_b128 v[216:219], v153 offset:39936
	global_load_lds_dwordx4 v[228:229], off
	v_lshl_add_u64 v[228:229], s[30:31], 0, v[130:131]
	s_mov_b32 m0, s44
	s_nop 0
	global_load_lds_dwordx4 v[228:229], off
	s_waitcnt vmcnt(8)
	s_waitcnt lgkmcnt(0)
	s_barrier
	v_mfma_f32_16x16x32_bf16 v[120:123], v[156:159], v[188:191], v[120:123]
	v_mfma_f32_16x16x32_bf16 v[116:119], v[164:167], v[188:191], v[116:119]
	v_mfma_f32_16x16x32_bf16 v[108:111], v[156:159], v[196:199], v[108:111]
	v_mfma_f32_16x16x32_bf16 v[100:103], v[164:167], v[196:199], v[100:103]
	v_mfma_f32_16x16x32_bf16 v[92:95], v[156:159], v[204:207], v[92:95]
	v_mfma_f32_16x16x32_bf16 v[84:87], v[164:167], v[204:207], v[84:87]
	v_mfma_f32_16x16x32_bf16 v[76:79], v[156:159], v[212:215], v[76:79]
	v_mfma_f32_16x16x32_bf16 v[68:71], v[164:167], v[212:215], v[68:71]
	v_mfma_f32_16x16x32_bf16 v[120:123], v[160:163], v[192:195], v[120:123]
	v_mfma_f32_16x16x32_bf16 v[116:119], v[168:171], v[192:195], v[116:119]
	v_mfma_f32_16x16x32_bf16 v[108:111], v[160:163], v[200:203], v[108:111]
	v_mfma_f32_16x16x32_bf16 v[100:103], v[168:171], v[200:203], v[100:103]
	v_mfma_f32_16x16x32_bf16 v[92:95], v[160:163], v[208:211], v[92:95]
	v_mfma_f32_16x16x32_bf16 v[84:87], v[168:171], v[208:211], v[84:87]
	v_mfma_f32_16x16x32_bf16 v[76:79], v[160:163], v[216:219], v[76:79]
	v_mfma_f32_16x16x32_bf16 v[68:71], v[168:171], v[216:219], v[68:71]
	v_mfma_f32_16x16x32_bf16 v[124:127], v[172:175], v[188:191], v[124:127]
	v_mfma_f32_16x16x32_bf16 v[112:115], v[180:183], v[188:191], v[112:115]
	v_mfma_f32_16x16x32_bf16 v[104:107], v[172:175], v[196:199], v[104:107]
	v_mfma_f32_16x16x32_bf16 v[96:99], v[180:183], v[196:199], v[96:99]
	v_mfma_f32_16x16x32_bf16 v[88:91], v[172:175], v[204:207], v[88:91]
	v_mfma_f32_16x16x32_bf16 v[80:83], v[180:183], v[204:207], v[80:83]
	v_mfma_f32_16x16x32_bf16 v[72:75], v[172:175], v[212:215], v[72:75]
	v_mfma_f32_16x16x32_bf16 v[64:67], v[180:183], v[212:215], v[64:67]
	v_mfma_f32_16x16x32_bf16 v[124:127], v[176:179], v[192:195], v[124:127]
	v_mfma_f32_16x16x32_bf16 v[112:115], v[184:187], v[192:195], v[112:115]
	v_mfma_f32_16x16x32_bf16 v[104:107], v[176:179], v[200:203], v[104:107]
	v_mfma_f32_16x16x32_bf16 v[96:99], v[184:187], v[200:203], v[96:99]
	v_mfma_f32_16x16x32_bf16 v[88:91], v[176:179], v[208:211], v[88:91]
	v_mfma_f32_16x16x32_bf16 v[80:83], v[184:187], v[208:211], v[80:83]
	v_mfma_f32_16x16x32_bf16 v[72:75], v[176:179], v[216:219], v[72:75]
	v_mfma_f32_16x16x32_bf16 v[64:67], v[184:187], v[216:219], v[64:67]
	s_barrier
; #define PG8_STAGE(bufoff, gbase, voff) do { _Pragma("unroll") for (int _i = 0; _i < 2; ++_i) \
;         __builtin_amdgcn_global_load_lds((const unsigned*)((const char*)(gbase) + (voff)[_i]), (LAS unsigned*)(lds + (bufoff) + ldsw + _i * 8192), 16, 0, 0); } while (0)
; #define PG8_LDA(dst, b, h) do { _Pragma("unroll") for (int m = 0; m < 4; ++m) _Pragma("unroll") for (int k = 0; k < 2; ++k) dst[m][k] = *(const LAS bf16x8*)(lds + PG8_SA(b, h) + aoff + m * 2048 + k * 1024); } while (0)
; #define PG8_MMA(ai, bj, At, Bt) do { __builtin_amdgcn_s_setprio(1); _Pragma("unroll") for (int m = 0; m < 4; ++m) _Pragma("unroll") for (int n = 0; n < 2; ++n) _Pragma("unroll") for (int k = 0; k < 2; ++k) \
;         acc[ai][bj][m][n] = __builtin_amdgcn_mfma_f32_16x16x32_bf16(Bt[n][k], At[m][k], acc[ai][bj][m][n], 0, 0, 0); __builtin_amdgcn_s_setprio(0); } while (0)
; #define PG8_WAIT_V(n) asm volatile("s_waitcnt vmcnt(" #n ")" ::: "memory")
; #define PG8_WAIT_L(n) asm volatile("s_waitcnt lgkmcnt(" #n ")" ::: "memory")
; #define PG8_BAR __builtin_amdgcn_s_barrier()
; #define PG8_SCHED __builtin_amdgcn_sched_barrier(0)
; template <class Epi>
; __device__ __forceinline__ void gemm_phase(LAS unsigned char* lds, const int tid, const Gemm g, const StaticOrder& S, const Epi& E) {
;     ...
;             PG8_LDA(At, 1, 1); PG8_STAGE(PG8_SB(1, 0), b3, voffB); PG8_STAGE(PG8_SB(1, 1), b3 + hstepB, voffB); PG8_STAGE(PG8_SA(1, 0), a3, voffA);
;             PG8_WAIT_V(8); PG8_WAIT_L(0); PG8_BAR; PG8_MMA(1, 0, At, B0); PG8_MMA(1, 1, At, B1); PG8_BAR; PG8_SCHED;
	s_add_i32 s30, s59, s38
	v_lshl_add_u64 v[220:221], v[220:221], 0, s[12:13]
	s_mov_b32 m0, s30
	ds_read_b128 v[188:191], v153 offset:49152
	ds_read_b128 v[192:195], v153 offset:50176
	ds_read_b128 v[196:199], v153 offset:51200
	ds_read_b128 v[200:203], v153 offset:52224
	ds_read_b128 v[204:207], v153 offset:53248
	ds_read_b128 v[208:211], v153 offset:54272
	ds_read_b128 v[212:215], v153 offset:55296
	ds_read_b128 v[216:219], v153 offset:56320
	global_load_lds_dwordx4 v[220:221], off
	s_add_i32 m0, s30, 0x2000
	s_add_u32 s28, s28, 0x40080
	v_lshl_add_u64 v[220:221], v[222:223], 0, s[12:13]
	s_addc_u32 s29, s29, 0
	s_add_i32 s30, s60, s38
	global_load_lds_dwordx4 v[220:221], off
	v_lshl_add_u64 v[220:221], s[28:29], 0, v[132:133]
	s_mov_b32 m0, s30
	s_nop 0
	global_load_lds_dwordx4 v[220:221], off
	v_lshl_add_u64 v[220:221], s[28:29], 0, v[128:129]
	s_add_i32 m0, s30, 0x2000
	s_nop 0
	global_load_lds_dwordx4 v[220:221], off
	v_lshl_add_u64 v[220:221], v[224:225], 0, s[12:13]
	s_mov_b32 m0, s47
	s_nop 0
	global_load_lds_dwordx4 v[220:221], off
	v_lshl_add_u64 v[220:221], v[226:227], 0, s[12:13]
	s_mov_b32 m0, s48
	s_nop 0
	global_load_lds_dwordx4 v[220:221], off
	s_waitcnt vmcnt(8)
	s_waitcnt lgkmcnt(0)
	s_barrier
	v_mfma_f32_16x16x32_bf16 v[60:63], v[156:159], v[188:191], v[60:63]
	v_mfma_f32_16x16x32_bf16 v[52:55], v[164:167], v[188:191], v[52:55]
	v_mfma_f32_16x16x32_bf16 v[44:47], v[156:159], v[196:199], v[44:47]
	v_mfma_f32_16x16x32_bf16 v[36:39], v[164:167], v[196:199], v[36:39]
	v_mfma_f32_16x16x32_bf16 v[28:31], v[156:159], v[204:207], v[28:31]
	v_mfma_f32_16x16x32_bf16 v[20:23], v[164:167], v[204:207], v[20:23]
	v_mfma_f32_16x16x32_bf16 v[12:15], v[156:159], v[212:215], v[12:15]
	v_mfma_f32_16x16x32_bf16 v[4:7], v[164:167], v[212:215], v[4:7]
	v_mfma_f32_16x16x32_bf16 v[60:63], v[160:163], v[192:195], v[60:63]
	v_mfma_f32_16x16x32_bf16 v[52:55], v[168:171], v[192:195], v[52:55]
	v_mfma_f32_16x16x32_bf16 v[44:47], v[160:163], v[200:203], v[44:47]
	v_mfma_f32_16x16x32_bf16 v[36:39], v[168:171], v[200:203], v[36:39]
	v_mfma_f32_16x16x32_bf16 v[28:31], v[160:163], v[208:211], v[28:31]
	v_mfma_f32_16x16x32_bf16 v[20:23], v[168:171], v[208:211], v[20:23]
	v_mfma_f32_16x16x32_bf16 v[12:15], v[160:163], v[216:219], v[12:15]
	v_mfma_f32_16x16x32_bf16 v[4:7], v[168:171], v[216:219], v[4:7]
	v_mfma_f32_16x16x32_bf16 v[56:59], v[172:175], v[188:191], v[56:59]
	v_mfma_f32_16x16x32_bf16 v[48:51], v[180:183], v[188:191], v[48:51]
	v_mfma_f32_16x16x32_bf16 v[40:43], v[172:175], v[196:199], v[40:43]
	v_mfma_f32_16x16x32_bf16 v[32:35], v[180:183], v[196:199], v[32:35]
	v_mfma_f32_16x16x32_bf16 v[24:27], v[172:175], v[204:207], v[24:27]
	v_mfma_f32_16x16x32_bf16 v[16:19], v[180:183], v[204:207], v[16:19]
	v_mfma_f32_16x16x32_bf16 v[8:11], v[172:175], v[212:215], v[8:11]
	v_mfma_f32_16x16x32_bf16 v[0:3], v[180:183], v[212:215], v[0:3]
	v_mfma_f32_16x16x32_bf16 v[56:59], v[176:179], v[192:195], v[56:59]
	v_mfma_f32_16x16x32_bf16 v[48:51], v[184:187], v[192:195], v[48:51]
	v_mfma_f32_16x16x32_bf16 v[40:43], v[176:179], v[200:203], v[40:43]
	v_mfma_f32_16x16x32_bf16 v[32:35], v[184:187], v[200:203], v[32:35]
	v_mfma_f32_16x16x32_bf16 v[24:27], v[176:179], v[208:211], v[24:27]
	v_mfma_f32_16x16x32_bf16 v[16:19], v[184:187], v[208:211], v[16:19]
	v_mfma_f32_16x16x32_bf16 v[8:11], v[176:179], v[216:219], v[8:11]
	v_mfma_f32_16x16x32_bf16 v[0:3], v[184:187], v[216:219], v[0:3]
	s_barrier
	s_add_u32 s25, s25, 0x100
	s_addc_u32 s57, s57, 0
	s_add_u32 s26, s26, 0x100
	s_addc_u32 s27, s27, 0
	s_cmp_ge_i32 s58, s46
	s_cbranch_scc1 .LBB0_266

; #define LAS __attribute__((address_space(3)))
; #define PG8_STAGE(bufoff, gbase, voff) do { _Pragma("unroll") for (int _i = 0; _i < 2; ++_i) \
;         __builtin_amdgcn_global_load_lds((const unsigned*)((const char*)(gbase) + (voff)[_i]), (LAS unsigned*)(lds + (bufoff) + ldsw + _i * 8192), 16, 0, 0); } while (0)
; #define PG8_LDA(dst, b, h) do { _Pragma("unroll") for (int m = 0; m < 4; ++m) _Pragma("unroll") for (int k = 0; k < 2; ++k) dst[m][k] = *(const LAS bf16x8*)(lds + PG8_SA(b, h) + aoff + m * 2048 + k * 1024); } while (0)
; #define PG8_LDB(dst, b, h) do { _Pragma("unroll") for (int n = 0; n < 2; ++n) _Pragma("unroll") for (int k = 0; k < 2; ++k) dst[n][k] = *(const LAS bf16x8*)(lds + PG8_SB(b, h) + boff + n * 2048 + k * 1024); } while (0)
; #define PG8_WAIT_V(n) asm volatile("s_waitcnt vmcnt(" #n ")" ::: "memory")
; #define PG8_WAIT_L(n) asm volatile("s_waitcnt lgkmcnt(" #n ")" ::: "memory")
; template <class Epi>
; __device__ __forceinline__ void gemm_phase(LAS unsigned char* lds, const int tid, const Gemm g, const StaticOrder& S, const Epi& E) {
;     ...
;         for (int t = 0; t < nt; t += 2) {
;             const bool last = (t == nt - 2);
;             const char* a1 = cA + (size_t)(t + 1) * kstep;
;             const char* a2 = last ? nA : cA + (size_t)(t + 2) * kstep; const char* b2 = last ? nB : cB + (size_t)(t + 2) * kstep;
;             const char* a3 = a2 + kstep; const char* b3 = b2 + kstep;
;             if constexpr (Epi::SS_LDS) { if (last) {
;                 const char* sp = (const char*)E.ss + (size_t)cur.pm * (256 * 64) + (size_t)tid * 16;
;                 __builtin_amdgcn_global_load_lds((const unsigned*)sp, (LAS unsigned*)(lds + RS_OFF + ldsw), 16, 0, 0);
;                 __builtin_amdgcn_global_load_lds((const unsigned*)(sp + 8192), (LAS unsigned*)(lds + RS_OFF + 8192 + ldsw), 16, 0, 0); } }
;     ...
;             PG8_LDB(B0, 0, 0); PG8_LDB(B1, 0, 1); PG8_SCHED; PG8_LDA(At, 0, 0); PG8_STAGE(PG8_SA(1, 1), a1 + hstepA, voffA);
;             PG8_WAIT_V(8); PG8_WAIT_L(0); PG8_BAR; PG8_MMA(0, 0, At, B0); PG8_MMA(0, 1, At, B1); PG8_BAR; PG8_SCHED;
;             PG8_LDA(At, 0, 1); PG8_STAGE(PG8_SB(0, 0), b2, voffB); PG8_STAGE(PG8_SB(0, 1), b2 + hstepB, voffB); PG8_STAGE(PG8_SA(0, 0), a2, voffA);
;             PG8_WAIT_V(8); PG8_WAIT_L(0); PG8_BAR; PG8_MMA(1, 0, At, B0); PG8_MMA(1, 1, At, B1); PG8_BAR; PG8_SCHED;
.LBB0_352:
	ds_read_b128 v[144:147], v207
	ds_read_b128 v[148:151], v207 offset:1024
	ds_read_b128 v[152:155], v207 offset:2048
	ds_read_b128 v[156:159], v207 offset:3072
	ds_read_b128 v[160:163], v208
	ds_read_b128 v[164:167], v208 offset:1024
	ds_read_b128 v[168:171], v208 offset:2048
	ds_read_b128 v[172:175], v208 offset:3072
	s_add_i32 s60, s30, 2
	s_add_u32 s28, s26, 0x100
	s_addc_u32 s29, s27, 0
	s_cmp_eq_u32 s49, s30
	s_cselect_b32 s30, s24, s58
	s_cselect_b32 s35, s7, s29
	s_cselect_b32 s34, s6, s28
	s_cselect_b32 s31, s25, s59
	v_lshl_add_u64 v[214:215], s[26:27], 0, v[138:139]
	s_add_i32 m0, s41, 0xc000
	ds_read_b128 v[176:179], v209
	ds_read_b128 v[180:183], v209 offset:1024
	ds_read_b128 v[184:187], v209 offset:2048
	ds_read_b128 v[188:191], v209 offset:3072
	ds_read_b128 v[192:195], v209 offset:4096
	ds_read_b128 v[196:199], v209 offset:5120
	ds_read_b128 v[200:203], v209 offset:6144
	ds_read_b128 v[210:213], v209 offset:7168
	global_load_lds_dwordx4 v[214:215], off
	v_lshl_add_u64 v[214:215], s[26:27], 0, v[136:137]
	s_add_i32 m0, s41, 0xe000
	s_nop 0
	global_load_lds_dwordx4 v[214:215], off
	s_waitcnt vmcnt(8)
	s_waitcnt lgkmcnt(0)
	s_barrier
	v_mfma_f32_16x16x32_bf16 v[124:127], v[144:147], v[176:179], v[124:127]
	v_mfma_f32_16x16x32_bf16 v[120:123], v[152:155], v[176:179], v[120:123]
	v_mfma_f32_16x16x32_bf16 v[116:119], v[144:147], v[184:187], v[116:119]
	v_mfma_f32_16x16x32_bf16 v[112:115], v[152:155], v[184:187], v[112:115]
	v_mfma_f32_16x16x32_bf16 v[104:107], v[144:147], v[192:195], v[104:107]
	v_mfma_f32_16x16x32_bf16 v[96:99], v[152:155], v[192:195], v[96:99]
	v_mfma_f32_16x16x32_bf16 v[88:91], v[144:147], v[200:203], v[88:91]
	v_mfma_f32_16x16x32_bf16 v[80:83], v[152:155], v[200:203], v[80:83]
	v_mfma_f32_16x16x32_bf16 v[124:127], v[148:151], v[180:183], v[124:127]
	v_mfma_f32_16x16x32_bf16 v[120:123], v[156:159], v[180:183], v[120:123]
	v_mfma_f32_16x16x32_bf16 v[116:119], v[148:151], v[188:191], v[116:119]
	v_mfma_f32_16x16x32_bf16 v[112:115], v[156:159], v[188:191], v[112:115]
	v_mfma_f32_16x16x32_bf16 v[104:107], v[148:151], v[196:199], v[104:107]
	v_mfma_f32_16x16x32_bf16 v[96:99], v[156:159], v[196:199], v[96:99]
	v_mfma_f32_16x16x32_bf16 v[88:91], v[148:151], v[210:213], v[88:91]
	v_mfma_f32_16x16x32_bf16 v[80:83], v[156:159], v[210:213], v[80:83]
	v_mfma_f32_16x16x32_bf16 v[108:111], v[160:163], v[176:179], v[108:111]
	v_mfma_f32_16x16x32_bf16 v[100:103], v[168:171], v[176:179], v[100:103]
	v_mfma_f32_16x16x32_bf16 v[92:95], v[160:163], v[184:187], v[92:95]
	v_mfma_f32_16x16x32_bf16 v[84:87], v[168:171], v[184:187], v[84:87]
	v_mfma_f32_16x16x32_bf16 v[76:79], v[160:163], v[192:195], v[76:79]
	v_mfma_f32_16x16x32_bf16 v[72:75], v[168:171], v[192:195], v[72:75]
	v_mfma_f32_16x16x32_bf16 v[68:71], v[160:163], v[200:203], v[68:71]
	v_mfma_f32_16x16x32_bf16 v[64:67], v[168:171], v[200:203], v[64:67]
	v_mfma_f32_16x16x32_bf16 v[108:111], v[164:167], v[180:183], v[108:111]
	v_mfma_f32_16x16x32_bf16 v[100:103], v[172:175], v[180:183], v[100:103]
	v_mfma_f32_16x16x32_bf16 v[92:95], v[164:167], v[188:191], v[92:95]
	v_mfma_f32_16x16x32_bf16 v[84:87], v[172:175], v[188:191], v[84:87]
	v_mfma_f32_16x16x32_bf16 v[76:79], v[164:167], v[196:199], v[76:79]
	v_mfma_f32_16x16x32_bf16 v[72:75], v[172:175], v[196:199], v[72:75]
	v_mfma_f32_16x16x32_bf16 v[68:71], v[164:167], v[210:213], v[68:71]
	v_mfma_f32_16x16x32_bf16 v[64:67], v[172:175], v[210:213], v[64:67]
	s_barrier
	s_add_i32 s26, s52, s40
	v_lshl_add_u64 v[214:215], s[30:31], 0, v[130:131]
	s_mov_b32 m0, s26
	ds_read_b128 v[176:179], v209 offset:16384
	ds_read_b128 v[180:183], v209 offset:17408
	ds_read_b128 v[184:187], v209 offset:18432
	ds_read_b128 v[188:191], v209 offset:19456
	ds_read_b128 v[192:195], v209 offset:20480
	ds_read_b128 v[196:199], v209 offset:21504
	ds_read_b128 v[200:203], v209 offset:22528
	ds_read_b128 v[210:213], v209 offset:23552
	global_load_lds_dwordx4 v[214:215], off
	s_add_i32 m0, s26, 0x2000
	s_add_u32 s26, s30, 0xb0000
	v_lshl_add_u64 v[216:217], s[30:31], 0, v[134:135]
	s_addc_u32 s27, s31, 0
	s_add_i32 s61, s53, s40
	global_load_lds_dwordx4 v[216:217], off
	v_lshl_add_u64 v[218:219], s[26:27], 0, v[130:131]
	s_mov_b32 m0, s61
	v_lshl_add_u64 v[220:221], s[34:35], 0, v[132:133]
	global_load_lds_dwordx4 v[218:219], off
	v_lshl_add_u64 v[218:219], s[26:27], 0, v[134:135]
	s_add_i32 m0, s61, 0x2000
	s_nop 0
	global_load_lds_dwordx4 v[218:219], off
	v_lshl_add_u64 v[218:219], s[34:35], 0, v[128:129]
	s_mov_b32 m0, s41
	s_nop 0
	global_load_lds_dwordx4 v[218:219], off
	s_mov_b32 m0, s42
	s_nop 0
	global_load_lds_dwordx4 v[220:221], off
	s_waitcnt vmcnt(8)
	s_waitcnt lgkmcnt(0)
	s_barrier
; #define PG8_STAGE(bufoff, gbase, voff) do { _Pragma("unroll") for (int _i = 0; _i < 2; ++_i) \
;         __builtin_amdgcn_global_load_lds((const unsigned*)((const char*)(gbase) + (voff)[_i]), (LAS unsigned*)(lds + (bufoff) + ldsw + _i * 8192), 16, 0, 0); } while (0)
; #define PG8_LDA(dst, b, h) do { _Pragma("unroll") for (int m = 0; m < 4; ++m) _Pragma("unroll") for (int k = 0; k < 2; ++k) dst[m][k] = *(const LAS bf16x8*)(lds + PG8_SA(b, h) + aoff + m * 2048 + k * 1024); } while (0)
; #define PG8_LDB(dst, b, h) do { _Pragma("unroll") for (int n = 0; n < 2; ++n) _Pragma("unroll") for (int k = 0; k < 2; ++k) dst[n][k] = *(const LAS bf16x8*)(lds + PG8_SB(b, h) + boff + n * 2048 + k * 1024); } while (0)
; #define PG8_MMA(ai, bj, At, Bt) do { __builtin_amdgcn_s_setprio(1); _Pragma("unroll") for (int m = 0; m < 4; ++m) _Pragma("unroll") for (int n = 0; n < 2; ++n) _Pragma("unroll") for (int k = 0; k < 2; ++k) \
;         acc[ai][bj][m][n] = __builtin_amdgcn_mfma_f32_16x16x32_bf16(Bt[n][k], At[m][k], acc[ai][bj][m][n], 0, 0, 0); __builtin_amdgcn_s_setprio(0); } while (0)
; #define PG8_WAIT_V(n) asm volatile("s_waitcnt vmcnt(" #n ")" ::: "memory")
; #define PG8_WAIT_L(n) asm volatile("s_waitcnt lgkmcnt(" #n ")" ::: "memory")
; #define PG8_BAR __builtin_amdgcn_s_barrier()
; #define PG8_SCHED __builtin_amdgcn_sched_barrier(0)
; template <class Epi>
; __device__ __forceinline__ void gemm_phase(LAS unsigned char* lds, const int tid, const Gemm g, const StaticOrder& S, const Epi& E) {
;     ...
;             PG8_WAIT_V(8); PG8_WAIT_L(0); PG8_BAR; PG8_MMA(1, 0, At, B0); PG8_MMA(1, 1, At, B1); PG8_BAR; PG8_SCHED;
;             PG8_LDB(B0, 1, 0); PG8_LDB(B1, 1, 1); PG8_SCHED; PG8_LDA(At, 1, 0); PG8_STAGE(PG8_SA(0, 1), a2 + hstepA, voffA);
;             PG8_WAIT_V(8); PG8_WAIT_L(0); PG8_BAR; PG8_MMA(0, 0, At, B0); PG8_MMA(0, 1, At, B1); PG8_BAR; PG8_SCHED;
	v_mfma_f32_16x16x32_bf16 v[60:63], v[144:147], v[176:179], v[60:63]
	v_mfma_f32_16x16x32_bf16 v[56:59], v[152:155], v[176:179], v[56:59]
	v_mfma_f32_16x16x32_bf16 v[52:55], v[144:147], v[184:187], v[52:55]
	v_mfma_f32_16x16x32_bf16 v[48:51], v[152:155], v[184:187], v[48:51]
	v_mfma_f32_16x16x32_bf16 v[40:43], v[144:147], v[192:195], v[40:43]
	v_mfma_f32_16x16x32_bf16 v[32:35], v[152:155], v[192:195], v[32:35]
	v_mfma_f32_16x16x32_bf16 v[24:27], v[144:147], v[200:203], v[24:27]
	v_mfma_f32_16x16x32_bf16 v[16:19], v[152:155], v[200:203], v[16:19]
	v_mfma_f32_16x16x32_bf16 v[60:63], v[148:151], v[180:183], v[60:63]
	v_mfma_f32_16x16x32_bf16 v[56:59], v[156:159], v[180:183], v[56:59]
	v_mfma_f32_16x16x32_bf16 v[52:55], v[148:151], v[188:191], v[52:55]
	v_mfma_f32_16x16x32_bf16 v[48:51], v[156:159], v[188:191], v[48:51]
	v_mfma_f32_16x16x32_bf16 v[40:43], v[148:151], v[196:199], v[40:43]
	v_mfma_f32_16x16x32_bf16 v[32:35], v[156:159], v[196:199], v[32:35]
	v_mfma_f32_16x16x32_bf16 v[24:27], v[148:151], v[210:213], v[24:27]
	v_mfma_f32_16x16x32_bf16 v[16:19], v[156:159], v[210:213], v[16:19]
	v_mfma_f32_16x16x32_bf16 v[44:47], v[160:163], v[176:179], v[44:47]
	v_mfma_f32_16x16x32_bf16 v[36:39], v[168:171], v[176:179], v[36:39]
	v_mfma_f32_16x16x32_bf16 v[28:31], v[160:163], v[184:187], v[28:31]
	v_mfma_f32_16x16x32_bf16 v[20:23], v[168:171], v[184:187], v[20:23]
	v_mfma_f32_16x16x32_bf16 v[12:15], v[160:163], v[192:195], v[12:15]
	v_mfma_f32_16x16x32_bf16 v[8:11], v[168:171], v[192:195], v[8:11]
	v_mfma_f32_16x16x32_bf16 v[4:7], v[160:163], v[200:203], v[4:7]
	v_mfma_f32_16x16x32_bf16 v[0:3], v[168:171], v[200:203], v[0:3]
	v_mfma_f32_16x16x32_bf16 v[44:47], v[164:167], v[180:183], v[44:47]
	v_mfma_f32_16x16x32_bf16 v[36:39], v[172:175], v[180:183], v[36:39]
	v_mfma_f32_16x16x32_bf16 v[28:31], v[164:167], v[188:191], v[28:31]
	v_mfma_f32_16x16x32_bf16 v[20:23], v[172:175], v[188:191], v[20:23]
	v_mfma_f32_16x16x32_bf16 v[12:15], v[164:167], v[196:199], v[12:15]
	v_mfma_f32_16x16x32_bf16 v[8:11], v[172:175], v[196:199], v[8:11]
	v_mfma_f32_16x16x32_bf16 v[4:7], v[164:167], v[210:213], v[4:7]
	v_mfma_f32_16x16x32_bf16 v[0:3], v[172:175], v[210:213], v[0:3]
	s_barrier
	s_add_i32 s61, 0, 0x18000
	s_add_i32 s62, 0, 0x1c000
	v_add_u32_e32 v156, s61, v205
	v_add_u32_e32 v172, s62, v205
	ds_read_b128 v[144:147], v156
	ds_read_b128 v[148:151], v156 offset:1024
	ds_read_b128 v[152:155], v156 offset:2048
	ds_read_b128 v[156:159], v156 offset:3072
	ds_read_b128 v[160:163], v172
	ds_read_b128 v[164:167], v172 offset:1024
	ds_read_b128 v[168:171], v172 offset:2048
	ds_read_b128 v[172:175], v172 offset:3072
	s_add_u32 s26, s34, 0xb0000
	s_addc_u32 s27, s35, 0
	s_mov_b32 m0, s43
	v_lshl_add_u64 v[222:223], s[26:27], 0, v[128:129]
	ds_read_b128 v[176:179], v209 offset:32768
	ds_read_b128 v[180:183], v209 offset:33792
	ds_read_b128 v[184:187], v209 offset:34816
	ds_read_b128 v[188:191], v209 offset:35840
	ds_read_b128 v[192:195], v209 offset:36864
	ds_read_b128 v[196:199], v209 offset:37888
	ds_read_b128 v[200:203], v209 offset:38912
	ds_read_b128 v[210:213], v209 offset:39936
	global_load_lds_dwordx4 v[222:223], off
	v_lshl_add_u64 v[222:223], s[26:27], 0, v[132:133]
	s_mov_b32 m0, s44
	s_nop 0
	global_load_lds_dwordx4 v[222:223], off
	s_waitcnt vmcnt(8)
	s_waitcnt lgkmcnt(0)
	s_barrier
	v_mfma_f32_16x16x32_bf16 v[124:127], v[144:147], v[176:179], v[124:127]
	v_mfma_f32_16x16x32_bf16 v[120:123], v[152:155], v[176:179], v[120:123]
	v_mfma_f32_16x16x32_bf16 v[116:119], v[144:147], v[184:187], v[116:119]
	v_mfma_f32_16x16x32_bf16 v[112:115], v[152:155], v[184:187], v[112:115]
	v_mfma_f32_16x16x32_bf16 v[104:107], v[144:147], v[192:195], v[104:107]
	v_mfma_f32_16x16x32_bf16 v[96:99], v[152:155], v[192:195], v[96:99]
	v_mfma_f32_16x16x32_bf16 v[88:91], v[144:147], v[200:203], v[88:91]
	v_mfma_f32_16x16x32_bf16 v[80:83], v[152:155], v[200:203], v[80:83]
	v_mfma_f32_16x16x32_bf16 v[124:127], v[148:151], v[180:183], v[124:127]
	v_mfma_f32_16x16x32_bf16 v[120:123], v[156:159], v[180:183], v[120:123]
	v_mfma_f32_16x16x32_bf16 v[116:119], v[148:151], v[188:191], v[116:119]
	v_mfma_f32_16x16x32_bf16 v[112:115], v[156:159], v[188:191], v[112:115]
	v_mfma_f32_16x16x32_bf16 v[104:107], v[148:151], v[196:199], v[104:107]
	v_mfma_f32_16x16x32_bf16 v[96:99], v[156:159], v[196:199], v[96:99]
	v_mfma_f32_16x16x32_bf16 v[88:91], v[148:151], v[210:213], v[88:91]
	v_mfma_f32_16x16x32_bf16 v[80:83], v[156:159], v[210:213], v[80:83]
	v_mfma_f32_16x16x32_bf16 v[108:111], v[160:163], v[176:179], v[108:111]
	v_mfma_f32_16x16x32_bf16 v[100:103], v[168:171], v[176:179], v[100:103]
	v_mfma_f32_16x16x32_bf16 v[92:95], v[160:163], v[184:187], v[92:95]
	v_mfma_f32_16x16x32_bf16 v[84:87], v[168:171], v[184:187], v[84:87]
	v_mfma_f32_16x16x32_bf16 v[76:79], v[160:163], v[192:195], v[76:79]
	v_mfma_f32_16x16x32_bf16 v[72:75], v[168:171], v[192:195], v[72:75]
	v_mfma_f32_16x16x32_bf16 v[68:71], v[160:163], v[200:203], v[68:71]
	v_mfma_f32_16x16x32_bf16 v[64:67], v[168:171], v[200:203], v[64:67]
	v_mfma_f32_16x16x32_bf16 v[108:111], v[164:167], v[180:183], v[108:111]
	v_mfma_f32_16x16x32_bf16 v[100:103], v[172:175], v[180:183], v[100:103]
	v_mfma_f32_16x16x32_bf16 v[92:95], v[164:167], v[188:191], v[92:95]
	v_mfma_f32_16x16x32_bf16 v[84:87], v[172:175], v[188:191], v[84:87]
	v_mfma_f32_16x16x32_bf16 v[76:79], v[164:167], v[196:199], v[76:79]
	v_mfma_f32_16x16x32_bf16 v[72:75], v[172:175], v[196:199], v[72:75]
	v_mfma_f32_16x16x32_bf16 v[68:71], v[164:167], v[210:213], v[68:71]
	v_mfma_f32_16x16x32_bf16 v[64:67], v[172:175], v[210:213], v[64:67]
	s_barrier
; #define PG8_STAGE(bufoff, gbase, voff) do { _Pragma("unroll") for (int _i = 0; _i < 2; ++_i) \
;         __builtin_amdgcn_global_load_lds((const unsigned*)((const char*)(gbase) + (voff)[_i]), (LAS unsigned*)(lds + (bufoff) + ldsw + _i * 8192), 16, 0, 0); } while (0)
; #define PG8_LDA(dst, b, h) do { _Pragma("unroll") for (int m = 0; m < 4; ++m) _Pragma("unroll") for (int k = 0; k < 2; ++k) dst[m][k] = *(const LAS bf16x8*)(lds + PG8_SA(b, h) + aoff + m * 2048 + k * 1024); } while (0)
; #define PG8_MMA(ai, bj, At, Bt) do { __builtin_amdgcn_s_setprio(1); _Pragma("unroll") for (int m = 0; m < 4; ++m) _Pragma("unroll") for (int n = 0; n < 2; ++n) _Pragma("unroll") for (int k = 0; k < 2; ++k) \
;         acc[ai][bj][m][n] = __builtin_amdgcn_mfma_f32_16x16x32_bf16(Bt[n][k], At[m][k], acc[ai][bj][m][n], 0, 0, 0); __builtin_amdgcn_s_setprio(0); } while (0)
; #define PG8_WAIT_V(n) asm volatile("s_waitcnt vmcnt(" #n ")" ::: "memory")
; #define PG8_WAIT_L(n) asm volatile("s_waitcnt lgkmcnt(" #n ")" ::: "memory")
; #define PG8_BAR __builtin_amdgcn_s_barrier()
; #define PG8_SCHED __builtin_amdgcn_sched_barrier(0)
; template <class Epi>
; __device__ __forceinline__ void gemm_phase(LAS unsigned char* lds, const int tid, const Gemm g, const StaticOrder& S, const Epi& E) {
;     ...
;             PG8_LDA(At, 1, 1); PG8_STAGE(PG8_SB(1, 0), b3, voffB); PG8_STAGE(PG8_SB(1, 1), b3 + hstepB, voffB); PG8_STAGE(PG8_SA(1, 0), a3, voffA);
;             PG8_WAIT_V(8); PG8_WAIT_L(0); PG8_BAR; PG8_MMA(1, 0, At, B0); PG8_MMA(1, 1, At, B1); PG8_BAR; PG8_SCHED;
	s_add_i32 s26, s61, s40
	v_lshl_add_u64 v[214:215], v[214:215], 0, s[18:19]
	s_mov_b32 m0, s26
	ds_read_b128 v[176:179], v209 offset:49152
	ds_read_b128 v[180:183], v209 offset:50176
	ds_read_b128 v[184:187], v209 offset:51200
	ds_read_b128 v[188:191], v209 offset:52224
	ds_read_b128 v[192:195], v209 offset:53248
	ds_read_b128 v[196:199], v209 offset:54272
	ds_read_b128 v[200:203], v209 offset:55296
	ds_read_b128 v[210:213], v209 offset:56320
	global_load_lds_dwordx4 v[214:215], off
	s_add_i32 m0, s26, 0x2000
	s_add_u32 s26, s30, 0xb0080
	v_lshl_add_u64 v[214:215], v[216:217], 0, s[18:19]
	s_addc_u32 s27, s31, 0
	s_add_i32 s30, s62, s40
	global_load_lds_dwordx4 v[214:215], off
	v_lshl_add_u64 v[214:215], s[26:27], 0, v[130:131]
	s_mov_b32 m0, s30
	s_nop 0
	global_load_lds_dwordx4 v[214:215], off
	v_lshl_add_u64 v[214:215], s[26:27], 0, v[134:135]
	s_add_i32 m0, s30, 0x2000
	s_nop 0
	global_load_lds_dwordx4 v[214:215], off
	v_lshl_add_u64 v[214:215], v[218:219], 0, s[18:19]
	s_mov_b32 m0, s47
	s_nop 0
	global_load_lds_dwordx4 v[214:215], off
	v_lshl_add_u64 v[214:215], v[220:221], 0, s[18:19]
	s_mov_b32 m0, s48
	s_nop 0
	global_load_lds_dwordx4 v[214:215], off
	s_waitcnt vmcnt(8)
	s_waitcnt lgkmcnt(0)
	s_barrier
	v_mfma_f32_16x16x32_bf16 v[60:63], v[144:147], v[176:179], v[60:63]
	v_mfma_f32_16x16x32_bf16 v[56:59], v[152:155], v[176:179], v[56:59]
	v_mfma_f32_16x16x32_bf16 v[52:55], v[144:147], v[184:187], v[52:55]
	v_mfma_f32_16x16x32_bf16 v[48:51], v[152:155], v[184:187], v[48:51]
	v_mfma_f32_16x16x32_bf16 v[40:43], v[144:147], v[192:195], v[40:43]
	v_mfma_f32_16x16x32_bf16 v[32:35], v[152:155], v[192:195], v[32:35]
	v_mfma_f32_16x16x32_bf16 v[24:27], v[144:147], v[200:203], v[24:27]
	v_mfma_f32_16x16x32_bf16 v[16:19], v[152:155], v[200:203], v[16:19]
	v_mfma_f32_16x16x32_bf16 v[60:63], v[148:151], v[180:183], v[60:63]
	v_mfma_f32_16x16x32_bf16 v[56:59], v[156:159], v[180:183], v[56:59]
	v_mfma_f32_16x16x32_bf16 v[52:55], v[148:151], v[188:191], v[52:55]
	v_mfma_f32_16x16x32_bf16 v[48:51], v[156:159], v[188:191], v[48:51]
	v_mfma_f32_16x16x32_bf16 v[40:43], v[148:151], v[196:199], v[40:43]
	v_mfma_f32_16x16x32_bf16 v[32:35], v[156:159], v[196:199], v[32:35]
	v_mfma_f32_16x16x32_bf16 v[24:27], v[148:151], v[210:213], v[24:27]
	v_mfma_f32_16x16x32_bf16 v[16:19], v[156:159], v[210:213], v[16:19]
	v_mfma_f32_16x16x32_bf16 v[44:47], v[160:163], v[176:179], v[44:47]
	v_mfma_f32_16x16x32_bf16 v[36:39], v[168:171], v[176:179], v[36:39]
	v_mfma_f32_16x16x32_bf16 v[28:31], v[160:163], v[184:187], v[28:31]
	v_mfma_f32_16x16x32_bf16 v[20:23], v[168:171], v[184:187], v[20:23]
	v_mfma_f32_16x16x32_bf16 v[12:15], v[160:163], v[192:195], v[12:15]
	v_mfma_f32_16x16x32_bf16 v[8:11], v[168:171], v[192:195], v[8:11]
	v_mfma_f32_16x16x32_bf16 v[4:7], v[160:163], v[200:203], v[4:7]
	v_mfma_f32_16x16x32_bf16 v[0:3], v[168:171], v[200:203], v[0:3]
	v_mfma_f32_16x16x32_bf16 v[44:47], v[164:167], v[180:183], v[44:47]
	v_mfma_f32_16x16x32_bf16 v[36:39], v[172:175], v[180:183], v[36:39]
	v_mfma_f32_16x16x32_bf16 v[28:31], v[164:167], v[188:191], v[28:31]
	v_mfma_f32_16x16x32_bf16 v[20:23], v[172:175], v[188:191], v[20:23]
	v_mfma_f32_16x16x32_bf16 v[12:15], v[164:167], v[196:199], v[12:15]
	v_mfma_f32_16x16x32_bf16 v[8:11], v[172:175], v[196:199], v[8:11]
	v_mfma_f32_16x16x32_bf16 v[4:7], v[164:167], v[210:213], v[4:7]
	v_mfma_f32_16x16x32_bf16 v[0:3], v[172:175], v[210:213], v[0:3]
	s_barrier
	s_add_u32 s58, s58, 0x100
	s_addc_u32 s59, s59, 0
	s_cmp_ge_i32 s60, s46
	s_mov_b64 s[26:27], s[28:29]
	s_mov_b32 s30, s60
	s_cbranch_scc0 .LBB0_352
;     __device__ __forceinline__ void operator()(const Acc& acc, const Unit& u, int wr, int wc, int fr, int fq) const {
;     ...
;                     const f32x4 h0 = hv[m][bj][0] + acc[ai][bj][m][0] * scale, h1 = hv[m][bj][1] + acc[ai][bj][m][1] * scale;
	v_pk_mul_f32 v[178:179], v[126:127], 0.5 op_sel_hi:[1,0]
	v_pk_mul_f32 v[180:181], v[124:125], 0.5 op_sel_hi:[1,0]
	v_pk_mul_f32 v[182:183], v[122:123], 0.5 op_sel_hi:[1,0]
	v_pk_mul_f32 v[184:185], v[120:121], 0.5 op_sel_hi:[1,0]
	v_pk_mul_f32 v[192:193], v[110:111], 0.5 op_sel_hi:[1,0]
	v_pk_mul_f32 v[190:191], v[108:109], 0.5 op_sel_hi:[1,0]
	v_pk_mul_f32 v[188:189], v[102:103], 0.5 op_sel_hi:[1,0]
	v_pk_mul_f32 v[186:187], v[100:101], 0.5 op_sel_hi:[1,0]
	v_pk_mul_f32 v[176:177], v[118:119], 0.5 op_sel_hi:[1,0]
	v_pk_mul_f32 v[174:175], v[116:117], 0.5 op_sel_hi:[1,0]
	v_pk_mul_f32 v[172:173], v[114:115], 0.5 op_sel_hi:[1,0]
	v_pk_mul_f32 v[170:171], v[112:113], 0.5 op_sel_hi:[1,0]
	v_pk_mul_f32 v[168:169], v[94:95], 0.5 op_sel_hi:[1,0]
	v_pk_mul_f32 v[166:167], v[92:93], 0.5 op_sel_hi:[1,0]
	v_pk_mul_f32 v[164:165], v[86:87], 0.5 op_sel_hi:[1,0]
	v_pk_mul_f32 v[162:163], v[84:85], 0.5 op_sel_hi:[1,0]
	v_pk_mul_f32 v[160:161], v[106:107], 0.5 op_sel_hi:[1,0]
	v_pk_mul_f32 v[158:159], v[104:105], 0.5 op_sel_hi:[1,0]
	v_pk_mul_f32 v[156:157], v[98:99], 0.5 op_sel_hi:[1,0]
	v_pk_mul_f32 v[154:155], v[96:97], 0.5 op_sel_hi:[1,0]
	v_pk_mul_f32 v[152:153], v[78:79], 0.5 op_sel_hi:[1,0]
	v_pk_mul_f32 v[150:151], v[76:77], 0.5 op_sel_hi:[1,0]
	v_pk_mul_f32 v[148:149], v[74:75], 0.5 op_sel_hi:[1,0]
	v_pk_mul_f32 v[146:147], v[72:73], 0.5 op_sel_hi:[1,0]
	v_pk_mul_f32 v[144:145], v[90:91], 0.5 op_sel_hi:[1,0]
	v_pk_mul_f32 v[126:127], v[88:89], 0.5 op_sel_hi:[1,0]
	v_pk_mul_f32 v[124:125], v[82:83], 0.5 op_sel_hi:[1,0]
	v_pk_mul_f32 v[122:123], v[80:81], 0.5 op_sel_hi:[1,0]
	v_pk_mul_f32 v[120:121], v[70:71], 0.5 op_sel_hi:[1,0]
	v_pk_mul_f32 v[118:119], v[68:69], 0.5 op_sel_hi:[1,0]
	v_pk_mul_f32 v[116:117], v[66:67], 0.5 op_sel_hi:[1,0]
	v_pk_mul_f32 v[114:115], v[64:65], 0.5 op_sel_hi:[1,0]
	v_pk_mul_f32 v[96:97], v[62:63], 0.5 op_sel_hi:[1,0]
	v_pk_mul_f32 v[98:99], v[60:61], 0.5 op_sel_hi:[1,0]
	v_pk_mul_f32 v[100:101], v[58:59], 0.5 op_sel_hi:[1,0]
	v_pk_mul_f32 v[102:103], v[56:57], 0.5 op_sel_hi:[1,0]
	v_pk_mul_f32 v[110:111], v[46:47], 0.5 op_sel_hi:[1,0]
	v_pk_mul_f32 v[108:109], v[44:45], 0.5 op_sel_hi:[1,0]
	v_pk_mul_f32 v[106:107], v[38:39], 0.5 op_sel_hi:[1,0]
	v_pk_mul_f32 v[104:105], v[36:37], 0.5 op_sel_hi:[1,0]
	v_pk_mul_f32 v[94:95], v[54:55], 0.5 op_sel_hi:[1,0]
	v_pk_mul_f32 v[92:93], v[52:53], 0.5 op_sel_hi:[1,0]
	v_pk_mul_f32 v[90:91], v[50:51], 0.5 op_sel_hi:[1,0]
	v_pk_mul_f32 v[88:89], v[48:49], 0.5 op_sel_hi:[1,0]
	v_pk_mul_f32 v[86:87], v[30:31], 0.5 op_sel_hi:[1,0]
	v_pk_mul_f32 v[84:85], v[28:29], 0.5 op_sel_hi:[1,0]
	v_pk_mul_f32 v[82:83], v[22:23], 0.5 op_sel_hi:[1,0]
	v_pk_mul_f32 v[80:81], v[20:21], 0.5 op_sel_hi:[1,0]
	v_pk_mul_f32 v[78:79], v[42:43], 0.5 op_sel_hi:[1,0]
	v_pk_mul_f32 v[76:77], v[40:41], 0.5 op_sel_hi:[1,0]
	v_pk_mul_f32 v[74:75], v[34:35], 0.5 op_sel_hi:[1,0]
	v_pk_mul_f32 v[72:73], v[32:33], 0.5 op_sel_hi:[1,0]
	v_pk_mul_f32 v[70:71], v[14:15], 0.5 op_sel_hi:[1,0]
	v_pk_mul_f32 v[68:69], v[12:13], 0.5 op_sel_hi:[1,0]
	v_pk_mul_f32 v[66:67], v[10:11], 0.5 op_sel_hi:[1,0]
	v_pk_mul_f32 v[64:65], v[8:9], 0.5 op_sel_hi:[1,0]
	v_pk_mul_f32 v[62:63], v[26:27], 0.5 op_sel_hi:[1,0]
	v_pk_mul_f32 v[60:61], v[24:25], 0.5 op_sel_hi:[1,0]
	v_pk_mul_f32 v[58:59], v[18:19], 0.5 op_sel_hi:[1,0]
	v_pk_mul_f32 v[56:57], v[16:17], 0.5 op_sel_hi:[1,0]
	v_pk_mul_f32 v[54:55], v[6:7], 0.5 op_sel_hi:[1,0]
	v_pk_mul_f32 v[52:53], v[4:5], 0.5 op_sel_hi:[1,0]
	v_pk_mul_f32 v[50:51], v[2:3], 0.5 op_sel_hi:[1,0]
	v_pk_mul_f32 v[48:49], v[0:1], 0.5 op_sel_hi:[1,0]

; #define LAS __attribute__((address_space(3)))
; #define PG8_STAGE(bufoff, gbase, voff) do { _Pragma("unroll") for (int _i = 0; _i < 2; ++_i) \
;         __builtin_amdgcn_global_load_lds((const unsigned*)((const char*)(gbase) + (voff)[_i]), (LAS unsigned*)(lds + (bufoff) + ldsw + _i * 8192), 16, 0, 0); } while (0)
; #define PG8_LDA(dst, b, h) do { _Pragma("unroll") for (int m = 0; m < 4; ++m) _Pragma("unroll") for (int k = 0; k < 2; ++k) dst[m][k] = *(const LAS bf16x8*)(lds + PG8_SA(b, h) + aoff + m * 2048 + k * 1024); } while (0)
; #define PG8_LDB(dst, b, h) do { _Pragma("unroll") for (int n = 0; n < 2; ++n) _Pragma("unroll") for (int k = 0; k < 2; ++k) dst[n][k] = *(const LAS bf16x8*)(lds + PG8_SB(b, h) + boff + n * 2048 + k * 1024); } while (0)
; #define PG8_WAIT_V(n) asm volatile("s_waitcnt vmcnt(" #n ")" ::: "memory")
; #define PG8_WAIT_L(n) asm volatile("s_waitcnt lgkmcnt(" #n ")" ::: "memory")
; template <class Epi>
; __device__ __forceinline__ void gemm_phase(LAS unsigned char* lds, const int tid, const Gemm g, const StaticOrder& S, const Epi& E) {
;     ...
;         for (int t = 0; t < nt; t += 2) {
;             const bool last = (t == nt - 2);
;             const char* a1 = cA + (size_t)(t + 1) * kstep;
;             const char* a2 = last ? nA : cA + (size_t)(t + 2) * kstep; const char* b2 = last ? nB : cB + (size_t)(t + 2) * kstep;
;             const char* a3 = a2 + kstep; const char* b3 = b2 + kstep;
;             if constexpr (Epi::SS_LDS) { if (last) {
;                 const char* sp = (const char*)E.ss + (size_t)cur.pm * (256 * 64) + (size_t)tid * 16;
;                 __builtin_amdgcn_global_load_lds((const unsigned*)sp, (LAS unsigned*)(lds + RS_OFF + ldsw), 16, 0, 0);
;                 __builtin_amdgcn_global_load_lds((const unsigned*)(sp + 8192), (LAS unsigned*)(lds + RS_OFF + 8192 + ldsw), 16, 0, 0); } }
;     ...
;             PG8_LDB(B0, 0, 0); PG8_LDB(B1, 0, 1); PG8_SCHED; PG8_LDA(At, 0, 0); PG8_STAGE(PG8_SA(1, 1), a1 + hstepA, voffA);
;             PG8_WAIT_V(8); PG8_WAIT_L(0); PG8_BAR; PG8_MMA(0, 0, At, B0); PG8_MMA(0, 1, At, B1); PG8_BAR; PG8_SCHED;
;             PG8_LDA(At, 0, 1); PG8_STAGE(PG8_SB(0, 0), b2, voffB); PG8_STAGE(PG8_SB(0, 1), b2 + hstepB, voffB); PG8_STAGE(PG8_SA(0, 0), a2, voffA);
;             PG8_WAIT_V(8); PG8_WAIT_L(0); PG8_BAR; PG8_MMA(1, 0, At, B0); PG8_MMA(1, 1, At, B1); PG8_BAR; PG8_SCHED;
.LBB0_442:
	v_add_u32_e32 v136, s61, v171
	ds_read_b128 v[154:157], v136
	ds_read_b128 v[158:161], v136 offset:1024
	ds_read_b128 v[162:165], v136 offset:2048
	ds_read_b128 v[166:169], v136 offset:3072
	v_add_u32_e32 v136, s62, v171
	ds_read_b128 v[176:179], v136
	ds_read_b128 v[180:183], v136 offset:1024
	ds_read_b128 v[184:187], v136 offset:2048
	ds_read_b128 v[188:191], v136 offset:3072
	s_add_i32 s68, s68, 2
	s_add_u32 s40, s36, 0xfffc0080
	s_addc_u32 s41, s37, -1
	s_and_b64 s[38:39], s[38:39], exec
	s_cselect_b32 s41, s4, s41
	s_cselect_b32 s40, s25, s40
	s_cselect_b32 s39, s27, s67
	s_cselect_b32 s38, s66, s35
	v_lshl_add_u64 v[224:225], s[36:37], 0, v[144:145]
	s_add_i32 m0, s50, 0xc000
	ds_read_b128 v[192:195], v173
	ds_read_b128 v[196:199], v173 offset:1024
	ds_read_b128 v[200:203], v173 offset:2048
	ds_read_b128 v[204:207], v173 offset:3072
	ds_read_b128 v[208:211], v173 offset:4096
	ds_read_b128 v[212:215], v173 offset:5120
	ds_read_b128 v[216:219], v173 offset:6144
	ds_read_b128 v[220:223], v173 offset:7168
	global_load_lds_dwordx4 v[224:225], off
	v_lshl_add_u64 v[224:225], s[36:37], 0, v[142:143]
	s_add_i32 m0, s50, 0xe000
	s_nop 0
	global_load_lds_dwordx4 v[224:225], off
	s_waitcnt vmcnt(8)
	s_waitcnt lgkmcnt(0)
	s_barrier
	v_mfma_f32_16x16x32_bf16 v[124:127], v[154:157], v[192:195], v[124:127]
	v_mfma_f32_16x16x32_bf16 v[120:123], v[162:165], v[192:195], v[120:123]
	v_mfma_f32_16x16x32_bf16 v[108:111], v[154:157], v[200:203], v[108:111]
	v_mfma_f32_16x16x32_bf16 v[104:107], v[162:165], v[200:203], v[104:107]
	v_mfma_f32_16x16x32_bf16 v[92:95], v[154:157], v[208:211], v[92:95]
	v_mfma_f32_16x16x32_bf16 v[88:91], v[162:165], v[208:211], v[88:91]
	v_mfma_f32_16x16x32_bf16 v[76:79], v[154:157], v[216:219], v[76:79]
	v_mfma_f32_16x16x32_bf16 v[72:75], v[162:165], v[216:219], v[72:75]
	v_mfma_f32_16x16x32_bf16 v[124:127], v[158:161], v[196:199], v[124:127]
	v_mfma_f32_16x16x32_bf16 v[120:123], v[166:169], v[196:199], v[120:123]
	v_mfma_f32_16x16x32_bf16 v[108:111], v[158:161], v[204:207], v[108:111]
	v_mfma_f32_16x16x32_bf16 v[104:107], v[166:169], v[204:207], v[104:107]
	v_mfma_f32_16x16x32_bf16 v[92:95], v[158:161], v[212:215], v[92:95]
	v_mfma_f32_16x16x32_bf16 v[88:91], v[166:169], v[212:215], v[88:91]
	v_mfma_f32_16x16x32_bf16 v[76:79], v[158:161], v[220:223], v[76:79]
	v_mfma_f32_16x16x32_bf16 v[72:75], v[166:169], v[220:223], v[72:75]
	v_mfma_f32_16x16x32_bf16 v[116:119], v[176:179], v[192:195], v[116:119]
	v_mfma_f32_16x16x32_bf16 v[112:115], v[184:187], v[192:195], v[112:115]
	v_mfma_f32_16x16x32_bf16 v[100:103], v[176:179], v[200:203], v[100:103]
	v_mfma_f32_16x16x32_bf16 v[96:99], v[184:187], v[200:203], v[96:99]
	v_mfma_f32_16x16x32_bf16 v[84:87], v[176:179], v[208:211], v[84:87]
	v_mfma_f32_16x16x32_bf16 v[80:83], v[184:187], v[208:211], v[80:83]
	v_mfma_f32_16x16x32_bf16 v[68:71], v[176:179], v[216:219], v[68:71]
	v_mfma_f32_16x16x32_bf16 v[64:67], v[184:187], v[216:219], v[64:67]
	v_mfma_f32_16x16x32_bf16 v[116:119], v[180:183], v[196:199], v[116:119]
	v_mfma_f32_16x16x32_bf16 v[112:115], v[188:191], v[196:199], v[112:115]
	v_mfma_f32_16x16x32_bf16 v[100:103], v[180:183], v[204:207], v[100:103]
	v_mfma_f32_16x16x32_bf16 v[96:99], v[188:191], v[204:207], v[96:99]
	v_mfma_f32_16x16x32_bf16 v[84:87], v[180:183], v[212:215], v[84:87]
	v_mfma_f32_16x16x32_bf16 v[80:83], v[188:191], v[212:215], v[80:83]
	v_mfma_f32_16x16x32_bf16 v[68:71], v[180:183], v[220:223], v[68:71]
	v_mfma_f32_16x16x32_bf16 v[64:67], v[188:191], v[220:223], v[64:67]
	s_barrier
	s_add_i32 s69, s61, s47
	v_lshl_add_u64 v[224:225], s[38:39], 0, v[132:133]
	s_mov_b32 m0, s69
	ds_read_b128 v[192:195], v173 offset:16384
	ds_read_b128 v[196:199], v173 offset:17408
	ds_read_b128 v[200:203], v173 offset:18432
	ds_read_b128 v[204:207], v173 offset:19456
	ds_read_b128 v[208:211], v173 offset:20480
	ds_read_b128 v[212:215], v173 offset:21504
	ds_read_b128 v[216:219], v173 offset:22528
	ds_read_b128 v[220:223], v173 offset:23552
	global_load_lds_dwordx4 v[224:225], off
	s_add_i32 m0, s69, 0x2000
	s_add_u32 s70, s38, 0x40000
	v_lshl_add_u64 v[226:227], s[38:39], 0, v[128:129]
	s_addc_u32 s71, s39, 0
	s_add_i32 s69, s62, s47
	global_load_lds_dwordx4 v[226:227], off
	v_lshl_add_u64 v[228:229], s[70:71], 0, v[132:133]
	s_mov_b32 m0, s69
	v_lshl_add_u64 v[230:231], s[40:41], 0, v[130:131]
	global_load_lds_dwordx4 v[228:229], off
	v_lshl_add_u64 v[228:229], s[70:71], 0, v[128:129]
	s_add_i32 m0, s69, 0x2000
	s_nop 0
	global_load_lds_dwordx4 v[228:229], off
	v_lshl_add_u64 v[228:229], s[40:41], 0, v[134:135]
	s_mov_b32 m0, s50
	s_nop 0
	global_load_lds_dwordx4 v[228:229], off
	s_mov_b32 m0, s51
	s_nop 0
	global_load_lds_dwordx4 v[230:231], off
	s_waitcnt vmcnt(8)
	s_waitcnt lgkmcnt(0)
	s_barrier
; #define PG8_STAGE(bufoff, gbase, voff) do { _Pragma("unroll") for (int _i = 0; _i < 2; ++_i) \
;         __builtin_amdgcn_global_load_lds((const unsigned*)((const char*)(gbase) + (voff)[_i]), (LAS unsigned*)(lds + (bufoff) + ldsw + _i * 8192), 16, 0, 0); } while (0)
; #define PG8_LDA(dst, b, h) do { _Pragma("unroll") for (int m = 0; m < 4; ++m) _Pragma("unroll") for (int k = 0; k < 2; ++k) dst[m][k] = *(const LAS bf16x8*)(lds + PG8_SA(b, h) + aoff + m * 2048 + k * 1024); } while (0)
; #define PG8_LDB(dst, b, h) do { _Pragma("unroll") for (int n = 0; n < 2; ++n) _Pragma("unroll") for (int k = 0; k < 2; ++k) dst[n][k] = *(const LAS bf16x8*)(lds + PG8_SB(b, h) + boff + n * 2048 + k * 1024); } while (0)
; #define PG8_MMA(ai, bj, At, Bt) do { __builtin_amdgcn_s_setprio(1); _Pragma("unroll") for (int m = 0; m < 4; ++m) _Pragma("unroll") for (int n = 0; n < 2; ++n) _Pragma("unroll") for (int k = 0; k < 2; ++k) \
;         acc[ai][bj][m][n] = __builtin_amdgcn_mfma_f32_16x16x32_bf16(Bt[n][k], At[m][k], acc[ai][bj][m][n], 0, 0, 0); __builtin_amdgcn_s_setprio(0); } while (0)
; #define PG8_WAIT_V(n) asm volatile("s_waitcnt vmcnt(" #n ")" ::: "memory")
; #define PG8_WAIT_L(n) asm volatile("s_waitcnt lgkmcnt(" #n ")" ::: "memory")
; #define PG8_BAR __builtin_amdgcn_s_barrier()
; #define PG8_SCHED __builtin_amdgcn_sched_barrier(0)
; template <class Epi>
; __device__ __forceinline__ void gemm_phase(LAS unsigned char* lds, const int tid, const Gemm g, const StaticOrder& S, const Epi& E) {
;     ...
;             PG8_WAIT_V(8); PG8_WAIT_L(0); PG8_BAR; PG8_MMA(1, 0, At, B0); PG8_MMA(1, 1, At, B1); PG8_BAR; PG8_SCHED;
;             PG8_LDB(B0, 1, 0); PG8_LDB(B1, 1, 1); PG8_SCHED; PG8_LDA(At, 1, 0); PG8_STAGE(PG8_SA(0, 1), a2 + hstepA, voffA);
;             PG8_WAIT_V(8); PG8_WAIT_L(0); PG8_BAR; PG8_MMA(0, 0, At, B0); PG8_MMA(0, 1, At, B1); PG8_BAR; PG8_SCHED;
	v_mfma_f32_16x16x32_bf16 v[60:63], v[154:157], v[192:195], v[60:63]
	v_mfma_f32_16x16x32_bf16 v[56:59], v[162:165], v[192:195], v[56:59]
	v_mfma_f32_16x16x32_bf16 v[44:47], v[154:157], v[200:203], v[44:47]
	v_mfma_f32_16x16x32_bf16 v[40:43], v[162:165], v[200:203], v[40:43]
	v_mfma_f32_16x16x32_bf16 v[28:31], v[154:157], v[208:211], v[28:31]
	v_mfma_f32_16x16x32_bf16 v[24:27], v[162:165], v[208:211], v[24:27]
	v_mfma_f32_16x16x32_bf16 v[12:15], v[154:157], v[216:219], v[12:15]
	v_mfma_f32_16x16x32_bf16 v[8:11], v[162:165], v[216:219], v[8:11]
	v_mfma_f32_16x16x32_bf16 v[60:63], v[158:161], v[196:199], v[60:63]
	v_mfma_f32_16x16x32_bf16 v[56:59], v[166:169], v[196:199], v[56:59]
	v_mfma_f32_16x16x32_bf16 v[44:47], v[158:161], v[204:207], v[44:47]
	v_mfma_f32_16x16x32_bf16 v[40:43], v[166:169], v[204:207], v[40:43]
	v_mfma_f32_16x16x32_bf16 v[28:31], v[158:161], v[212:215], v[28:31]
	v_mfma_f32_16x16x32_bf16 v[24:27], v[166:169], v[212:215], v[24:27]
	v_mfma_f32_16x16x32_bf16 v[12:15], v[158:161], v[220:223], v[12:15]
	v_mfma_f32_16x16x32_bf16 v[8:11], v[166:169], v[220:223], v[8:11]
	v_mfma_f32_16x16x32_bf16 v[52:55], v[176:179], v[192:195], v[52:55]
	v_mfma_f32_16x16x32_bf16 v[48:51], v[184:187], v[192:195], v[48:51]
	v_mfma_f32_16x16x32_bf16 v[36:39], v[176:179], v[200:203], v[36:39]
	v_mfma_f32_16x16x32_bf16 v[32:35], v[184:187], v[200:203], v[32:35]
	v_mfma_f32_16x16x32_bf16 v[20:23], v[176:179], v[208:211], v[20:23]
	v_mfma_f32_16x16x32_bf16 v[16:19], v[184:187], v[208:211], v[16:19]
	v_mfma_f32_16x16x32_bf16 v[4:7], v[176:179], v[216:219], v[4:7]
	v_mfma_f32_16x16x32_bf16 v[0:3], v[184:187], v[216:219], v[0:3]
	v_mfma_f32_16x16x32_bf16 v[52:55], v[180:183], v[196:199], v[52:55]
	v_mfma_f32_16x16x32_bf16 v[48:51], v[188:191], v[196:199], v[48:51]
	v_mfma_f32_16x16x32_bf16 v[36:39], v[180:183], v[204:207], v[36:39]
	v_mfma_f32_16x16x32_bf16 v[32:35], v[188:191], v[204:207], v[32:35]
	v_mfma_f32_16x16x32_bf16 v[20:23], v[180:183], v[212:215], v[20:23]
	v_mfma_f32_16x16x32_bf16 v[16:19], v[188:191], v[212:215], v[16:19]
	v_mfma_f32_16x16x32_bf16 v[4:7], v[180:183], v[220:223], v[4:7]
	v_mfma_f32_16x16x32_bf16 v[0:3], v[188:191], v[220:223], v[0:3]
	s_barrier
	s_add_i32 s69, 0, 0x18000
	v_add_u32_e32 v136, s69, v171
	s_add_i32 s70, 0, 0x1c000
	ds_read_b128 v[154:157], v136
	ds_read_b128 v[158:161], v136 offset:1024
	ds_read_b128 v[162:165], v136 offset:2048
	ds_read_b128 v[166:169], v136 offset:3072
	v_add_u32_e32 v136, s70, v171
	ds_read_b128 v[176:179], v136
	ds_read_b128 v[180:183], v136 offset:1024
	ds_read_b128 v[184:187], v136 offset:2048
	ds_read_b128 v[188:191], v136 offset:3072
	s_add_u32 s40, s40, 0x40000
	s_addc_u32 s41, s41, 0
	s_mov_b32 m0, s52
	v_lshl_add_u64 v[232:233], s[40:41], 0, v[134:135]
	ds_read_b128 v[192:195], v173 offset:32768
	ds_read_b128 v[196:199], v173 offset:33792
	ds_read_b128 v[200:203], v173 offset:34816
	ds_read_b128 v[204:207], v173 offset:35840
	ds_read_b128 v[208:211], v173 offset:36864
	ds_read_b128 v[212:215], v173 offset:37888
	ds_read_b128 v[216:219], v173 offset:38912
	ds_read_b128 v[220:223], v173 offset:39936
	global_load_lds_dwordx4 v[232:233], off
	v_lshl_add_u64 v[232:233], s[40:41], 0, v[130:131]
	s_mov_b32 m0, s53
	s_nop 0
	global_load_lds_dwordx4 v[232:233], off
	s_waitcnt vmcnt(8)
	s_waitcnt lgkmcnt(0)
	s_barrier
	v_mfma_f32_16x16x32_bf16 v[124:127], v[154:157], v[192:195], v[124:127]
	v_mfma_f32_16x16x32_bf16 v[120:123], v[162:165], v[192:195], v[120:123]
	v_mfma_f32_16x16x32_bf16 v[108:111], v[154:157], v[200:203], v[108:111]
	v_mfma_f32_16x16x32_bf16 v[104:107], v[162:165], v[200:203], v[104:107]
	v_mfma_f32_16x16x32_bf16 v[92:95], v[154:157], v[208:211], v[92:95]
	v_mfma_f32_16x16x32_bf16 v[88:91], v[162:165], v[208:211], v[88:91]
	v_mfma_f32_16x16x32_bf16 v[76:79], v[154:157], v[216:219], v[76:79]
	v_mfma_f32_16x16x32_bf16 v[72:75], v[162:165], v[216:219], v[72:75]
	v_mfma_f32_16x16x32_bf16 v[124:127], v[158:161], v[196:199], v[124:127]
	v_mfma_f32_16x16x32_bf16 v[120:123], v[166:169], v[196:199], v[120:123]
	v_mfma_f32_16x16x32_bf16 v[108:111], v[158:161], v[204:207], v[108:111]
	v_mfma_f32_16x16x32_bf16 v[104:107], v[166:169], v[204:207], v[104:107]
	v_mfma_f32_16x16x32_bf16 v[92:95], v[158:161], v[212:215], v[92:95]
	v_mfma_f32_16x16x32_bf16 v[88:91], v[166:169], v[212:215], v[88:91]
	v_mfma_f32_16x16x32_bf16 v[76:79], v[158:161], v[220:223], v[76:79]
	v_mfma_f32_16x16x32_bf16 v[72:75], v[166:169], v[220:223], v[72:75]
	v_mfma_f32_16x16x32_bf16 v[116:119], v[176:179], v[192:195], v[116:119]
	v_mfma_f32_16x16x32_bf16 v[112:115], v[184:187], v[192:195], v[112:115]
	v_mfma_f32_16x16x32_bf16 v[100:103], v[176:179], v[200:203], v[100:103]
	v_mfma_f32_16x16x32_bf16 v[96:99], v[184:187], v[200:203], v[96:99]
	v_mfma_f32_16x16x32_bf16 v[84:87], v[176:179], v[208:211], v[84:87]
	v_mfma_f32_16x16x32_bf16 v[80:83], v[184:187], v[208:211], v[80:83]
	v_mfma_f32_16x16x32_bf16 v[68:71], v[176:179], v[216:219], v[68:71]
	v_mfma_f32_16x16x32_bf16 v[64:67], v[184:187], v[216:219], v[64:67]
	v_mfma_f32_16x16x32_bf16 v[116:119], v[180:183], v[196:199], v[116:119]
	v_mfma_f32_16x16x32_bf16 v[112:115], v[188:191], v[196:199], v[112:115]
	v_mfma_f32_16x16x32_bf16 v[100:103], v[180:183], v[204:207], v[100:103]
	v_mfma_f32_16x16x32_bf16 v[96:99], v[188:191], v[204:207], v[96:99]
	v_mfma_f32_16x16x32_bf16 v[84:87], v[180:183], v[212:215], v[84:87]
	v_mfma_f32_16x16x32_bf16 v[80:83], v[188:191], v[212:215], v[80:83]
	v_mfma_f32_16x16x32_bf16 v[68:71], v[180:183], v[220:223], v[68:71]
	v_mfma_f32_16x16x32_bf16 v[64:67], v[188:191], v[220:223], v[64:67]
	s_barrier
; #define PG8_STAGE(bufoff, gbase, voff) do { _Pragma("unroll") for (int _i = 0; _i < 2; ++_i) \
;         __builtin_amdgcn_global_load_lds((const unsigned*)((const char*)(gbase) + (voff)[_i]), (LAS unsigned*)(lds + (bufoff) + ldsw + _i * 8192), 16, 0, 0); } while (0)
; #define PG8_LDA(dst, b, h) do { _Pragma("unroll") for (int m = 0; m < 4; ++m) _Pragma("unroll") for (int k = 0; k < 2; ++k) dst[m][k] = *(const LAS bf16x8*)(lds + PG8_SA(b, h) + aoff + m * 2048 + k * 1024); } while (0)
; #define PG8_MMA(ai, bj, At, Bt) do { __builtin_amdgcn_s_setprio(1); _Pragma("unroll") for (int m = 0; m < 4; ++m) _Pragma("unroll") for (int n = 0; n < 2; ++n) _Pragma("unroll") for (int k = 0; k < 2; ++k) \
;         acc[ai][bj][m][n] = __builtin_amdgcn_mfma_f32_16x16x32_bf16(Bt[n][k], At[m][k], acc[ai][bj][m][n], 0, 0, 0); __builtin_amdgcn_s_setprio(0); } while (0)
; #define PG8_WAIT_V(n) asm volatile("s_waitcnt vmcnt(" #n ")" ::: "memory")
; #define PG8_WAIT_L(n) asm volatile("s_waitcnt lgkmcnt(" #n ")" ::: "memory")
; #define PG8_BAR __builtin_amdgcn_s_barrier()
; #define PG8_SCHED __builtin_amdgcn_sched_barrier(0)
; template <class Epi>
; __device__ __forceinline__ void gemm_phase(LAS unsigned char* lds, const int tid, const Gemm g, const StaticOrder& S, const Epi& E) {
;     ...
;             PG8_LDA(At, 1, 1); PG8_STAGE(PG8_SB(1, 0), b3, voffB); PG8_STAGE(PG8_SB(1, 1), b3 + hstepB, voffB); PG8_STAGE(PG8_SA(1, 0), a3, voffA);
;             PG8_WAIT_V(8); PG8_WAIT_L(0); PG8_BAR; PG8_MMA(1, 0, At, B0); PG8_MMA(1, 1, At, B1); PG8_BAR; PG8_SCHED;
	s_add_i32 s40, s69, s47
	v_lshl_add_u64 v[224:225], v[224:225], 0, s[16:17]
	s_mov_b32 m0, s40
	ds_read_b128 v[192:195], v173 offset:49152
	ds_read_b128 v[196:199], v173 offset:50176
	ds_read_b128 v[200:203], v173 offset:51200
	ds_read_b128 v[204:207], v173 offset:52224
	ds_read_b128 v[208:211], v173 offset:53248
	ds_read_b128 v[212:215], v173 offset:54272
	ds_read_b128 v[216:219], v173 offset:55296
	ds_read_b128 v[220:223], v173 offset:56320
	global_load_lds_dwordx4 v[224:225], off
	s_add_i32 m0, s40, 0x2000
	s_add_u32 s38, s38, 0x40080
	v_lshl_add_u64 v[224:225], v[226:227], 0, s[16:17]
	s_addc_u32 s39, s39, 0
	s_add_i32 s40, s70, s47
	global_load_lds_dwordx4 v[224:225], off
	v_lshl_add_u64 v[224:225], s[38:39], 0, v[132:133]
	s_mov_b32 m0, s40
	s_nop 0
	global_load_lds_dwordx4 v[224:225], off
	v_lshl_add_u64 v[224:225], s[38:39], 0, v[128:129]
	s_add_i32 m0, s40, 0x2000
	s_nop 0
	global_load_lds_dwordx4 v[224:225], off
	v_lshl_add_u64 v[224:225], v[228:229], 0, s[16:17]
	s_mov_b32 m0, s57
	s_nop 0
	global_load_lds_dwordx4 v[224:225], off
	v_lshl_add_u64 v[224:225], v[230:231], 0, s[16:17]
	s_mov_b32 m0, s58
	s_nop 0
	global_load_lds_dwordx4 v[224:225], off
	s_waitcnt vmcnt(8)
	s_waitcnt lgkmcnt(0)
	s_barrier
	v_mfma_f32_16x16x32_bf16 v[60:63], v[154:157], v[192:195], v[60:63]
	v_mfma_f32_16x16x32_bf16 v[56:59], v[162:165], v[192:195], v[56:59]
	v_mfma_f32_16x16x32_bf16 v[44:47], v[154:157], v[200:203], v[44:47]
	v_mfma_f32_16x16x32_bf16 v[40:43], v[162:165], v[200:203], v[40:43]
	v_mfma_f32_16x16x32_bf16 v[28:31], v[154:157], v[208:211], v[28:31]
	v_mfma_f32_16x16x32_bf16 v[24:27], v[162:165], v[208:211], v[24:27]
	v_mfma_f32_16x16x32_bf16 v[12:15], v[154:157], v[216:219], v[12:15]
	v_mfma_f32_16x16x32_bf16 v[8:11], v[162:165], v[216:219], v[8:11]
	v_mfma_f32_16x16x32_bf16 v[60:63], v[158:161], v[196:199], v[60:63]
	v_mfma_f32_16x16x32_bf16 v[56:59], v[166:169], v[196:199], v[56:59]
	v_mfma_f32_16x16x32_bf16 v[44:47], v[158:161], v[204:207], v[44:47]
	v_mfma_f32_16x16x32_bf16 v[40:43], v[166:169], v[204:207], v[40:43]
	v_mfma_f32_16x16x32_bf16 v[28:31], v[158:161], v[212:215], v[28:31]
	v_mfma_f32_16x16x32_bf16 v[24:27], v[166:169], v[212:215], v[24:27]
	v_mfma_f32_16x16x32_bf16 v[12:15], v[158:161], v[220:223], v[12:15]
	v_mfma_f32_16x16x32_bf16 v[8:11], v[166:169], v[220:223], v[8:11]
	v_mfma_f32_16x16x32_bf16 v[52:55], v[176:179], v[192:195], v[52:55]
	v_mfma_f32_16x16x32_bf16 v[48:51], v[184:187], v[192:195], v[48:51]
	v_mfma_f32_16x16x32_bf16 v[36:39], v[176:179], v[200:203], v[36:39]
	v_mfma_f32_16x16x32_bf16 v[32:35], v[184:187], v[200:203], v[32:35]
	v_mfma_f32_16x16x32_bf16 v[20:23], v[176:179], v[208:211], v[20:23]
	v_mfma_f32_16x16x32_bf16 v[16:19], v[184:187], v[208:211], v[16:19]
	v_mfma_f32_16x16x32_bf16 v[4:7], v[176:179], v[216:219], v[4:7]
	v_mfma_f32_16x16x32_bf16 v[0:3], v[184:187], v[216:219], v[0:3]
	v_mfma_f32_16x16x32_bf16 v[52:55], v[180:183], v[196:199], v[52:55]
	v_mfma_f32_16x16x32_bf16 v[48:51], v[188:191], v[196:199], v[48:51]
	v_mfma_f32_16x16x32_bf16 v[36:39], v[180:183], v[204:207], v[36:39]
	v_mfma_f32_16x16x32_bf16 v[32:35], v[188:191], v[204:207], v[32:35]
	v_mfma_f32_16x16x32_bf16 v[20:23], v[180:183], v[212:215], v[20:23]
	v_mfma_f32_16x16x32_bf16 v[16:19], v[188:191], v[212:215], v[16:19]
	v_mfma_f32_16x16x32_bf16 v[4:7], v[180:183], v[220:223], v[4:7]
	v_mfma_f32_16x16x32_bf16 v[0:3], v[188:191], v[220:223], v[0:3]
	s_barrier
	s_add_u32 s35, s35, 0x100
	s_addc_u32 s67, s67, 0
	s_add_u32 s36, s36, 0x100
	s_addc_u32 s37, s37, 0
	s_cmp_ge_i32 s68, s55
	s_cbranch_scc1 .LBB0_445

; #define LAS __attribute__((address_space(3)))
; #define PG8_STAGE(bufoff, gbase, voff) do { _Pragma("unroll") for (int _i = 0; _i < 2; ++_i) \
;         __builtin_amdgcn_global_load_lds((const unsigned*)((const char*)(gbase) + (voff)[_i]), (LAS unsigned*)(lds + (bufoff) + ldsw + _i * 8192), 16, 0, 0); } while (0)
; #define PG8_LDA(dst, b, h) do { _Pragma("unroll") for (int m = 0; m < 4; ++m) _Pragma("unroll") for (int k = 0; k < 2; ++k) dst[m][k] = *(const LAS bf16x8*)(lds + PG8_SA(b, h) + aoff + m * 2048 + k * 1024); } while (0)
; #define PG8_LDB(dst, b, h) do { _Pragma("unroll") for (int n = 0; n < 2; ++n) _Pragma("unroll") for (int k = 0; k < 2; ++k) dst[n][k] = *(const LAS bf16x8*)(lds + PG8_SB(b, h) + boff + n * 2048 + k * 1024); } while (0)
; #define PG8_WAIT_V(n) asm volatile("s_waitcnt vmcnt(" #n ")" ::: "memory")
; #define PG8_WAIT_L(n) asm volatile("s_waitcnt lgkmcnt(" #n ")" ::: "memory")
; template <class Epi>
; __device__ __forceinline__ void gemm_phase(LAS unsigned char* lds, const int tid, const Gemm g, const StaticOrder& S, const Epi& E) {
;     ...
;         for (int t = 0; t < nt; t += 2) {
;             const bool last = (t == nt - 2);
;             const char* a1 = cA + (size_t)(t + 1) * kstep;
;             const char* a2 = last ? nA : cA + (size_t)(t + 2) * kstep; const char* b2 = last ? nB : cB + (size_t)(t + 2) * kstep;
;             const char* a3 = a2 + kstep; const char* b3 = b2 + kstep;
;             if constexpr (Epi::SS_LDS) { if (last) {
;                 const char* sp = (const char*)E.ss + (size_t)cur.pm * (256 * 64) + (size_t)tid * 16;
;                 __builtin_amdgcn_global_load_lds((const unsigned*)sp, (LAS unsigned*)(lds + RS_OFF + ldsw), 16, 0, 0);
;                 __builtin_amdgcn_global_load_lds((const unsigned*)(sp + 8192), (LAS unsigned*)(lds + RS_OFF + 8192 + ldsw), 16, 0, 0); } }
;     ...
;             PG8_LDB(B0, 0, 0); PG8_LDB(B1, 0, 1); PG8_SCHED; PG8_LDA(At, 0, 0); PG8_STAGE(PG8_SA(1, 1), a1 + hstepA, voffA);
;             PG8_WAIT_V(8); PG8_WAIT_L(0); PG8_BAR; PG8_MMA(0, 0, At, B0); PG8_MMA(0, 1, At, B1); PG8_BAR; PG8_SCHED;
;             PG8_LDA(At, 0, 1); PG8_STAGE(PG8_SB(0, 0), b2, voffB); PG8_STAGE(PG8_SB(0, 1), b2 + hstepB, voffB); PG8_STAGE(PG8_SA(0, 0), a2, voffA);
;             PG8_WAIT_V(8); PG8_WAIT_L(0); PG8_BAR; PG8_MMA(1, 0, At, B0); PG8_MMA(1, 1, At, B1); PG8_BAR; PG8_SCHED;
.LBB0_728:
	ds_read_b128 v[128:131], v189
	ds_read_b128 v[132:135], v189 offset:1024
	ds_read_b128 v[136:139], v189 offset:2048
	ds_read_b128 v[140:143], v189 offset:3072
	ds_read_b128 v[144:147], v190
	ds_read_b128 v[148:151], v190 offset:1024
	ds_read_b128 v[168:171], v190 offset:2048
	ds_read_b128 v[172:175], v190 offset:3072
	s_add_i32 s60, s34, 2
	s_add_u32 s35, s30, 0xfffc0080
	s_addc_u32 s36, s31, -1
	s_cmp_eq_u32 s51, s34
	s_cselect_b32 s34, s57, s58
	s_cselect_b32 s37, s21, s36
	s_cselect_b32 s36, s23, s35
	s_cselect_b32 s35, s29, s59
	v_lshl_add_u64 v[184:185], s[30:31], 0, v[162:163]
	s_add_i32 m0, s43, 0xc000
	ds_read_b128 v[176:179], v191
	ds_read_b128 v[180:183], v191 offset:1024
	ds_read_b128 v[192:195], v191 offset:2048
	ds_read_b128 v[196:199], v191 offset:3072
	ds_read_b128 v[200:203], v191 offset:4096
	ds_read_b128 v[204:207], v191 offset:5120
	ds_read_b128 v[208:211], v191 offset:6144
	ds_read_b128 v[212:215], v191 offset:7168
	global_load_lds_dwordx4 v[184:185], off
	v_lshl_add_u64 v[184:185], s[30:31], 0, v[160:161]
	s_add_i32 m0, s43, 0xe000
	s_nop 0
	global_load_lds_dwordx4 v[184:185], off
	s_waitcnt vmcnt(8)
	s_waitcnt lgkmcnt(0)
	s_barrier
	v_mfma_f32_16x16x32_bf16 v[120:123], v[128:131], v[176:179], v[120:123]
	v_mfma_f32_16x16x32_bf16 v[124:127], v[136:139], v[176:179], v[124:127]
	v_mfma_f32_16x16x32_bf16 v[108:111], v[128:131], v[192:195], v[108:111]
	v_mfma_f32_16x16x32_bf16 v[104:107], v[136:139], v[192:195], v[104:107]
	v_mfma_f32_16x16x32_bf16 v[92:95], v[128:131], v[200:203], v[92:95]
	v_mfma_f32_16x16x32_bf16 v[88:91], v[136:139], v[200:203], v[88:91]
	v_mfma_f32_16x16x32_bf16 v[76:79], v[128:131], v[208:211], v[76:79]
	v_mfma_f32_16x16x32_bf16 v[72:75], v[136:139], v[208:211], v[72:75]
	v_mfma_f32_16x16x32_bf16 v[120:123], v[132:135], v[180:183], v[120:123]
	v_mfma_f32_16x16x32_bf16 v[124:127], v[140:143], v[180:183], v[124:127]
	v_mfma_f32_16x16x32_bf16 v[108:111], v[132:135], v[196:199], v[108:111]
	v_mfma_f32_16x16x32_bf16 v[104:107], v[140:143], v[196:199], v[104:107]
	v_mfma_f32_16x16x32_bf16 v[92:95], v[132:135], v[204:207], v[92:95]
	v_mfma_f32_16x16x32_bf16 v[88:91], v[140:143], v[204:207], v[88:91]
	v_mfma_f32_16x16x32_bf16 v[76:79], v[132:135], v[212:215], v[76:79]
	v_mfma_f32_16x16x32_bf16 v[72:75], v[140:143], v[212:215], v[72:75]
	v_mfma_f32_16x16x32_bf16 v[116:119], v[144:147], v[176:179], v[116:119]
	v_mfma_f32_16x16x32_bf16 v[112:115], v[168:171], v[176:179], v[112:115]
	v_mfma_f32_16x16x32_bf16 v[100:103], v[144:147], v[192:195], v[100:103]
	v_mfma_f32_16x16x32_bf16 v[96:99], v[168:171], v[192:195], v[96:99]
	v_mfma_f32_16x16x32_bf16 v[84:87], v[144:147], v[200:203], v[84:87]
	v_mfma_f32_16x16x32_bf16 v[80:83], v[168:171], v[200:203], v[80:83]
	v_mfma_f32_16x16x32_bf16 v[68:71], v[144:147], v[208:211], v[68:71]
	v_mfma_f32_16x16x32_bf16 v[64:67], v[168:171], v[208:211], v[64:67]
	v_mfma_f32_16x16x32_bf16 v[116:119], v[148:151], v[180:183], v[116:119]
	v_mfma_f32_16x16x32_bf16 v[112:115], v[172:175], v[180:183], v[112:115]
	v_mfma_f32_16x16x32_bf16 v[100:103], v[148:151], v[196:199], v[100:103]
	v_mfma_f32_16x16x32_bf16 v[96:99], v[172:175], v[196:199], v[96:99]
	v_mfma_f32_16x16x32_bf16 v[84:87], v[148:151], v[204:207], v[84:87]
	v_mfma_f32_16x16x32_bf16 v[80:83], v[172:175], v[204:207], v[80:83]
	v_mfma_f32_16x16x32_bf16 v[68:71], v[148:151], v[212:215], v[68:71]
	v_mfma_f32_16x16x32_bf16 v[64:67], v[172:175], v[212:215], v[64:67]
	s_barrier
	s_add_i32 s61, s54, s42
	v_lshl_add_u64 v[184:185], s[34:35], 0, v[154:155]
	s_mov_b32 m0, s61
	ds_read_b128 v[176:179], v191 offset:16384
	ds_read_b128 v[180:183], v191 offset:17408
	ds_read_b128 v[192:195], v191 offset:18432
	ds_read_b128 v[196:199], v191 offset:19456
	ds_read_b128 v[200:203], v191 offset:20480
	ds_read_b128 v[204:207], v191 offset:21504
	ds_read_b128 v[208:211], v191 offset:22528
	ds_read_b128 v[212:215], v191 offset:23552
	global_load_lds_dwordx4 v[184:185], off
	s_add_i32 m0, s61, 0x2000
	s_add_u32 s62, s34, 0x40000
	v_lshl_add_u64 v[216:217], s[34:35], 0, v[158:159]
	s_addc_u32 s63, s35, 0
	s_add_i32 s61, s55, s42
	global_load_lds_dwordx4 v[216:217], off
	v_lshl_add_u64 v[218:219], s[62:63], 0, v[154:155]
	s_mov_b32 m0, s61
	v_lshl_add_u64 v[220:221], s[36:37], 0, v[156:157]
	global_load_lds_dwordx4 v[218:219], off
	v_lshl_add_u64 v[218:219], s[62:63], 0, v[158:159]
	s_add_i32 m0, s61, 0x2000
	s_nop 0
	global_load_lds_dwordx4 v[218:219], off
	v_lshl_add_u64 v[218:219], s[36:37], 0, v[152:153]
	s_mov_b32 m0, s43
	s_nop 0
	global_load_lds_dwordx4 v[218:219], off
	s_mov_b32 m0, s44
	s_nop 0
	global_load_lds_dwordx4 v[220:221], off
	s_waitcnt vmcnt(8)
	s_waitcnt lgkmcnt(0)
	s_barrier
; #define PG8_STAGE(bufoff, gbase, voff) do { _Pragma("unroll") for (int _i = 0; _i < 2; ++_i) \
;         __builtin_amdgcn_global_load_lds((const unsigned*)((const char*)(gbase) + (voff)[_i]), (LAS unsigned*)(lds + (bufoff) + ldsw + _i * 8192), 16, 0, 0); } while (0)
; #define PG8_LDA(dst, b, h) do { _Pragma("unroll") for (int m = 0; m < 4; ++m) _Pragma("unroll") for (int k = 0; k < 2; ++k) dst[m][k] = *(const LAS bf16x8*)(lds + PG8_SA(b, h) + aoff + m * 2048 + k * 1024); } while (0)
; #define PG8_LDB(dst, b, h) do { _Pragma("unroll") for (int n = 0; n < 2; ++n) _Pragma("unroll") for (int k = 0; k < 2; ++k) dst[n][k] = *(const LAS bf16x8*)(lds + PG8_SB(b, h) + boff + n * 2048 + k * 1024); } while (0)
; #define PG8_MMA(ai, bj, At, Bt) do { __builtin_amdgcn_s_setprio(1); _Pragma("unroll") for (int m = 0; m < 4; ++m) _Pragma("unroll") for (int n = 0; n < 2; ++n) _Pragma("unroll") for (int k = 0; k < 2; ++k) \
;         acc[ai][bj][m][n] = __builtin_amdgcn_mfma_f32_16x16x32_bf16(Bt[n][k], At[m][k], acc[ai][bj][m][n], 0, 0, 0); __builtin_amdgcn_s_setprio(0); } while (0)
; #define PG8_WAIT_V(n) asm volatile("s_waitcnt vmcnt(" #n ")" ::: "memory")
; #define PG8_WAIT_L(n) asm volatile("s_waitcnt lgkmcnt(" #n ")" ::: "memory")
; #define PG8_BAR __builtin_amdgcn_s_barrier()
; #define PG8_SCHED __builtin_amdgcn_sched_barrier(0)
; template <class Epi>
; __device__ __forceinline__ void gemm_phase(LAS unsigned char* lds, const int tid, const Gemm g, const StaticOrder& S, const Epi& E) {
;     ...
;             PG8_WAIT_V(8); PG8_WAIT_L(0); PG8_BAR; PG8_MMA(1, 0, At, B0); PG8_MMA(1, 1, At, B1); PG8_BAR; PG8_SCHED;
;             PG8_LDB(B0, 1, 0); PG8_LDB(B1, 1, 1); PG8_SCHED; PG8_LDA(At, 1, 0); PG8_STAGE(PG8_SA(0, 1), a2 + hstepA, voffA);
;             PG8_WAIT_V(8); PG8_WAIT_L(0); PG8_BAR; PG8_MMA(0, 0, At, B0); PG8_MMA(0, 1, At, B1); PG8_BAR; PG8_SCHED;
	v_mfma_f32_16x16x32_bf16 v[60:63], v[128:131], v[176:179], v[60:63]
	v_mfma_f32_16x16x32_bf16 v[56:59], v[136:139], v[176:179], v[56:59]
	v_mfma_f32_16x16x32_bf16 v[44:47], v[128:131], v[192:195], v[44:47]
	v_mfma_f32_16x16x32_bf16 v[40:43], v[136:139], v[192:195], v[40:43]
	v_mfma_f32_16x16x32_bf16 v[28:31], v[128:131], v[200:203], v[28:31]
	v_mfma_f32_16x16x32_bf16 v[24:27], v[136:139], v[200:203], v[24:27]
	v_mfma_f32_16x16x32_bf16 v[12:15], v[128:131], v[208:211], v[12:15]
	v_mfma_f32_16x16x32_bf16 v[8:11], v[136:139], v[208:211], v[8:11]
	v_mfma_f32_16x16x32_bf16 v[60:63], v[132:135], v[180:183], v[60:63]
	v_mfma_f32_16x16x32_bf16 v[56:59], v[140:143], v[180:183], v[56:59]
	v_mfma_f32_16x16x32_bf16 v[44:47], v[132:135], v[196:199], v[44:47]
	v_mfma_f32_16x16x32_bf16 v[40:43], v[140:143], v[196:199], v[40:43]
	v_mfma_f32_16x16x32_bf16 v[28:31], v[132:135], v[204:207], v[28:31]
	v_mfma_f32_16x16x32_bf16 v[24:27], v[140:143], v[204:207], v[24:27]
	v_mfma_f32_16x16x32_bf16 v[12:15], v[132:135], v[212:215], v[12:15]
	v_mfma_f32_16x16x32_bf16 v[8:11], v[140:143], v[212:215], v[8:11]
	v_mfma_f32_16x16x32_bf16 v[52:55], v[144:147], v[176:179], v[52:55]
	v_mfma_f32_16x16x32_bf16 v[48:51], v[168:171], v[176:179], v[48:51]
	v_mfma_f32_16x16x32_bf16 v[36:39], v[144:147], v[192:195], v[36:39]
	v_mfma_f32_16x16x32_bf16 v[32:35], v[168:171], v[192:195], v[32:35]
	v_mfma_f32_16x16x32_bf16 v[20:23], v[144:147], v[200:203], v[20:23]
	v_mfma_f32_16x16x32_bf16 v[16:19], v[168:171], v[200:203], v[16:19]
	v_mfma_f32_16x16x32_bf16 v[4:7], v[144:147], v[208:211], v[4:7]
	v_mfma_f32_16x16x32_bf16 v[0:3], v[168:171], v[208:211], v[0:3]
	v_mfma_f32_16x16x32_bf16 v[52:55], v[148:151], v[180:183], v[52:55]
	v_mfma_f32_16x16x32_bf16 v[48:51], v[172:175], v[180:183], v[48:51]
	v_mfma_f32_16x16x32_bf16 v[36:39], v[148:151], v[196:199], v[36:39]
	v_mfma_f32_16x16x32_bf16 v[32:35], v[172:175], v[196:199], v[32:35]
	v_mfma_f32_16x16x32_bf16 v[20:23], v[148:151], v[204:207], v[20:23]
	v_mfma_f32_16x16x32_bf16 v[16:19], v[172:175], v[204:207], v[16:19]
	v_mfma_f32_16x16x32_bf16 v[4:7], v[148:151], v[212:215], v[4:7]
	v_mfma_f32_16x16x32_bf16 v[0:3], v[172:175], v[212:215], v[0:3]
	s_barrier
	s_add_i32 s61, 0, 0x18000
	s_add_i32 s62, 0, 0x1c000
	v_add_u32_e32 v140, s61, v187
	v_add_u32_e32 v172, s62, v187
	ds_read_b128 v[128:131], v140
	ds_read_b128 v[132:135], v140 offset:1024
	ds_read_b128 v[136:139], v140 offset:2048
	ds_read_b128 v[140:143], v140 offset:3072
	ds_read_b128 v[144:147], v172
	ds_read_b128 v[148:151], v172 offset:1024
	ds_read_b128 v[168:171], v172 offset:2048
	ds_read_b128 v[172:175], v172 offset:3072
	s_add_u32 s36, s36, 0x40000
	s_addc_u32 s37, s37, 0
	s_mov_b32 m0, s45
	v_lshl_add_u64 v[222:223], s[36:37], 0, v[152:153]
	ds_read_b128 v[176:179], v191 offset:32768
	ds_read_b128 v[180:183], v191 offset:33792
	ds_read_b128 v[192:195], v191 offset:34816
	ds_read_b128 v[196:199], v191 offset:35840
	ds_read_b128 v[200:203], v191 offset:36864
	ds_read_b128 v[204:207], v191 offset:37888
	ds_read_b128 v[208:211], v191 offset:38912
	ds_read_b128 v[212:215], v191 offset:39936
	global_load_lds_dwordx4 v[222:223], off
	v_lshl_add_u64 v[222:223], s[36:37], 0, v[156:157]
	s_mov_b32 m0, s46
	s_nop 0
	global_load_lds_dwordx4 v[222:223], off
	s_waitcnt vmcnt(8)
	s_waitcnt lgkmcnt(0)
	s_barrier
	v_mfma_f32_16x16x32_bf16 v[120:123], v[128:131], v[176:179], v[120:123]
	v_mfma_f32_16x16x32_bf16 v[124:127], v[136:139], v[176:179], v[124:127]
	v_mfma_f32_16x16x32_bf16 v[108:111], v[128:131], v[192:195], v[108:111]
	v_mfma_f32_16x16x32_bf16 v[104:107], v[136:139], v[192:195], v[104:107]
	v_mfma_f32_16x16x32_bf16 v[92:95], v[128:131], v[200:203], v[92:95]
	v_mfma_f32_16x16x32_bf16 v[88:91], v[136:139], v[200:203], v[88:91]
	v_mfma_f32_16x16x32_bf16 v[76:79], v[128:131], v[208:211], v[76:79]
	v_mfma_f32_16x16x32_bf16 v[72:75], v[136:139], v[208:211], v[72:75]
	v_mfma_f32_16x16x32_bf16 v[120:123], v[132:135], v[180:183], v[120:123]
	v_mfma_f32_16x16x32_bf16 v[124:127], v[140:143], v[180:183], v[124:127]
	v_mfma_f32_16x16x32_bf16 v[108:111], v[132:135], v[196:199], v[108:111]
	v_mfma_f32_16x16x32_bf16 v[104:107], v[140:143], v[196:199], v[104:107]
	v_mfma_f32_16x16x32_bf16 v[92:95], v[132:135], v[204:207], v[92:95]
	v_mfma_f32_16x16x32_bf16 v[88:91], v[140:143], v[204:207], v[88:91]
	v_mfma_f32_16x16x32_bf16 v[76:79], v[132:135], v[212:215], v[76:79]
	v_mfma_f32_16x16x32_bf16 v[72:75], v[140:143], v[212:215], v[72:75]
	v_mfma_f32_16x16x32_bf16 v[116:119], v[144:147], v[176:179], v[116:119]
	v_mfma_f32_16x16x32_bf16 v[112:115], v[168:171], v[176:179], v[112:115]
	v_mfma_f32_16x16x32_bf16 v[100:103], v[144:147], v[192:195], v[100:103]
	v_mfma_f32_16x16x32_bf16 v[96:99], v[168:171], v[192:195], v[96:99]
	v_mfma_f32_16x16x32_bf16 v[84:87], v[144:147], v[200:203], v[84:87]
	v_mfma_f32_16x16x32_bf16 v[80:83], v[168:171], v[200:203], v[80:83]
	v_mfma_f32_16x16x32_bf16 v[68:71], v[144:147], v[208:211], v[68:71]
	v_mfma_f32_16x16x32_bf16 v[64:67], v[168:171], v[208:211], v[64:67]
	v_mfma_f32_16x16x32_bf16 v[116:119], v[148:151], v[180:183], v[116:119]
	v_mfma_f32_16x16x32_bf16 v[112:115], v[172:175], v[180:183], v[112:115]
	v_mfma_f32_16x16x32_bf16 v[100:103], v[148:151], v[196:199], v[100:103]
	v_mfma_f32_16x16x32_bf16 v[96:99], v[172:175], v[196:199], v[96:99]
	v_mfma_f32_16x16x32_bf16 v[84:87], v[148:151], v[204:207], v[84:87]
	v_mfma_f32_16x16x32_bf16 v[80:83], v[172:175], v[204:207], v[80:83]
	v_mfma_f32_16x16x32_bf16 v[68:71], v[148:151], v[212:215], v[68:71]
	v_mfma_f32_16x16x32_bf16 v[64:67], v[172:175], v[212:215], v[64:67]
	s_barrier
; #define PG8_STAGE(bufoff, gbase, voff) do { _Pragma("unroll") for (int _i = 0; _i < 2; ++_i) \
;         __builtin_amdgcn_global_load_lds((const unsigned*)((const char*)(gbase) + (voff)[_i]), (LAS unsigned*)(lds + (bufoff) + ldsw + _i * 8192), 16, 0, 0); } while (0)
; #define PG8_LDA(dst, b, h) do { _Pragma("unroll") for (int m = 0; m < 4; ++m) _Pragma("unroll") for (int k = 0; k < 2; ++k) dst[m][k] = *(const LAS bf16x8*)(lds + PG8_SA(b, h) + aoff + m * 2048 + k * 1024); } while (0)
; #define PG8_MMA(ai, bj, At, Bt) do { __builtin_amdgcn_s_setprio(1); _Pragma("unroll") for (int m = 0; m < 4; ++m) _Pragma("unroll") for (int n = 0; n < 2; ++n) _Pragma("unroll") for (int k = 0; k < 2; ++k) \
;         acc[ai][bj][m][n] = __builtin_amdgcn_mfma_f32_16x16x32_bf16(Bt[n][k], At[m][k], acc[ai][bj][m][n], 0, 0, 0); __builtin_amdgcn_s_setprio(0); } while (0)
; #define PG8_WAIT_V(n) asm volatile("s_waitcnt vmcnt(" #n ")" ::: "memory")
; #define PG8_WAIT_L(n) asm volatile("s_waitcnt lgkmcnt(" #n ")" ::: "memory")
; #define PG8_BAR __builtin_amdgcn_s_barrier()
; #define PG8_SCHED __builtin_amdgcn_sched_barrier(0)
; template <class Epi>
; __device__ __forceinline__ void gemm_phase(LAS unsigned char* lds, const int tid, const Gemm g, const StaticOrder& S, const Epi& E) {
;     ...
;             PG8_LDA(At, 1, 1); PG8_STAGE(PG8_SB(1, 0), b3, voffB); PG8_STAGE(PG8_SB(1, 1), b3 + hstepB, voffB); PG8_STAGE(PG8_SA(1, 0), a3, voffA);
;             PG8_WAIT_V(8); PG8_WAIT_L(0); PG8_BAR; PG8_MMA(1, 0, At, B0); PG8_MMA(1, 1, At, B1); PG8_BAR; PG8_SCHED;
	s_add_i32 s36, s61, s42
	v_lshl_add_u64 v[184:185], v[184:185], 0, s[14:15]
	s_mov_b32 m0, s36
	ds_read_b128 v[176:179], v191 offset:49152
	ds_read_b128 v[180:183], v191 offset:50176
	ds_read_b128 v[192:195], v191 offset:51200
	ds_read_b128 v[196:199], v191 offset:52224
	ds_read_b128 v[200:203], v191 offset:53248
	ds_read_b128 v[204:207], v191 offset:54272
	ds_read_b128 v[208:211], v191 offset:55296
	ds_read_b128 v[212:215], v191 offset:56320
	global_load_lds_dwordx4 v[184:185], off
	s_add_i32 m0, s36, 0x2000
	s_add_u32 s34, s34, 0x40080
	v_lshl_add_u64 v[184:185], v[216:217], 0, s[14:15]
	s_addc_u32 s35, s35, 0
	s_add_i32 s36, s62, s42
	global_load_lds_dwordx4 v[184:185], off
	v_lshl_add_u64 v[184:185], s[34:35], 0, v[154:155]
	s_mov_b32 m0, s36
	s_nop 0
	global_load_lds_dwordx4 v[184:185], off
	v_lshl_add_u64 v[184:185], s[34:35], 0, v[158:159]
	s_add_i32 m0, s36, 0x2000
	s_nop 0
	global_load_lds_dwordx4 v[184:185], off
	v_lshl_add_u64 v[184:185], v[218:219], 0, s[14:15]
	s_mov_b32 m0, s49
	s_nop 0
	global_load_lds_dwordx4 v[184:185], off
	v_lshl_add_u64 v[184:185], v[220:221], 0, s[14:15]
	s_mov_b32 m0, s50
	s_nop 0
	global_load_lds_dwordx4 v[184:185], off
	s_waitcnt vmcnt(8)
	s_waitcnt lgkmcnt(0)
	s_barrier
	v_mfma_f32_16x16x32_bf16 v[60:63], v[128:131], v[176:179], v[60:63]
	v_mfma_f32_16x16x32_bf16 v[56:59], v[136:139], v[176:179], v[56:59]
	v_mfma_f32_16x16x32_bf16 v[44:47], v[128:131], v[192:195], v[44:47]
	v_mfma_f32_16x16x32_bf16 v[40:43], v[136:139], v[192:195], v[40:43]
	v_mfma_f32_16x16x32_bf16 v[28:31], v[128:131], v[200:203], v[28:31]
	v_mfma_f32_16x16x32_bf16 v[24:27], v[136:139], v[200:203], v[24:27]
	v_mfma_f32_16x16x32_bf16 v[12:15], v[128:131], v[208:211], v[12:15]
	v_mfma_f32_16x16x32_bf16 v[8:11], v[136:139], v[208:211], v[8:11]
	v_mfma_f32_16x16x32_bf16 v[60:63], v[132:135], v[180:183], v[60:63]
	v_mfma_f32_16x16x32_bf16 v[56:59], v[140:143], v[180:183], v[56:59]
	v_mfma_f32_16x16x32_bf16 v[44:47], v[132:135], v[196:199], v[44:47]
	v_mfma_f32_16x16x32_bf16 v[40:43], v[140:143], v[196:199], v[40:43]
	v_mfma_f32_16x16x32_bf16 v[28:31], v[132:135], v[204:207], v[28:31]
	v_mfma_f32_16x16x32_bf16 v[24:27], v[140:143], v[204:207], v[24:27]
	v_mfma_f32_16x16x32_bf16 v[12:15], v[132:135], v[212:215], v[12:15]
	v_mfma_f32_16x16x32_bf16 v[8:11], v[140:143], v[212:215], v[8:11]
	v_mfma_f32_16x16x32_bf16 v[52:55], v[144:147], v[176:179], v[52:55]
	v_mfma_f32_16x16x32_bf16 v[48:51], v[168:171], v[176:179], v[48:51]
	v_mfma_f32_16x16x32_bf16 v[36:39], v[144:147], v[192:195], v[36:39]
	v_mfma_f32_16x16x32_bf16 v[32:35], v[168:171], v[192:195], v[32:35]
	v_mfma_f32_16x16x32_bf16 v[20:23], v[144:147], v[200:203], v[20:23]
	v_mfma_f32_16x16x32_bf16 v[16:19], v[168:171], v[200:203], v[16:19]
	v_mfma_f32_16x16x32_bf16 v[4:7], v[144:147], v[208:211], v[4:7]
	v_mfma_f32_16x16x32_bf16 v[0:3], v[168:171], v[208:211], v[0:3]
	v_mfma_f32_16x16x32_bf16 v[52:55], v[148:151], v[180:183], v[52:55]
	v_mfma_f32_16x16x32_bf16 v[48:51], v[172:175], v[180:183], v[48:51]
	v_mfma_f32_16x16x32_bf16 v[36:39], v[148:151], v[196:199], v[36:39]
	v_mfma_f32_16x16x32_bf16 v[32:35], v[172:175], v[196:199], v[32:35]
	v_mfma_f32_16x16x32_bf16 v[20:23], v[148:151], v[204:207], v[20:23]
	v_mfma_f32_16x16x32_bf16 v[16:19], v[172:175], v[204:207], v[16:19]
	v_mfma_f32_16x16x32_bf16 v[4:7], v[148:151], v[212:215], v[4:7]
	v_mfma_f32_16x16x32_bf16 v[0:3], v[172:175], v[212:215], v[0:3]
	s_barrier
	s_add_u32 s58, s58, 0x100
	s_addc_u32 s59, s59, 0
	s_add_u32 s30, s30, 0x100
	s_addc_u32 s31, s31, 0
	s_cmp_ge_i32 s60, s48
	s_mov_b32 s34, s60
	s_cbranch_scc0 .LBB0_728

; #define LAS __attribute__((address_space(3)))
; #define PG8_STAGE(bufoff, gbase, voff) do { _Pragma("unroll") for (int _i = 0; _i < 2; ++_i) \
;         __builtin_amdgcn_global_load_lds((const unsigned*)((const char*)(gbase) + (voff)[_i]), (LAS unsigned*)(lds + (bufoff) + ldsw + _i * 8192), 16, 0, 0); } while (0)
; #define PG8_LDA(dst, b, h) do { _Pragma("unroll") for (int m = 0; m < 4; ++m) _Pragma("unroll") for (int k = 0; k < 2; ++k) dst[m][k] = *(const LAS bf16x8*)(lds + PG8_SA(b, h) + aoff + m * 2048 + k * 1024); } while (0)
; #define PG8_LDB(dst, b, h) do { _Pragma("unroll") for (int n = 0; n < 2; ++n) _Pragma("unroll") for (int k = 0; k < 2; ++k) dst[n][k] = *(const LAS bf16x8*)(lds + PG8_SB(b, h) + boff + n * 2048 + k * 1024); } while (0)
; #define PG8_WAIT_V(n) asm volatile("s_waitcnt vmcnt(" #n ")" ::: "memory")
; #define PG8_WAIT_L(n) asm volatile("s_waitcnt lgkmcnt(" #n ")" ::: "memory")
; template <class Epi>
; __device__ __forceinline__ void gemm_phase(LAS unsigned char* lds, const int tid, const Gemm g, const StaticOrder& S, const Epi& E) {
;     ...
;         for (int t = 0; t < nt; t += 2) {
;             const bool last = (t == nt - 2);
;             const char* a1 = cA + (size_t)(t + 1) * kstep;
;             const char* a2 = last ? nA : cA + (size_t)(t + 2) * kstep; const char* b2 = last ? nB : cB + (size_t)(t + 2) * kstep;
;             const char* a3 = a2 + kstep; const char* b3 = b2 + kstep;
;             if constexpr (Epi::SS_LDS) { if (last) {
;                 const char* sp = (const char*)E.ss + (size_t)cur.pm * (256 * 64) + (size_t)tid * 16;
;                 __builtin_amdgcn_global_load_lds((const unsigned*)sp, (LAS unsigned*)(lds + RS_OFF + ldsw), 16, 0, 0);
;                 __builtin_amdgcn_global_load_lds((const unsigned*)(sp + 8192), (LAS unsigned*)(lds + RS_OFF + 8192 + ldsw), 16, 0, 0); } }
;     ...
;             PG8_LDB(B0, 0, 0); PG8_LDB(B1, 0, 1); PG8_SCHED; PG8_LDA(At, 0, 0); PG8_STAGE(PG8_SA(1, 1), a1 + hstepA, voffA);
;             PG8_WAIT_V(8); PG8_WAIT_L(0); PG8_BAR; PG8_MMA(0, 0, At, B0); PG8_MMA(0, 1, At, B1); PG8_BAR; PG8_SCHED;
;             PG8_LDA(At, 0, 1); PG8_STAGE(PG8_SB(0, 0), b2, voffB); PG8_STAGE(PG8_SB(0, 1), b2 + hstepB, voffB); PG8_STAGE(PG8_SA(0, 0), a2, voffA);
;             PG8_WAIT_V(8); PG8_WAIT_L(0); PG8_BAR; PG8_MMA(1, 0, At, B0); PG8_MMA(1, 1, At, B1); PG8_BAR; PG8_SCHED;
.LBB0_906:
	ds_read_b128 v[144:147], v189
	ds_read_b128 v[148:151], v189 offset:1024
	ds_read_b128 v[152:155], v189 offset:2048
	ds_read_b128 v[156:159], v189 offset:3072
	ds_read_b128 v[160:163], v190
	ds_read_b128 v[164:167], v190 offset:1024
	ds_read_b128 v[168:171], v190 offset:2048
	ds_read_b128 v[172:175], v190 offset:3072
	s_add_i32 s58, s28, 2
	s_add_u32 s26, s24, 0x100
	s_addc_u32 s27, s25, 0
	s_cmp_eq_u32 s47, s28
	s_cselect_b32 s28, s22, s56
	s_cselect_b32 s31, s7, s27
	s_cselect_b32 s30, s6, s26
	s_cselect_b32 s29, s23, s57
	v_lshl_add_u64 v[184:185], s[24:25], 0, v[138:139]
	s_add_i32 m0, s39, 0xc000
	ds_read_b128 v[176:179], v191
	ds_read_b128 v[180:183], v191 offset:1024
	ds_read_b128 v[192:195], v191 offset:2048
	ds_read_b128 v[196:199], v191 offset:3072
	ds_read_b128 v[200:203], v191 offset:4096
	ds_read_b128 v[204:207], v191 offset:5120
	ds_read_b128 v[208:211], v191 offset:6144
	ds_read_b128 v[212:215], v191 offset:7168
	global_load_lds_dwordx4 v[184:185], off
	v_lshl_add_u64 v[184:185], s[24:25], 0, v[136:137]
	s_add_i32 m0, s39, 0xe000
	s_nop 0
	global_load_lds_dwordx4 v[184:185], off
	s_waitcnt vmcnt(8)
	s_waitcnt lgkmcnt(0)
	s_barrier
	v_mfma_f32_16x16x32_bf16 v[124:127], v[144:147], v[176:179], v[124:127]
	v_mfma_f32_16x16x32_bf16 v[120:123], v[152:155], v[176:179], v[120:123]
	v_mfma_f32_16x16x32_bf16 v[116:119], v[144:147], v[192:195], v[116:119]
	v_mfma_f32_16x16x32_bf16 v[112:115], v[152:155], v[192:195], v[112:115]
	v_mfma_f32_16x16x32_bf16 v[104:107], v[144:147], v[200:203], v[104:107]
	v_mfma_f32_16x16x32_bf16 v[96:99], v[152:155], v[200:203], v[96:99]
	v_mfma_f32_16x16x32_bf16 v[88:91], v[144:147], v[208:211], v[88:91]
	v_mfma_f32_16x16x32_bf16 v[80:83], v[152:155], v[208:211], v[80:83]
	v_mfma_f32_16x16x32_bf16 v[124:127], v[148:151], v[180:183], v[124:127]
	v_mfma_f32_16x16x32_bf16 v[120:123], v[156:159], v[180:183], v[120:123]
	v_mfma_f32_16x16x32_bf16 v[116:119], v[148:151], v[196:199], v[116:119]
	v_mfma_f32_16x16x32_bf16 v[112:115], v[156:159], v[196:199], v[112:115]
	v_mfma_f32_16x16x32_bf16 v[104:107], v[148:151], v[204:207], v[104:107]
	v_mfma_f32_16x16x32_bf16 v[96:99], v[156:159], v[204:207], v[96:99]
	v_mfma_f32_16x16x32_bf16 v[88:91], v[148:151], v[212:215], v[88:91]
	v_mfma_f32_16x16x32_bf16 v[80:83], v[156:159], v[212:215], v[80:83]
	v_mfma_f32_16x16x32_bf16 v[108:111], v[160:163], v[176:179], v[108:111]
	v_mfma_f32_16x16x32_bf16 v[100:103], v[168:171], v[176:179], v[100:103]
	v_mfma_f32_16x16x32_bf16 v[92:95], v[160:163], v[192:195], v[92:95]
	v_mfma_f32_16x16x32_bf16 v[84:87], v[168:171], v[192:195], v[84:87]
	v_mfma_f32_16x16x32_bf16 v[76:79], v[160:163], v[200:203], v[76:79]
	v_mfma_f32_16x16x32_bf16 v[72:75], v[168:171], v[200:203], v[72:75]
	v_mfma_f32_16x16x32_bf16 v[68:71], v[160:163], v[208:211], v[68:71]
	v_mfma_f32_16x16x32_bf16 v[64:67], v[168:171], v[208:211], v[64:67]
	v_mfma_f32_16x16x32_bf16 v[108:111], v[164:167], v[180:183], v[108:111]
	v_mfma_f32_16x16x32_bf16 v[100:103], v[172:175], v[180:183], v[100:103]
	v_mfma_f32_16x16x32_bf16 v[92:95], v[164:167], v[196:199], v[92:95]
	v_mfma_f32_16x16x32_bf16 v[84:87], v[172:175], v[196:199], v[84:87]
	v_mfma_f32_16x16x32_bf16 v[76:79], v[164:167], v[204:207], v[76:79]
	v_mfma_f32_16x16x32_bf16 v[72:75], v[172:175], v[204:207], v[72:75]
	v_mfma_f32_16x16x32_bf16 v[68:71], v[164:167], v[212:215], v[68:71]
	v_mfma_f32_16x16x32_bf16 v[64:67], v[172:175], v[212:215], v[64:67]
	s_barrier
	s_add_i32 s24, s50, s38
	v_lshl_add_u64 v[184:185], s[28:29], 0, v[130:131]
	s_mov_b32 m0, s24
	ds_read_b128 v[176:179], v191 offset:16384
	ds_read_b128 v[180:183], v191 offset:17408
	ds_read_b128 v[192:195], v191 offset:18432
	ds_read_b128 v[196:199], v191 offset:19456
	ds_read_b128 v[200:203], v191 offset:20480
	ds_read_b128 v[204:207], v191 offset:21504
	ds_read_b128 v[208:211], v191 offset:22528
	ds_read_b128 v[212:215], v191 offset:23552
	global_load_lds_dwordx4 v[184:185], off
	s_add_i32 m0, s24, 0x2000
	s_add_u32 s24, s28, 0xb0000
	v_lshl_add_u64 v[216:217], s[28:29], 0, v[134:135]
	s_addc_u32 s25, s29, 0
	s_add_i32 s59, s51, s38
	global_load_lds_dwordx4 v[216:217], off
	v_lshl_add_u64 v[218:219], s[24:25], 0, v[130:131]
	s_mov_b32 m0, s59
	v_lshl_add_u64 v[220:221], s[30:31], 0, v[132:133]
	global_load_lds_dwordx4 v[218:219], off
	v_lshl_add_u64 v[218:219], s[24:25], 0, v[134:135]
	s_add_i32 m0, s59, 0x2000
	s_nop 0
	global_load_lds_dwordx4 v[218:219], off
	v_lshl_add_u64 v[218:219], s[30:31], 0, v[128:129]
	s_mov_b32 m0, s39
	s_nop 0
	global_load_lds_dwordx4 v[218:219], off
	s_mov_b32 m0, s40
	s_nop 0
	global_load_lds_dwordx4 v[220:221], off
	s_waitcnt vmcnt(8)
	s_waitcnt lgkmcnt(0)
	s_barrier
; #define PG8_STAGE(bufoff, gbase, voff) do { _Pragma("unroll") for (int _i = 0; _i < 2; ++_i) \
;         __builtin_amdgcn_global_load_lds((const unsigned*)((const char*)(gbase) + (voff)[_i]), (LAS unsigned*)(lds + (bufoff) + ldsw + _i * 8192), 16, 0, 0); } while (0)
; #define PG8_LDA(dst, b, h) do { _Pragma("unroll") for (int m = 0; m < 4; ++m) _Pragma("unroll") for (int k = 0; k < 2; ++k) dst[m][k] = *(const LAS bf16x8*)(lds + PG8_SA(b, h) + aoff + m * 2048 + k * 1024); } while (0)
; #define PG8_LDB(dst, b, h) do { _Pragma("unroll") for (int n = 0; n < 2; ++n) _Pragma("unroll") for (int k = 0; k < 2; ++k) dst[n][k] = *(const LAS bf16x8*)(lds + PG8_SB(b, h) + boff + n * 2048 + k * 1024); } while (0)
; #define PG8_MMA(ai, bj, At, Bt) do { __builtin_amdgcn_s_setprio(1); _Pragma("unroll") for (int m = 0; m < 4; ++m) _Pragma("unroll") for (int n = 0; n < 2; ++n) _Pragma("unroll") for (int k = 0; k < 2; ++k) \
;         acc[ai][bj][m][n] = __builtin_amdgcn_mfma_f32_16x16x32_bf16(Bt[n][k], At[m][k], acc[ai][bj][m][n], 0, 0, 0); __builtin_amdgcn_s_setprio(0); } while (0)
; #define PG8_WAIT_V(n) asm volatile("s_waitcnt vmcnt(" #n ")" ::: "memory")
; #define PG8_WAIT_L(n) asm volatile("s_waitcnt lgkmcnt(" #n ")" ::: "memory")
; #define PG8_BAR __builtin_amdgcn_s_barrier()
; #define PG8_SCHED __builtin_amdgcn_sched_barrier(0)
; template <class Epi>
; __device__ __forceinline__ void gemm_phase(LAS unsigned char* lds, const int tid, const Gemm g, const StaticOrder& S, const Epi& E) {
;     ...
;             PG8_WAIT_V(8); PG8_WAIT_L(0); PG8_BAR; PG8_MMA(1, 0, At, B0); PG8_MMA(1, 1, At, B1); PG8_BAR; PG8_SCHED;
;             PG8_LDB(B0, 1, 0); PG8_LDB(B1, 1, 1); PG8_SCHED; PG8_LDA(At, 1, 0); PG8_STAGE(PG8_SA(0, 1), a2 + hstepA, voffA);
;             PG8_WAIT_V(8); PG8_WAIT_L(0); PG8_BAR; PG8_MMA(0, 0, At, B0); PG8_MMA(0, 1, At, B1); PG8_BAR; PG8_SCHED;
	v_mfma_f32_16x16x32_bf16 v[60:63], v[144:147], v[176:179], v[60:63]
	v_mfma_f32_16x16x32_bf16 v[56:59], v[152:155], v[176:179], v[56:59]
	v_mfma_f32_16x16x32_bf16 v[52:55], v[144:147], v[192:195], v[52:55]
	v_mfma_f32_16x16x32_bf16 v[48:51], v[152:155], v[192:195], v[48:51]
	v_mfma_f32_16x16x32_bf16 v[40:43], v[144:147], v[200:203], v[40:43]
	v_mfma_f32_16x16x32_bf16 v[32:35], v[152:155], v[200:203], v[32:35]
	v_mfma_f32_16x16x32_bf16 v[24:27], v[144:147], v[208:211], v[24:27]
	v_mfma_f32_16x16x32_bf16 v[16:19], v[152:155], v[208:211], v[16:19]
	v_mfma_f32_16x16x32_bf16 v[60:63], v[148:151], v[180:183], v[60:63]
	v_mfma_f32_16x16x32_bf16 v[56:59], v[156:159], v[180:183], v[56:59]
	v_mfma_f32_16x16x32_bf16 v[52:55], v[148:151], v[196:199], v[52:55]
	v_mfma_f32_16x16x32_bf16 v[48:51], v[156:159], v[196:199], v[48:51]
	v_mfma_f32_16x16x32_bf16 v[40:43], v[148:151], v[204:207], v[40:43]
	v_mfma_f32_16x16x32_bf16 v[32:35], v[156:159], v[204:207], v[32:35]
	v_mfma_f32_16x16x32_bf16 v[24:27], v[148:151], v[212:215], v[24:27]
	v_mfma_f32_16x16x32_bf16 v[16:19], v[156:159], v[212:215], v[16:19]
	v_mfma_f32_16x16x32_bf16 v[44:47], v[160:163], v[176:179], v[44:47]
	v_mfma_f32_16x16x32_bf16 v[36:39], v[168:171], v[176:179], v[36:39]
	v_mfma_f32_16x16x32_bf16 v[28:31], v[160:163], v[192:195], v[28:31]
	v_mfma_f32_16x16x32_bf16 v[20:23], v[168:171], v[192:195], v[20:23]
	v_mfma_f32_16x16x32_bf16 v[12:15], v[160:163], v[200:203], v[12:15]
	v_mfma_f32_16x16x32_bf16 v[8:11], v[168:171], v[200:203], v[8:11]
	v_mfma_f32_16x16x32_bf16 v[4:7], v[160:163], v[208:211], v[4:7]
	v_mfma_f32_16x16x32_bf16 v[0:3], v[168:171], v[208:211], v[0:3]
	v_mfma_f32_16x16x32_bf16 v[44:47], v[164:167], v[180:183], v[44:47]
	v_mfma_f32_16x16x32_bf16 v[36:39], v[172:175], v[180:183], v[36:39]
	v_mfma_f32_16x16x32_bf16 v[28:31], v[164:167], v[196:199], v[28:31]
	v_mfma_f32_16x16x32_bf16 v[20:23], v[172:175], v[196:199], v[20:23]
	v_mfma_f32_16x16x32_bf16 v[12:15], v[164:167], v[204:207], v[12:15]
	v_mfma_f32_16x16x32_bf16 v[8:11], v[172:175], v[204:207], v[8:11]
	v_mfma_f32_16x16x32_bf16 v[4:7], v[164:167], v[212:215], v[4:7]
	v_mfma_f32_16x16x32_bf16 v[0:3], v[172:175], v[212:215], v[0:3]
	s_barrier
	s_add_i32 s59, 0, 0x18000
	s_add_i32 s60, 0, 0x1c000
	v_add_u32_e32 v156, s59, v187
	v_add_u32_e32 v172, s60, v187
	ds_read_b128 v[144:147], v156
	ds_read_b128 v[148:151], v156 offset:1024
	ds_read_b128 v[152:155], v156 offset:2048
	ds_read_b128 v[156:159], v156 offset:3072
	ds_read_b128 v[160:163], v172
	ds_read_b128 v[164:167], v172 offset:1024
	ds_read_b128 v[168:171], v172 offset:2048
	ds_read_b128 v[172:175], v172 offset:3072
	s_add_u32 s24, s30, 0xb0000
	s_addc_u32 s25, s31, 0
	s_mov_b32 m0, s41
	v_lshl_add_u64 v[222:223], s[24:25], 0, v[128:129]
	ds_read_b128 v[176:179], v191 offset:32768
	ds_read_b128 v[180:183], v191 offset:33792
	ds_read_b128 v[192:195], v191 offset:34816
	ds_read_b128 v[196:199], v191 offset:35840
	ds_read_b128 v[200:203], v191 offset:36864
	ds_read_b128 v[204:207], v191 offset:37888
	ds_read_b128 v[208:211], v191 offset:38912
	ds_read_b128 v[212:215], v191 offset:39936
	global_load_lds_dwordx4 v[222:223], off
	v_lshl_add_u64 v[222:223], s[24:25], 0, v[132:133]
	s_mov_b32 m0, s42
	s_nop 0
	global_load_lds_dwordx4 v[222:223], off
	s_waitcnt vmcnt(8)
	s_waitcnt lgkmcnt(0)
	s_barrier
	v_mfma_f32_16x16x32_bf16 v[124:127], v[144:147], v[176:179], v[124:127]
	v_mfma_f32_16x16x32_bf16 v[120:123], v[152:155], v[176:179], v[120:123]
	v_mfma_f32_16x16x32_bf16 v[116:119], v[144:147], v[192:195], v[116:119]
	v_mfma_f32_16x16x32_bf16 v[112:115], v[152:155], v[192:195], v[112:115]
	v_mfma_f32_16x16x32_bf16 v[104:107], v[144:147], v[200:203], v[104:107]
	v_mfma_f32_16x16x32_bf16 v[96:99], v[152:155], v[200:203], v[96:99]
	v_mfma_f32_16x16x32_bf16 v[88:91], v[144:147], v[208:211], v[88:91]
	v_mfma_f32_16x16x32_bf16 v[80:83], v[152:155], v[208:211], v[80:83]
	v_mfma_f32_16x16x32_bf16 v[124:127], v[148:151], v[180:183], v[124:127]
	v_mfma_f32_16x16x32_bf16 v[120:123], v[156:159], v[180:183], v[120:123]
	v_mfma_f32_16x16x32_bf16 v[116:119], v[148:151], v[196:199], v[116:119]
	v_mfma_f32_16x16x32_bf16 v[112:115], v[156:159], v[196:199], v[112:115]
	v_mfma_f32_16x16x32_bf16 v[104:107], v[148:151], v[204:207], v[104:107]
	v_mfma_f32_16x16x32_bf16 v[96:99], v[156:159], v[204:207], v[96:99]
	v_mfma_f32_16x16x32_bf16 v[88:91], v[148:151], v[212:215], v[88:91]
	v_mfma_f32_16x16x32_bf16 v[80:83], v[156:159], v[212:215], v[80:83]
	v_mfma_f32_16x16x32_bf16 v[108:111], v[160:163], v[176:179], v[108:111]
	v_mfma_f32_16x16x32_bf16 v[100:103], v[168:171], v[176:179], v[100:103]
	v_mfma_f32_16x16x32_bf16 v[92:95], v[160:163], v[192:195], v[92:95]
	v_mfma_f32_16x16x32_bf16 v[84:87], v[168:171], v[192:195], v[84:87]
	v_mfma_f32_16x16x32_bf16 v[76:79], v[160:163], v[200:203], v[76:79]
	v_mfma_f32_16x16x32_bf16 v[72:75], v[168:171], v[200:203], v[72:75]
	v_mfma_f32_16x16x32_bf16 v[68:71], v[160:163], v[208:211], v[68:71]
	v_mfma_f32_16x16x32_bf16 v[64:67], v[168:171], v[208:211], v[64:67]
	v_mfma_f32_16x16x32_bf16 v[108:111], v[164:167], v[180:183], v[108:111]
	v_mfma_f32_16x16x32_bf16 v[100:103], v[172:175], v[180:183], v[100:103]
	v_mfma_f32_16x16x32_bf16 v[92:95], v[164:167], v[196:199], v[92:95]
	v_mfma_f32_16x16x32_bf16 v[84:87], v[172:175], v[196:199], v[84:87]
	v_mfma_f32_16x16x32_bf16 v[76:79], v[164:167], v[204:207], v[76:79]
	v_mfma_f32_16x16x32_bf16 v[72:75], v[172:175], v[204:207], v[72:75]
	v_mfma_f32_16x16x32_bf16 v[68:71], v[164:167], v[212:215], v[68:71]
	v_mfma_f32_16x16x32_bf16 v[64:67], v[172:175], v[212:215], v[64:67]
	s_barrier
; #define PG8_STAGE(bufoff, gbase, voff) do { _Pragma("unroll") for (int _i = 0; _i < 2; ++_i) \
;         __builtin_amdgcn_global_load_lds((const unsigned*)((const char*)(gbase) + (voff)[_i]), (LAS unsigned*)(lds + (bufoff) + ldsw + _i * 8192), 16, 0, 0); } while (0)
; #define PG8_LDA(dst, b, h) do { _Pragma("unroll") for (int m = 0; m < 4; ++m) _Pragma("unroll") for (int k = 0; k < 2; ++k) dst[m][k] = *(const LAS bf16x8*)(lds + PG8_SA(b, h) + aoff + m * 2048 + k * 1024); } while (0)
; #define PG8_MMA(ai, bj, At, Bt) do { __builtin_amdgcn_s_setprio(1); _Pragma("unroll") for (int m = 0; m < 4; ++m) _Pragma("unroll") for (int n = 0; n < 2; ++n) _Pragma("unroll") for (int k = 0; k < 2; ++k) \
;         acc[ai][bj][m][n] = __builtin_amdgcn_mfma_f32_16x16x32_bf16(Bt[n][k], At[m][k], acc[ai][bj][m][n], 0, 0, 0); __builtin_amdgcn_s_setprio(0); } while (0)
; #define PG8_WAIT_V(n) asm volatile("s_waitcnt vmcnt(" #n ")" ::: "memory")
; #define PG8_WAIT_L(n) asm volatile("s_waitcnt lgkmcnt(" #n ")" ::: "memory")
; #define PG8_BAR __builtin_amdgcn_s_barrier()
; #define PG8_SCHED __builtin_amdgcn_sched_barrier(0)
; template <class Epi>
; __device__ __forceinline__ void gemm_phase(LAS unsigned char* lds, const int tid, const Gemm g, const StaticOrder& S, const Epi& E) {
;     ...
;             PG8_LDA(At, 1, 1); PG8_STAGE(PG8_SB(1, 0), b3, voffB); PG8_STAGE(PG8_SB(1, 1), b3 + hstepB, voffB); PG8_STAGE(PG8_SA(1, 0), a3, voffA);
;             PG8_WAIT_V(8); PG8_WAIT_L(0); PG8_BAR; PG8_MMA(1, 0, At, B0); PG8_MMA(1, 1, At, B1); PG8_BAR; PG8_SCHED;
	s_add_i32 s24, s59, s38
	v_lshl_add_u64 v[184:185], v[184:185], 0, s[16:17]
	s_mov_b32 m0, s24
	ds_read_b128 v[176:179], v191 offset:49152
	ds_read_b128 v[180:183], v191 offset:50176
	ds_read_b128 v[192:195], v191 offset:51200
	ds_read_b128 v[196:199], v191 offset:52224
	ds_read_b128 v[200:203], v191 offset:53248
	ds_read_b128 v[204:207], v191 offset:54272
	ds_read_b128 v[208:211], v191 offset:55296
	ds_read_b128 v[212:215], v191 offset:56320
	global_load_lds_dwordx4 v[184:185], off
	s_add_i32 m0, s24, 0x2000
	s_add_u32 s24, s28, 0xb0080
	v_lshl_add_u64 v[184:185], v[216:217], 0, s[16:17]
	s_addc_u32 s25, s29, 0
	s_add_i32 s28, s60, s38
	global_load_lds_dwordx4 v[184:185], off
	v_lshl_add_u64 v[184:185], s[24:25], 0, v[130:131]
	s_mov_b32 m0, s28
	s_nop 0
	global_load_lds_dwordx4 v[184:185], off
	v_lshl_add_u64 v[184:185], s[24:25], 0, v[134:135]
	s_add_i32 m0, s28, 0x2000
	s_nop 0
	global_load_lds_dwordx4 v[184:185], off
	v_lshl_add_u64 v[184:185], v[218:219], 0, s[16:17]
	s_mov_b32 m0, s45
	s_nop 0
	global_load_lds_dwordx4 v[184:185], off
	v_lshl_add_u64 v[184:185], v[220:221], 0, s[16:17]
	s_mov_b32 m0, s46
	s_nop 0
	global_load_lds_dwordx4 v[184:185], off
	s_waitcnt vmcnt(8)
	s_waitcnt lgkmcnt(0)
	s_barrier
	v_mfma_f32_16x16x32_bf16 v[60:63], v[144:147], v[176:179], v[60:63]
	v_mfma_f32_16x16x32_bf16 v[56:59], v[152:155], v[176:179], v[56:59]
	v_mfma_f32_16x16x32_bf16 v[52:55], v[144:147], v[192:195], v[52:55]
	v_mfma_f32_16x16x32_bf16 v[48:51], v[152:155], v[192:195], v[48:51]
	v_mfma_f32_16x16x32_bf16 v[40:43], v[144:147], v[200:203], v[40:43]
	v_mfma_f32_16x16x32_bf16 v[32:35], v[152:155], v[200:203], v[32:35]
	v_mfma_f32_16x16x32_bf16 v[24:27], v[144:147], v[208:211], v[24:27]
	v_mfma_f32_16x16x32_bf16 v[16:19], v[152:155], v[208:211], v[16:19]
	v_mfma_f32_16x16x32_bf16 v[60:63], v[148:151], v[180:183], v[60:63]
	v_mfma_f32_16x16x32_bf16 v[56:59], v[156:159], v[180:183], v[56:59]
	v_mfma_f32_16x16x32_bf16 v[52:55], v[148:151], v[196:199], v[52:55]
	v_mfma_f32_16x16x32_bf16 v[48:51], v[156:159], v[196:199], v[48:51]
	v_mfma_f32_16x16x32_bf16 v[40:43], v[148:151], v[204:207], v[40:43]
	v_mfma_f32_16x16x32_bf16 v[32:35], v[156:159], v[204:207], v[32:35]
	v_mfma_f32_16x16x32_bf16 v[24:27], v[148:151], v[212:215], v[24:27]
	v_mfma_f32_16x16x32_bf16 v[16:19], v[156:159], v[212:215], v[16:19]
	v_mfma_f32_16x16x32_bf16 v[44:47], v[160:163], v[176:179], v[44:47]
	v_mfma_f32_16x16x32_bf16 v[36:39], v[168:171], v[176:179], v[36:39]
	v_mfma_f32_16x16x32_bf16 v[28:31], v[160:163], v[192:195], v[28:31]
	v_mfma_f32_16x16x32_bf16 v[20:23], v[168:171], v[192:195], v[20:23]
	v_mfma_f32_16x16x32_bf16 v[12:15], v[160:163], v[200:203], v[12:15]
	v_mfma_f32_16x16x32_bf16 v[8:11], v[168:171], v[200:203], v[8:11]
	v_mfma_f32_16x16x32_bf16 v[4:7], v[160:163], v[208:211], v[4:7]
	v_mfma_f32_16x16x32_bf16 v[0:3], v[168:171], v[208:211], v[0:3]
	v_mfma_f32_16x16x32_bf16 v[44:47], v[164:167], v[180:183], v[44:47]
	v_mfma_f32_16x16x32_bf16 v[36:39], v[172:175], v[180:183], v[36:39]
	v_mfma_f32_16x16x32_bf16 v[28:31], v[164:167], v[196:199], v[28:31]
	v_mfma_f32_16x16x32_bf16 v[20:23], v[172:175], v[196:199], v[20:23]
	v_mfma_f32_16x16x32_bf16 v[12:15], v[164:167], v[204:207], v[12:15]
	v_mfma_f32_16x16x32_bf16 v[8:11], v[172:175], v[204:207], v[8:11]
	v_mfma_f32_16x16x32_bf16 v[4:7], v[164:167], v[212:215], v[4:7]
	v_mfma_f32_16x16x32_bf16 v[0:3], v[172:175], v[212:215], v[0:3]
	s_barrier
	s_add_u32 s56, s56, 0x100
	s_addc_u32 s57, s57, 0
	s_cmp_ge_i32 s58, s44
	s_mov_b64 s[24:25], s[26:27]
	s_mov_b32 s28, s58
	s_cbranch_scc0 .LBB0_906
;     __device__ __forceinline__ void operator()(const Acc& acc, const Unit& u, int wr, int wc, int fr, int fq) const {
;     ...
;                     const f32x4 h0 = hv[m][bj][0] + acc[ai][bj][m][0] * scale, h1 = hv[m][bj][1] + acc[ai][bj][m][1] * scale;
	v_pk_mul_f32 v[154:155], v[126:127], 0.5 op_sel_hi:[1,0]
	v_pk_mul_f32 v[156:157], v[124:125], 0.5 op_sel_hi:[1,0]
	v_pk_mul_f32 v[158:159], v[122:123], 0.5 op_sel_hi:[1,0]
	v_pk_mul_f32 v[160:161], v[120:121], 0.5 op_sel_hi:[1,0]
	v_pk_mul_f32 v[168:169], v[110:111], 0.5 op_sel_hi:[1,0]
	v_pk_mul_f32 v[166:167], v[108:109], 0.5 op_sel_hi:[1,0]
	v_pk_mul_f32 v[164:165], v[102:103], 0.5 op_sel_hi:[1,0]
	v_pk_mul_f32 v[162:163], v[100:101], 0.5 op_sel_hi:[1,0]
	v_pk_mul_f32 v[152:153], v[118:119], 0.5 op_sel_hi:[1,0]
	v_pk_mul_f32 v[150:151], v[116:117], 0.5 op_sel_hi:[1,0]
	v_pk_mul_f32 v[148:149], v[114:115], 0.5 op_sel_hi:[1,0]
	v_pk_mul_f32 v[146:147], v[112:113], 0.5 op_sel_hi:[1,0]
	v_pk_mul_f32 v[144:145], v[94:95], 0.5 op_sel_hi:[1,0]
	v_pk_mul_f32 v[126:127], v[92:93], 0.5 op_sel_hi:[1,0]
	v_pk_mul_f32 v[124:125], v[86:87], 0.5 op_sel_hi:[1,0]
	v_pk_mul_f32 v[122:123], v[84:85], 0.5 op_sel_hi:[1,0]
	v_pk_mul_f32 v[120:121], v[106:107], 0.5 op_sel_hi:[1,0]
	v_pk_mul_f32 v[118:119], v[104:105], 0.5 op_sel_hi:[1,0]
	v_pk_mul_f32 v[116:117], v[98:99], 0.5 op_sel_hi:[1,0]
	v_pk_mul_f32 v[114:115], v[96:97], 0.5 op_sel_hi:[1,0]
	v_pk_mul_f32 v[112:113], v[78:79], 0.5 op_sel_hi:[1,0]
	v_pk_mul_f32 v[110:111], v[76:77], 0.5 op_sel_hi:[1,0]
	v_pk_mul_f32 v[108:109], v[74:75], 0.5 op_sel_hi:[1,0]
	v_pk_mul_f32 v[106:107], v[72:73], 0.5 op_sel_hi:[1,0]
	v_pk_mul_f32 v[104:105], v[90:91], 0.5 op_sel_hi:[1,0]
	v_pk_mul_f32 v[102:103], v[88:89], 0.5 op_sel_hi:[1,0]
	v_pk_mul_f32 v[100:101], v[82:83], 0.5 op_sel_hi:[1,0]
	v_pk_mul_f32 v[98:99], v[80:81], 0.5 op_sel_hi:[1,0]
	v_pk_mul_f32 v[96:97], v[70:71], 0.5 op_sel_hi:[1,0]
	v_pk_mul_f32 v[94:95], v[68:69], 0.5 op_sel_hi:[1,0]
	v_pk_mul_f32 v[92:93], v[66:67], 0.5 op_sel_hi:[1,0]
	v_pk_mul_f32 v[90:91], v[64:65], 0.5 op_sel_hi:[1,0]
	v_pk_mul_f32 v[72:73], v[62:63], 0.5 op_sel_hi:[1,0]
	v_pk_mul_f32 v[74:75], v[60:61], 0.5 op_sel_hi:[1,0]
	v_pk_mul_f32 v[76:77], v[58:59], 0.5 op_sel_hi:[1,0]
	v_pk_mul_f32 v[78:79], v[56:57], 0.5 op_sel_hi:[1,0]
	v_pk_mul_f32 v[86:87], v[46:47], 0.5 op_sel_hi:[1,0]
	v_pk_mul_f32 v[84:85], v[44:45], 0.5 op_sel_hi:[1,0]
	v_pk_mul_f32 v[82:83], v[38:39], 0.5 op_sel_hi:[1,0]
	v_pk_mul_f32 v[80:81], v[36:37], 0.5 op_sel_hi:[1,0]
	v_pk_mul_f32 v[70:71], v[54:55], 0.5 op_sel_hi:[1,0]
	v_pk_mul_f32 v[68:69], v[52:53], 0.5 op_sel_hi:[1,0]
	v_pk_mul_f32 v[66:67], v[50:51], 0.5 op_sel_hi:[1,0]
	v_pk_mul_f32 v[64:65], v[48:49], 0.5 op_sel_hi:[1,0]
	v_pk_mul_f32 v[62:63], v[30:31], 0.5 op_sel_hi:[1,0]
	v_pk_mul_f32 v[60:61], v[28:29], 0.5 op_sel_hi:[1,0]
	v_pk_mul_f32 v[58:59], v[22:23], 0.5 op_sel_hi:[1,0]
	v_pk_mul_f32 v[56:57], v[20:21], 0.5 op_sel_hi:[1,0]
	v_pk_mul_f32 v[54:55], v[42:43], 0.5 op_sel_hi:[1,0]
	v_pk_mul_f32 v[52:53], v[40:41], 0.5 op_sel_hi:[1,0]
	v_pk_mul_f32 v[50:51], v[34:35], 0.5 op_sel_hi:[1,0]
	v_pk_mul_f32 v[48:49], v[32:33], 0.5 op_sel_hi:[1,0]
	v_pk_mul_f32 v[46:47], v[14:15], 0.5 op_sel_hi:[1,0]
	v_pk_mul_f32 v[44:45], v[12:13], 0.5 op_sel_hi:[1,0]
	v_pk_mul_f32 v[42:43], v[10:11], 0.5 op_sel_hi:[1,0]
	v_pk_mul_f32 v[40:41], v[8:9], 0.5 op_sel_hi:[1,0]
	v_pk_mul_f32 v[38:39], v[26:27], 0.5 op_sel_hi:[1,0]
	v_pk_mul_f32 v[36:37], v[24:25], 0.5 op_sel_hi:[1,0]
	v_pk_mul_f32 v[34:35], v[18:19], 0.5 op_sel_hi:[1,0]
	v_pk_mul_f32 v[32:33], v[16:17], 0.5 op_sel_hi:[1,0]
	v_pk_mul_f32 v[30:31], v[6:7], 0.5 op_sel_hi:[1,0]
	v_pk_mul_f32 v[28:29], v[4:5], 0.5 op_sel_hi:[1,0]
	v_pk_mul_f32 v[26:27], v[2:3], 0.5 op_sel_hi:[1,0]
	v_pk_mul_f32 v[24:25], v[0:1], 0.5 op_sel_hi:[1,0]

; #define LAS __attribute__((address_space(3)))
; #define PG8_STAGE(bufoff, gbase, voff) do { _Pragma("unroll") for (int _i = 0; _i < 2; ++_i) \
;         __builtin_amdgcn_global_load_lds((const unsigned*)((const char*)(gbase) + (voff)[_i]), (LAS unsigned*)(lds + (bufoff) + ldsw + _i * 8192), 16, 0, 0); } while (0)
; #define PG8_LDA(dst, b, h) do { _Pragma("unroll") for (int m = 0; m < 4; ++m) _Pragma("unroll") for (int k = 0; k < 2; ++k) dst[m][k] = *(const LAS bf16x8*)(lds + PG8_SA(b, h) + aoff + m * 2048 + k * 1024); } while (0)
; #define PG8_LDB(dst, b, h) do { _Pragma("unroll") for (int n = 0; n < 2; ++n) _Pragma("unroll") for (int k = 0; k < 2; ++k) dst[n][k] = *(const LAS bf16x8*)(lds + PG8_SB(b, h) + boff + n * 2048 + k * 1024); } while (0)
; #define PG8_WAIT_V(n) asm volatile("s_waitcnt vmcnt(" #n ")" ::: "memory")
; #define PG8_WAIT_L(n) asm volatile("s_waitcnt lgkmcnt(" #n ")" ::: "memory")
; template <class Epi>
; __device__ __forceinline__ void gemm_phase(LAS unsigned char* lds, const int tid, const Gemm g, const StaticOrder& S, const Epi& E) {
;     ...
;         for (int t = 0; t < nt; t += 2) {
;             const bool last = (t == nt - 2);
;             const char* a1 = cA + (size_t)(t + 1) * kstep;
;             const char* a2 = last ? nA : cA + (size_t)(t + 2) * kstep; const char* b2 = last ? nB : cB + (size_t)(t + 2) * kstep;
;             const char* a3 = a2 + kstep; const char* b3 = b2 + kstep;
;             if constexpr (Epi::SS_LDS) { if (last) {
;                 const char* sp = (const char*)E.ss + (size_t)cur.pm * (256 * 64) + (size_t)tid * 16;
;                 __builtin_amdgcn_global_load_lds((const unsigned*)sp, (LAS unsigned*)(lds + RS_OFF + ldsw), 16, 0, 0);
;                 __builtin_amdgcn_global_load_lds((const unsigned*)(sp + 8192), (LAS unsigned*)(lds + RS_OFF + 8192 + ldsw), 16, 0, 0); } }
;     ...
;             PG8_LDB(B0, 0, 0); PG8_LDB(B1, 0, 1); PG8_SCHED; PG8_LDA(At, 0, 0); PG8_STAGE(PG8_SA(1, 1), a1 + hstepA, voffA);
;             PG8_WAIT_V(8); PG8_WAIT_L(0); PG8_BAR; PG8_MMA(0, 0, At, B0); PG8_MMA(0, 1, At, B1); PG8_BAR; PG8_SCHED;
;             PG8_LDA(At, 0, 1); PG8_STAGE(PG8_SB(0, 0), b2, voffB); PG8_STAGE(PG8_SB(0, 1), b2 + hstepB, voffB); PG8_STAGE(PG8_SA(0, 0), a2, voffA);
;             PG8_WAIT_V(8); PG8_WAIT_L(0); PG8_BAR; PG8_MMA(1, 0, At, B0); PG8_MMA(1, 1, At, B1); PG8_BAR; PG8_SCHED;
.LBB0_949:
	ds_read_b128 v[152:155], v148
	ds_read_b128 v[156:159], v148 offset:1024
	ds_read_b128 v[160:163], v148 offset:2048
	ds_read_b128 v[164:167], v148 offset:3072
	ds_read_b128 v[168:171], v149
	ds_read_b128 v[172:175], v149 offset:1024
	ds_read_b128 v[176:179], v149 offset:2048
	ds_read_b128 v[180:183], v149 offset:3072
	s_add_i32 s56, s28, 2
	s_add_u32 s29, s26, 0xffff0080
	s_addc_u32 s30, s27, -1
	s_cmp_eq_u32 s47, s28
	s_cselect_b32 s28, s53, s54
	s_cselect_b32 s31, s19, s30
	s_cselect_b32 s30, s21, s29
	s_cselect_b32 s29, s52, s55
	v_lshl_add_u64 v[216:217], s[26:27], 0, v[140:141]
	s_add_i32 m0, s40, 0xc000
	ds_read_b128 v[184:187], v150
	ds_read_b128 v[188:191], v150 offset:1024
	ds_read_b128 v[192:195], v150 offset:2048
	ds_read_b128 v[196:199], v150 offset:3072
	ds_read_b128 v[200:203], v150 offset:4096
	ds_read_b128 v[204:207], v150 offset:5120
	ds_read_b128 v[208:211], v150 offset:6144
	ds_read_b128 v[212:215], v150 offset:7168
	global_load_lds_dwordx4 v[216:217], off
	v_lshl_add_u64 v[216:217], s[26:27], 0, v[138:139]
	s_add_i32 m0, s40, 0xe000
	s_nop 0
	global_load_lds_dwordx4 v[216:217], off
	s_waitcnt vmcnt(8)
	s_waitcnt lgkmcnt(0)
	s_barrier
	v_mfma_f32_16x16x32_bf16 v[120:123], v[152:155], v[184:187], v[120:123]
	v_mfma_f32_16x16x32_bf16 v[124:127], v[160:163], v[184:187], v[124:127]
	v_mfma_f32_16x16x32_bf16 v[108:111], v[152:155], v[192:195], v[108:111]
	v_mfma_f32_16x16x32_bf16 v[104:107], v[160:163], v[192:195], v[104:107]
	v_mfma_f32_16x16x32_bf16 v[92:95], v[152:155], v[200:203], v[92:95]
	v_mfma_f32_16x16x32_bf16 v[88:91], v[160:163], v[200:203], v[88:91]
	v_mfma_f32_16x16x32_bf16 v[76:79], v[152:155], v[208:211], v[76:79]
	v_mfma_f32_16x16x32_bf16 v[72:75], v[160:163], v[208:211], v[72:75]
	v_mfma_f32_16x16x32_bf16 v[120:123], v[156:159], v[188:191], v[120:123]
	v_mfma_f32_16x16x32_bf16 v[124:127], v[164:167], v[188:191], v[124:127]
	v_mfma_f32_16x16x32_bf16 v[108:111], v[156:159], v[196:199], v[108:111]
	v_mfma_f32_16x16x32_bf16 v[104:107], v[164:167], v[196:199], v[104:107]
	v_mfma_f32_16x16x32_bf16 v[92:95], v[156:159], v[204:207], v[92:95]
	v_mfma_f32_16x16x32_bf16 v[88:91], v[164:167], v[204:207], v[88:91]
	v_mfma_f32_16x16x32_bf16 v[76:79], v[156:159], v[212:215], v[76:79]
	v_mfma_f32_16x16x32_bf16 v[72:75], v[164:167], v[212:215], v[72:75]
	v_mfma_f32_16x16x32_bf16 v[116:119], v[168:171], v[184:187], v[116:119]
	v_mfma_f32_16x16x32_bf16 v[112:115], v[176:179], v[184:187], v[112:115]
	v_mfma_f32_16x16x32_bf16 v[100:103], v[168:171], v[192:195], v[100:103]
	v_mfma_f32_16x16x32_bf16 v[96:99], v[176:179], v[192:195], v[96:99]
	v_mfma_f32_16x16x32_bf16 v[84:87], v[168:171], v[200:203], v[84:87]
	v_mfma_f32_16x16x32_bf16 v[80:83], v[176:179], v[200:203], v[80:83]
	v_mfma_f32_16x16x32_bf16 v[68:71], v[168:171], v[208:211], v[68:71]
	v_mfma_f32_16x16x32_bf16 v[64:67], v[176:179], v[208:211], v[64:67]
	v_mfma_f32_16x16x32_bf16 v[116:119], v[172:175], v[188:191], v[116:119]
	v_mfma_f32_16x16x32_bf16 v[112:115], v[180:183], v[188:191], v[112:115]
	v_mfma_f32_16x16x32_bf16 v[100:103], v[172:175], v[196:199], v[100:103]
	v_mfma_f32_16x16x32_bf16 v[96:99], v[180:183], v[196:199], v[96:99]
	v_mfma_f32_16x16x32_bf16 v[84:87], v[172:175], v[204:207], v[84:87]
	v_mfma_f32_16x16x32_bf16 v[80:83], v[180:183], v[204:207], v[80:83]
	v_mfma_f32_16x16x32_bf16 v[68:71], v[172:175], v[212:215], v[68:71]
	v_mfma_f32_16x16x32_bf16 v[64:67], v[180:183], v[212:215], v[64:67]
	s_barrier
	s_add_i32 s57, s49, s39
	v_lshl_add_u64 v[216:217], s[28:29], 0, v[130:131]
	s_mov_b32 m0, s57
	ds_read_b128 v[184:187], v150 offset:16384
	ds_read_b128 v[188:191], v150 offset:17408
	ds_read_b128 v[192:195], v150 offset:18432
	ds_read_b128 v[196:199], v150 offset:19456
	ds_read_b128 v[200:203], v150 offset:20480
	ds_read_b128 v[204:207], v150 offset:21504
	ds_read_b128 v[208:211], v150 offset:22528
	ds_read_b128 v[212:215], v150 offset:23552
	global_load_lds_dwordx4 v[216:217], off
	s_add_i32 m0, s57, 0x2000
	s_add_u32 s58, s28, 0x10000
	v_lshl_add_u64 v[218:219], s[28:29], 0, v[134:135]
	s_addc_u32 s59, s29, 0
	s_add_i32 s57, s50, s39
	global_load_lds_dwordx4 v[218:219], off
	v_lshl_add_u64 v[220:221], s[58:59], 0, v[130:131]
	s_mov_b32 m0, s57
	v_lshl_add_u64 v[222:223], s[30:31], 0, v[132:133]
	global_load_lds_dwordx4 v[220:221], off
	v_lshl_add_u64 v[220:221], s[58:59], 0, v[134:135]
	s_add_i32 m0, s57, 0x2000
	s_nop 0
	global_load_lds_dwordx4 v[220:221], off
	v_lshl_add_u64 v[220:221], s[30:31], 0, v[128:129]
	s_mov_b32 m0, s40
	s_nop 0
	global_load_lds_dwordx4 v[220:221], off
	s_mov_b32 m0, s41
	s_nop 0
	global_load_lds_dwordx4 v[222:223], off
	s_waitcnt vmcnt(8)
	s_waitcnt lgkmcnt(0)
	s_barrier
; #define PG8_STAGE(bufoff, gbase, voff) do { _Pragma("unroll") for (int _i = 0; _i < 2; ++_i) \
;         __builtin_amdgcn_global_load_lds((const unsigned*)((const char*)(gbase) + (voff)[_i]), (LAS unsigned*)(lds + (bufoff) + ldsw + _i * 8192), 16, 0, 0); } while (0)
; #define PG8_LDA(dst, b, h) do { _Pragma("unroll") for (int m = 0; m < 4; ++m) _Pragma("unroll") for (int k = 0; k < 2; ++k) dst[m][k] = *(const LAS bf16x8*)(lds + PG8_SA(b, h) + aoff + m * 2048 + k * 1024); } while (0)
; #define PG8_LDB(dst, b, h) do { _Pragma("unroll") for (int n = 0; n < 2; ++n) _Pragma("unroll") for (int k = 0; k < 2; ++k) dst[n][k] = *(const LAS bf16x8*)(lds + PG8_SB(b, h) + boff + n * 2048 + k * 1024); } while (0)
; #define PG8_MMA(ai, bj, At, Bt) do { __builtin_amdgcn_s_setprio(1); _Pragma("unroll") for (int m = 0; m < 4; ++m) _Pragma("unroll") for (int n = 0; n < 2; ++n) _Pragma("unroll") for (int k = 0; k < 2; ++k) \
;         acc[ai][bj][m][n] = __builtin_amdgcn_mfma_f32_16x16x32_bf16(Bt[n][k], At[m][k], acc[ai][bj][m][n], 0, 0, 0); __builtin_amdgcn_s_setprio(0); } while (0)
; #define PG8_WAIT_V(n) asm volatile("s_waitcnt vmcnt(" #n ")" ::: "memory")
; #define PG8_WAIT_L(n) asm volatile("s_waitcnt lgkmcnt(" #n ")" ::: "memory")
; #define PG8_BAR __builtin_amdgcn_s_barrier()
; #define PG8_SCHED __builtin_amdgcn_sched_barrier(0)
; template <class Epi>
; __device__ __forceinline__ void gemm_phase(LAS unsigned char* lds, const int tid, const Gemm g, const StaticOrder& S, const Epi& E) {
;     ...
;             PG8_WAIT_V(8); PG8_WAIT_L(0); PG8_BAR; PG8_MMA(1, 0, At, B0); PG8_MMA(1, 1, At, B1); PG8_BAR; PG8_SCHED;
;             PG8_LDB(B0, 1, 0); PG8_LDB(B1, 1, 1); PG8_SCHED; PG8_LDA(At, 1, 0); PG8_STAGE(PG8_SA(0, 1), a2 + hstepA, voffA);
;             PG8_WAIT_V(8); PG8_WAIT_L(0); PG8_BAR; PG8_MMA(0, 0, At, B0); PG8_MMA(0, 1, At, B1); PG8_BAR; PG8_SCHED;
	v_mfma_f32_16x16x32_bf16 v[60:63], v[152:155], v[184:187], v[60:63]
	v_mfma_f32_16x16x32_bf16 v[56:59], v[160:163], v[184:187], v[56:59]
	v_mfma_f32_16x16x32_bf16 v[44:47], v[152:155], v[192:195], v[44:47]
	v_mfma_f32_16x16x32_bf16 v[40:43], v[160:163], v[192:195], v[40:43]
	v_mfma_f32_16x16x32_bf16 v[28:31], v[152:155], v[200:203], v[28:31]
	v_mfma_f32_16x16x32_bf16 v[24:27], v[160:163], v[200:203], v[24:27]
	v_mfma_f32_16x16x32_bf16 v[12:15], v[152:155], v[208:211], v[12:15]
	v_mfma_f32_16x16x32_bf16 v[8:11], v[160:163], v[208:211], v[8:11]
	v_mfma_f32_16x16x32_bf16 v[60:63], v[156:159], v[188:191], v[60:63]
	v_mfma_f32_16x16x32_bf16 v[56:59], v[164:167], v[188:191], v[56:59]
	v_mfma_f32_16x16x32_bf16 v[44:47], v[156:159], v[196:199], v[44:47]
	v_mfma_f32_16x16x32_bf16 v[40:43], v[164:167], v[196:199], v[40:43]
	v_mfma_f32_16x16x32_bf16 v[28:31], v[156:159], v[204:207], v[28:31]
	v_mfma_f32_16x16x32_bf16 v[24:27], v[164:167], v[204:207], v[24:27]
	v_mfma_f32_16x16x32_bf16 v[12:15], v[156:159], v[212:215], v[12:15]
	v_mfma_f32_16x16x32_bf16 v[8:11], v[164:167], v[212:215], v[8:11]
	v_mfma_f32_16x16x32_bf16 v[52:55], v[168:171], v[184:187], v[52:55]
	v_mfma_f32_16x16x32_bf16 v[48:51], v[176:179], v[184:187], v[48:51]
	v_mfma_f32_16x16x32_bf16 v[36:39], v[168:171], v[192:195], v[36:39]
	v_mfma_f32_16x16x32_bf16 v[32:35], v[176:179], v[192:195], v[32:35]
	v_mfma_f32_16x16x32_bf16 v[20:23], v[168:171], v[200:203], v[20:23]
	v_mfma_f32_16x16x32_bf16 v[16:19], v[176:179], v[200:203], v[16:19]
	v_mfma_f32_16x16x32_bf16 v[4:7], v[168:171], v[208:211], v[4:7]
	v_mfma_f32_16x16x32_bf16 v[0:3], v[176:179], v[208:211], v[0:3]
	v_mfma_f32_16x16x32_bf16 v[52:55], v[172:175], v[188:191], v[52:55]
	v_mfma_f32_16x16x32_bf16 v[48:51], v[180:183], v[188:191], v[48:51]
	v_mfma_f32_16x16x32_bf16 v[36:39], v[172:175], v[196:199], v[36:39]
	v_mfma_f32_16x16x32_bf16 v[32:35], v[180:183], v[196:199], v[32:35]
	v_mfma_f32_16x16x32_bf16 v[20:23], v[172:175], v[204:207], v[20:23]
	v_mfma_f32_16x16x32_bf16 v[16:19], v[180:183], v[204:207], v[16:19]
	v_mfma_f32_16x16x32_bf16 v[4:7], v[172:175], v[212:215], v[4:7]
	v_mfma_f32_16x16x32_bf16 v[0:3], v[180:183], v[212:215], v[0:3]
	s_barrier
	s_add_i32 s57, 0, 0x18000
	v_add_u32_e32 v151, s57, v147
	s_add_i32 s58, 0, 0x1c000
	ds_read_b128 v[152:155], v151
	ds_read_b128 v[156:159], v151 offset:1024
	ds_read_b128 v[160:163], v151 offset:2048
	ds_read_b128 v[164:167], v151 offset:3072
	v_add_u32_e32 v151, s58, v147
	ds_read_b128 v[168:171], v151
	ds_read_b128 v[172:175], v151 offset:1024
	ds_read_b128 v[176:179], v151 offset:2048
	ds_read_b128 v[180:183], v151 offset:3072
	s_add_u32 s30, s30, 0x10000
	s_addc_u32 s31, s31, 0
	s_mov_b32 m0, s42
	v_lshl_add_u64 v[224:225], s[30:31], 0, v[128:129]
	ds_read_b128 v[184:187], v150 offset:32768
	ds_read_b128 v[188:191], v150 offset:33792
	ds_read_b128 v[192:195], v150 offset:34816
	ds_read_b128 v[196:199], v150 offset:35840
	ds_read_b128 v[200:203], v150 offset:36864
	ds_read_b128 v[204:207], v150 offset:37888
	ds_read_b128 v[208:211], v150 offset:38912
	ds_read_b128 v[212:215], v150 offset:39936
	global_load_lds_dwordx4 v[224:225], off
	v_lshl_add_u64 v[224:225], s[30:31], 0, v[132:133]
	s_mov_b32 m0, s43
	s_nop 0
	global_load_lds_dwordx4 v[224:225], off
	s_waitcnt vmcnt(8)
	s_waitcnt lgkmcnt(0)
	s_barrier
	v_mfma_f32_16x16x32_bf16 v[120:123], v[152:155], v[184:187], v[120:123]
	v_mfma_f32_16x16x32_bf16 v[124:127], v[160:163], v[184:187], v[124:127]
	v_mfma_f32_16x16x32_bf16 v[108:111], v[152:155], v[192:195], v[108:111]
	v_mfma_f32_16x16x32_bf16 v[104:107], v[160:163], v[192:195], v[104:107]
	v_mfma_f32_16x16x32_bf16 v[92:95], v[152:155], v[200:203], v[92:95]
	v_mfma_f32_16x16x32_bf16 v[88:91], v[160:163], v[200:203], v[88:91]
	v_mfma_f32_16x16x32_bf16 v[76:79], v[152:155], v[208:211], v[76:79]
	v_mfma_f32_16x16x32_bf16 v[72:75], v[160:163], v[208:211], v[72:75]
	v_mfma_f32_16x16x32_bf16 v[120:123], v[156:159], v[188:191], v[120:123]
	v_mfma_f32_16x16x32_bf16 v[124:127], v[164:167], v[188:191], v[124:127]
	v_mfma_f32_16x16x32_bf16 v[108:111], v[156:159], v[196:199], v[108:111]
	v_mfma_f32_16x16x32_bf16 v[104:107], v[164:167], v[196:199], v[104:107]
	v_mfma_f32_16x16x32_bf16 v[92:95], v[156:159], v[204:207], v[92:95]
	v_mfma_f32_16x16x32_bf16 v[88:91], v[164:167], v[204:207], v[88:91]
	v_mfma_f32_16x16x32_bf16 v[76:79], v[156:159], v[212:215], v[76:79]
	v_mfma_f32_16x16x32_bf16 v[72:75], v[164:167], v[212:215], v[72:75]
	v_mfma_f32_16x16x32_bf16 v[116:119], v[168:171], v[184:187], v[116:119]
	v_mfma_f32_16x16x32_bf16 v[112:115], v[176:179], v[184:187], v[112:115]
	v_mfma_f32_16x16x32_bf16 v[100:103], v[168:171], v[192:195], v[100:103]
	v_mfma_f32_16x16x32_bf16 v[96:99], v[176:179], v[192:195], v[96:99]
	v_mfma_f32_16x16x32_bf16 v[84:87], v[168:171], v[200:203], v[84:87]
	v_mfma_f32_16x16x32_bf16 v[80:83], v[176:179], v[200:203], v[80:83]
	v_mfma_f32_16x16x32_bf16 v[68:71], v[168:171], v[208:211], v[68:71]
	v_mfma_f32_16x16x32_bf16 v[64:67], v[176:179], v[208:211], v[64:67]
	v_mfma_f32_16x16x32_bf16 v[116:119], v[172:175], v[188:191], v[116:119]
	v_mfma_f32_16x16x32_bf16 v[112:115], v[180:183], v[188:191], v[112:115]
	v_mfma_f32_16x16x32_bf16 v[100:103], v[172:175], v[196:199], v[100:103]
	v_mfma_f32_16x16x32_bf16 v[96:99], v[180:183], v[196:199], v[96:99]
	v_mfma_f32_16x16x32_bf16 v[84:87], v[172:175], v[204:207], v[84:87]
	v_mfma_f32_16x16x32_bf16 v[80:83], v[180:183], v[204:207], v[80:83]
	v_mfma_f32_16x16x32_bf16 v[68:71], v[172:175], v[212:215], v[68:71]
	v_mfma_f32_16x16x32_bf16 v[64:67], v[180:183], v[212:215], v[64:67]
	s_barrier
; #define PG8_STAGE(bufoff, gbase, voff) do { _Pragma("unroll") for (int _i = 0; _i < 2; ++_i) \
;         __builtin_amdgcn_global_load_lds((const unsigned*)((const char*)(gbase) + (voff)[_i]), (LAS unsigned*)(lds + (bufoff) + ldsw + _i * 8192), 16, 0, 0); } while (0)
; #define PG8_LDA(dst, b, h) do { _Pragma("unroll") for (int m = 0; m < 4; ++m) _Pragma("unroll") for (int k = 0; k < 2; ++k) dst[m][k] = *(const LAS bf16x8*)(lds + PG8_SA(b, h) + aoff + m * 2048 + k * 1024); } while (0)
; #define PG8_MMA(ai, bj, At, Bt) do { __builtin_amdgcn_s_setprio(1); _Pragma("unroll") for (int m = 0; m < 4; ++m) _Pragma("unroll") for (int n = 0; n < 2; ++n) _Pragma("unroll") for (int k = 0; k < 2; ++k) \
;         acc[ai][bj][m][n] = __builtin_amdgcn_mfma_f32_16x16x32_bf16(Bt[n][k], At[m][k], acc[ai][bj][m][n], 0, 0, 0); __builtin_amdgcn_s_setprio(0); } while (0)
; #define PG8_WAIT_V(n) asm volatile("s_waitcnt vmcnt(" #n ")" ::: "memory")
; #define PG8_WAIT_L(n) asm volatile("s_waitcnt lgkmcnt(" #n ")" ::: "memory")
; #define PG8_BAR __builtin_amdgcn_s_barrier()
; #define PG8_SCHED __builtin_amdgcn_sched_barrier(0)
; template <class Epi>
; __device__ __forceinline__ void gemm_phase(LAS unsigned char* lds, const int tid, const Gemm g, const StaticOrder& S, const Epi& E) {
;     ...
;             PG8_LDA(At, 1, 1); PG8_STAGE(PG8_SB(1, 0), b3, voffB); PG8_STAGE(PG8_SB(1, 1), b3 + hstepB, voffB); PG8_STAGE(PG8_SA(1, 0), a3, voffA);
;             PG8_WAIT_V(8); PG8_WAIT_L(0); PG8_BAR; PG8_MMA(1, 0, At, B0); PG8_MMA(1, 1, At, B1); PG8_BAR; PG8_SCHED;
	s_add_i32 s30, s57, s39
	v_lshl_add_u64 v[216:217], v[216:217], 0, s[10:11]
	s_mov_b32 m0, s30
	ds_read_b128 v[184:187], v150 offset:49152
	ds_read_b128 v[188:191], v150 offset:50176
	ds_read_b128 v[192:195], v150 offset:51200
	ds_read_b128 v[196:199], v150 offset:52224
	ds_read_b128 v[200:203], v150 offset:53248
	ds_read_b128 v[204:207], v150 offset:54272
	ds_read_b128 v[208:211], v150 offset:55296
	ds_read_b128 v[212:215], v150 offset:56320
	global_load_lds_dwordx4 v[216:217], off
	s_add_i32 m0, s30, 0x2000
	s_add_u32 s28, s28, 0x10080
	v_lshl_add_u64 v[216:217], v[218:219], 0, s[10:11]
	s_addc_u32 s29, s29, 0
	s_add_i32 s30, s58, s39
	global_load_lds_dwordx4 v[216:217], off
	v_lshl_add_u64 v[216:217], s[28:29], 0, v[130:131]
	s_mov_b32 m0, s30
	s_nop 0
	global_load_lds_dwordx4 v[216:217], off
	v_lshl_add_u64 v[216:217], s[28:29], 0, v[134:135]
	s_add_i32 m0, s30, 0x2000
	s_nop 0
	global_load_lds_dwordx4 v[216:217], off
	v_lshl_add_u64 v[216:217], v[220:221], 0, s[10:11]
	s_mov_b32 m0, s45
	s_nop 0
	global_load_lds_dwordx4 v[216:217], off
	v_lshl_add_u64 v[216:217], v[222:223], 0, s[10:11]
	s_mov_b32 m0, s46
	s_nop 0
	global_load_lds_dwordx4 v[216:217], off
	s_waitcnt vmcnt(8)
	s_waitcnt lgkmcnt(0)
	s_barrier
	v_mfma_f32_16x16x32_bf16 v[60:63], v[152:155], v[184:187], v[60:63]
	v_mfma_f32_16x16x32_bf16 v[56:59], v[160:163], v[184:187], v[56:59]
	v_mfma_f32_16x16x32_bf16 v[44:47], v[152:155], v[192:195], v[44:47]
	v_mfma_f32_16x16x32_bf16 v[40:43], v[160:163], v[192:195], v[40:43]
	v_mfma_f32_16x16x32_bf16 v[28:31], v[152:155], v[200:203], v[28:31]
	v_mfma_f32_16x16x32_bf16 v[24:27], v[160:163], v[200:203], v[24:27]
	v_mfma_f32_16x16x32_bf16 v[12:15], v[152:155], v[208:211], v[12:15]
	v_mfma_f32_16x16x32_bf16 v[8:11], v[160:163], v[208:211], v[8:11]
	v_mfma_f32_16x16x32_bf16 v[60:63], v[156:159], v[188:191], v[60:63]
	v_mfma_f32_16x16x32_bf16 v[56:59], v[164:167], v[188:191], v[56:59]
	v_mfma_f32_16x16x32_bf16 v[44:47], v[156:159], v[196:199], v[44:47]
	v_mfma_f32_16x16x32_bf16 v[40:43], v[164:167], v[196:199], v[40:43]
	v_mfma_f32_16x16x32_bf16 v[28:31], v[156:159], v[204:207], v[28:31]
	v_mfma_f32_16x16x32_bf16 v[24:27], v[164:167], v[204:207], v[24:27]
	v_mfma_f32_16x16x32_bf16 v[12:15], v[156:159], v[212:215], v[12:15]
	v_mfma_f32_16x16x32_bf16 v[8:11], v[164:167], v[212:215], v[8:11]
	v_mfma_f32_16x16x32_bf16 v[52:55], v[168:171], v[184:187], v[52:55]
	v_mfma_f32_16x16x32_bf16 v[48:51], v[176:179], v[184:187], v[48:51]
	v_mfma_f32_16x16x32_bf16 v[36:39], v[168:171], v[192:195], v[36:39]
	v_mfma_f32_16x16x32_bf16 v[32:35], v[176:179], v[192:195], v[32:35]
	v_mfma_f32_16x16x32_bf16 v[20:23], v[168:171], v[200:203], v[20:23]
	v_mfma_f32_16x16x32_bf16 v[16:19], v[176:179], v[200:203], v[16:19]
	v_mfma_f32_16x16x32_bf16 v[4:7], v[168:171], v[208:211], v[4:7]
	v_mfma_f32_16x16x32_bf16 v[0:3], v[176:179], v[208:211], v[0:3]
	v_mfma_f32_16x16x32_bf16 v[52:55], v[172:175], v[188:191], v[52:55]
	v_mfma_f32_16x16x32_bf16 v[48:51], v[180:183], v[188:191], v[48:51]
	v_mfma_f32_16x16x32_bf16 v[36:39], v[172:175], v[196:199], v[36:39]
	v_mfma_f32_16x16x32_bf16 v[32:35], v[180:183], v[196:199], v[32:35]
	v_mfma_f32_16x16x32_bf16 v[20:23], v[172:175], v[204:207], v[20:23]
	v_mfma_f32_16x16x32_bf16 v[16:19], v[180:183], v[204:207], v[16:19]
	v_mfma_f32_16x16x32_bf16 v[4:7], v[172:175], v[212:215], v[4:7]
	v_mfma_f32_16x16x32_bf16 v[0:3], v[180:183], v[212:215], v[0:3]
	s_barrier
	s_add_u32 s54, s54, 0x100
	s_addc_u32 s55, s55, 0
	s_add_u32 s26, s26, 0x100
	s_addc_u32 s27, s27, 0
	s_cmp_ge_i32 s56, s44
	s_mov_b32 s28, s56
	s_cbranch_scc0 .LBB0_949

; #define LAS __attribute__((address_space(3)))
; #define PG8_STAGE(bufoff, gbase, voff) do { _Pragma("unroll") for (int _i = 0; _i < 2; ++_i) \
;         __builtin_amdgcn_global_load_lds((const unsigned*)((const char*)(gbase) + (voff)[_i]), (LAS unsigned*)(lds + (bufoff) + ldsw + _i * 8192), 16, 0, 0); } while (0)
; #define PG8_LDA(dst, b, h) do { _Pragma("unroll") for (int m = 0; m < 4; ++m) _Pragma("unroll") for (int k = 0; k < 2; ++k) dst[m][k] = *(const LAS bf16x8*)(lds + PG8_SA(b, h) + aoff + m * 2048 + k * 1024); } while (0)
; #define PG8_LDB(dst, b, h) do { _Pragma("unroll") for (int n = 0; n < 2; ++n) _Pragma("unroll") for (int k = 0; k < 2; ++k) dst[n][k] = *(const LAS bf16x8*)(lds + PG8_SB(b, h) + boff + n * 2048 + k * 1024); } while (0)
; #define PG8_WAIT_V(n) asm volatile("s_waitcnt vmcnt(" #n ")" ::: "memory")
; #define PG8_WAIT_L(n) asm volatile("s_waitcnt lgkmcnt(" #n ")" ::: "memory")
; template <class Epi>
; __device__ __forceinline__ void gemm_phase(LAS unsigned char* lds, const int tid, const Gemm g, const StaticOrder& S, const Epi& E) {
;     ...
;         for (int t = 0; t < nt; t += 2) {
;             const bool last = (t == nt - 2);
;             const char* a1 = cA + (size_t)(t + 1) * kstep;
;             const char* a2 = last ? nA : cA + (size_t)(t + 2) * kstep; const char* b2 = last ? nB : cB + (size_t)(t + 2) * kstep;
;             const char* a3 = a2 + kstep; const char* b3 = b2 + kstep;
;             if constexpr (Epi::SS_LDS) { if (last) {
;                 const char* sp = (const char*)E.ss + (size_t)cur.pm * (256 * 64) + (size_t)tid * 16;
;                 __builtin_amdgcn_global_load_lds((const unsigned*)sp, (LAS unsigned*)(lds + RS_OFF + ldsw), 16, 0, 0);
;                 __builtin_amdgcn_global_load_lds((const unsigned*)(sp + 8192), (LAS unsigned*)(lds + RS_OFF + 8192 + ldsw), 16, 0, 0); } }
;     ...
;             PG8_LDB(B0, 0, 0); PG8_LDB(B1, 0, 1); PG8_SCHED; PG8_LDA(At, 0, 0); PG8_STAGE(PG8_SA(1, 1), a1 + hstepA, voffA);
;             PG8_WAIT_V(8); PG8_WAIT_L(0); PG8_BAR; PG8_MMA(0, 0, At, B0); PG8_MMA(0, 1, At, B1); PG8_BAR; PG8_SCHED;
;             PG8_LDA(At, 0, 1); PG8_STAGE(PG8_SB(0, 0), b2, voffB); PG8_STAGE(PG8_SB(0, 1), b2 + hstepB, voffB); PG8_STAGE(PG8_SA(0, 0), a2, voffA);
;             PG8_WAIT_V(8); PG8_WAIT_L(0); PG8_BAR; PG8_MMA(1, 0, At, B0); PG8_MMA(1, 1, At, B1); PG8_BAR; PG8_SCHED;
.LBB0_1032:
	v_add_u32_e32 v144, s59, v209
	v_add_u32_e32 v160, s60, v209
	ds_read_b128 v[132:135], v144
	ds_read_b128 v[136:139], v144 offset:1024
	ds_read_b128 v[140:143], v144 offset:2048
	ds_read_b128 v[144:147], v144 offset:3072
	ds_read_b128 v[148:151], v160
	ds_read_b128 v[152:155], v160 offset:1024
	ds_read_b128 v[156:159], v160 offset:2048
	ds_read_b128 v[160:163], v160 offset:3072
	s_add_i32 s64, s64, 2
	s_add_u32 s42, s38, 0xfffc0080
	s_addc_u32 s43, s39, -1
	s_and_b64 s[40:41], s[40:41], exec
	s_cselect_b32 s43, s27, s43
	s_cselect_b32 s42, s29, s42
	s_cselect_b32 s41, s33, s63
	s_cselect_b32 s40, s62, s37
	v_lshl_add_u64 v[206:207], s[38:39], 0, v[192:193]
	s_add_i32 m0, s48, 0xc000
	ds_read_b128 v[164:167], v211
	ds_read_b128 v[168:171], v211 offset:1024
	ds_read_b128 v[172:175], v211 offset:2048
	ds_read_b128 v[176:179], v211 offset:3072
	ds_read_b128 v[198:201], v211 offset:4096
	ds_read_b128 v[202:205], v211 offset:5120
	ds_read_b128 v[214:217], v211 offset:6144
	ds_read_b128 v[218:221], v211 offset:7168
	global_load_lds_dwordx4 v[206:207], off
	v_lshl_add_u64 v[206:207], s[38:39], 0, v[190:191]
	s_add_i32 m0, s48, 0xe000
	s_nop 0
	global_load_lds_dwordx4 v[206:207], off
	s_waitcnt vmcnt(8)
	s_waitcnt lgkmcnt(0)
	s_barrier
	v_mfma_f32_16x16x32_bf16 v[124:127], v[132:135], v[164:167], v[124:127]
	v_mfma_f32_16x16x32_bf16 v[120:123], v[140:143], v[164:167], v[120:123]
	v_mfma_f32_16x16x32_bf16 v[108:111], v[132:135], v[172:175], v[108:111]
	v_mfma_f32_16x16x32_bf16 v[104:107], v[140:143], v[172:175], v[104:107]
	v_mfma_f32_16x16x32_bf16 v[92:95], v[132:135], v[198:201], v[92:95]
	v_mfma_f32_16x16x32_bf16 v[88:91], v[140:143], v[198:201], v[88:91]
	v_mfma_f32_16x16x32_bf16 v[76:79], v[132:135], v[214:217], v[76:79]
	v_mfma_f32_16x16x32_bf16 v[72:75], v[140:143], v[214:217], v[72:75]
	v_mfma_f32_16x16x32_bf16 v[124:127], v[136:139], v[168:171], v[124:127]
	v_mfma_f32_16x16x32_bf16 v[120:123], v[144:147], v[168:171], v[120:123]
	v_mfma_f32_16x16x32_bf16 v[108:111], v[136:139], v[176:179], v[108:111]
	v_mfma_f32_16x16x32_bf16 v[104:107], v[144:147], v[176:179], v[104:107]
	v_mfma_f32_16x16x32_bf16 v[92:95], v[136:139], v[202:205], v[92:95]
	v_mfma_f32_16x16x32_bf16 v[88:91], v[144:147], v[202:205], v[88:91]
	v_mfma_f32_16x16x32_bf16 v[76:79], v[136:139], v[218:221], v[76:79]
	v_mfma_f32_16x16x32_bf16 v[72:75], v[144:147], v[218:221], v[72:75]
	v_mfma_f32_16x16x32_bf16 v[116:119], v[148:151], v[164:167], v[116:119]
	v_mfma_f32_16x16x32_bf16 v[112:115], v[156:159], v[164:167], v[112:115]
	v_mfma_f32_16x16x32_bf16 v[100:103], v[148:151], v[172:175], v[100:103]
	v_mfma_f32_16x16x32_bf16 v[96:99], v[156:159], v[172:175], v[96:99]
	v_mfma_f32_16x16x32_bf16 v[84:87], v[148:151], v[198:201], v[84:87]
	v_mfma_f32_16x16x32_bf16 v[80:83], v[156:159], v[198:201], v[80:83]
	v_mfma_f32_16x16x32_bf16 v[68:71], v[148:151], v[214:217], v[68:71]
	v_mfma_f32_16x16x32_bf16 v[64:67], v[156:159], v[214:217], v[64:67]
	v_mfma_f32_16x16x32_bf16 v[116:119], v[152:155], v[168:171], v[116:119]
	v_mfma_f32_16x16x32_bf16 v[112:115], v[160:163], v[168:171], v[112:115]
	v_mfma_f32_16x16x32_bf16 v[100:103], v[152:155], v[176:179], v[100:103]
	v_mfma_f32_16x16x32_bf16 v[96:99], v[160:163], v[176:179], v[96:99]
	v_mfma_f32_16x16x32_bf16 v[84:87], v[152:155], v[202:205], v[84:87]
	v_mfma_f32_16x16x32_bf16 v[80:83], v[160:163], v[202:205], v[80:83]
	v_mfma_f32_16x16x32_bf16 v[68:71], v[152:155], v[218:221], v[68:71]
	v_mfma_f32_16x16x32_bf16 v[64:67], v[160:163], v[218:221], v[64:67]
	s_barrier
	s_add_i32 s65, s59, s47
	v_lshl_add_u64 v[206:207], s[40:41], 0, v[182:183]
	s_mov_b32 m0, s65
	ds_read_b128 v[164:167], v211 offset:16384
	ds_read_b128 v[168:171], v211 offset:17408
	ds_read_b128 v[172:175], v211 offset:18432
	ds_read_b128 v[176:179], v211 offset:19456
	ds_read_b128 v[198:201], v211 offset:20480
	ds_read_b128 v[202:205], v211 offset:21504
	ds_read_b128 v[214:217], v211 offset:22528
	ds_read_b128 v[218:221], v211 offset:23552
	global_load_lds_dwordx4 v[206:207], off
	s_add_i32 m0, s65, 0x2000
	s_add_u32 s66, s40, 0x40000
	v_lshl_add_u64 v[222:223], s[40:41], 0, v[186:187]
	s_addc_u32 s67, s41, 0
	s_add_i32 s65, s60, s47
	global_load_lds_dwordx4 v[222:223], off
	v_lshl_add_u64 v[224:225], s[66:67], 0, v[182:183]
	s_mov_b32 m0, s65
	v_lshl_add_u64 v[226:227], s[42:43], 0, v[184:185]
	global_load_lds_dwordx4 v[224:225], off
	v_lshl_add_u64 v[224:225], s[66:67], 0, v[186:187]
	s_add_i32 m0, s65, 0x2000
	s_nop 0
	global_load_lds_dwordx4 v[224:225], off
	v_lshl_add_u64 v[224:225], s[42:43], 0, v[180:181]
	s_mov_b32 m0, s48
	s_nop 0
	global_load_lds_dwordx4 v[224:225], off
	s_mov_b32 m0, s49
	s_nop 0
	global_load_lds_dwordx4 v[226:227], off
	s_waitcnt vmcnt(8)
	s_waitcnt lgkmcnt(0)
	s_barrier
; #define PG8_STAGE(bufoff, gbase, voff) do { _Pragma("unroll") for (int _i = 0; _i < 2; ++_i) \
;         __builtin_amdgcn_global_load_lds((const unsigned*)((const char*)(gbase) + (voff)[_i]), (LAS unsigned*)(lds + (bufoff) + ldsw + _i * 8192), 16, 0, 0); } while (0)
; #define PG8_LDA(dst, b, h) do { _Pragma("unroll") for (int m = 0; m < 4; ++m) _Pragma("unroll") for (int k = 0; k < 2; ++k) dst[m][k] = *(const LAS bf16x8*)(lds + PG8_SA(b, h) + aoff + m * 2048 + k * 1024); } while (0)
; #define PG8_LDB(dst, b, h) do { _Pragma("unroll") for (int n = 0; n < 2; ++n) _Pragma("unroll") for (int k = 0; k < 2; ++k) dst[n][k] = *(const LAS bf16x8*)(lds + PG8_SB(b, h) + boff + n * 2048 + k * 1024); } while (0)
; #define PG8_MMA(ai, bj, At, Bt) do { __builtin_amdgcn_s_setprio(1); _Pragma("unroll") for (int m = 0; m < 4; ++m) _Pragma("unroll") for (int n = 0; n < 2; ++n) _Pragma("unroll") for (int k = 0; k < 2; ++k) \
;         acc[ai][bj][m][n] = __builtin_amdgcn_mfma_f32_16x16x32_bf16(Bt[n][k], At[m][k], acc[ai][bj][m][n], 0, 0, 0); __builtin_amdgcn_s_setprio(0); } while (0)
; #define PG8_WAIT_V(n) asm volatile("s_waitcnt vmcnt(" #n ")" ::: "memory")
; #define PG8_WAIT_L(n) asm volatile("s_waitcnt lgkmcnt(" #n ")" ::: "memory")
; #define PG8_BAR __builtin_amdgcn_s_barrier()
; #define PG8_SCHED __builtin_amdgcn_sched_barrier(0)
; template <class Epi>
; __device__ __forceinline__ void gemm_phase(LAS unsigned char* lds, const int tid, const Gemm g, const StaticOrder& S, const Epi& E) {
;     ...
;             PG8_WAIT_V(8); PG8_WAIT_L(0); PG8_BAR; PG8_MMA(1, 0, At, B0); PG8_MMA(1, 1, At, B1); PG8_BAR; PG8_SCHED;
;             PG8_LDB(B0, 1, 0); PG8_LDB(B1, 1, 1); PG8_SCHED; PG8_LDA(At, 1, 0); PG8_STAGE(PG8_SA(0, 1), a2 + hstepA, voffA);
;             PG8_WAIT_V(8); PG8_WAIT_L(0); PG8_BAR; PG8_MMA(0, 0, At, B0); PG8_MMA(0, 1, At, B1); PG8_BAR; PG8_SCHED;
	v_mfma_f32_16x16x32_bf16 v[60:63], v[132:135], v[164:167], v[60:63]
	v_mfma_f32_16x16x32_bf16 v[56:59], v[140:143], v[164:167], v[56:59]
	v_mfma_f32_16x16x32_bf16 v[44:47], v[132:135], v[172:175], v[44:47]
	v_mfma_f32_16x16x32_bf16 v[40:43], v[140:143], v[172:175], v[40:43]
	v_mfma_f32_16x16x32_bf16 v[28:31], v[132:135], v[198:201], v[28:31]
	v_mfma_f32_16x16x32_bf16 v[24:27], v[140:143], v[198:201], v[24:27]
	v_mfma_f32_16x16x32_bf16 v[12:15], v[132:135], v[214:217], v[12:15]
	v_mfma_f32_16x16x32_bf16 v[8:11], v[140:143], v[214:217], v[8:11]
	v_mfma_f32_16x16x32_bf16 v[60:63], v[136:139], v[168:171], v[60:63]
	v_mfma_f32_16x16x32_bf16 v[56:59], v[144:147], v[168:171], v[56:59]
	v_mfma_f32_16x16x32_bf16 v[44:47], v[136:139], v[176:179], v[44:47]
	v_mfma_f32_16x16x32_bf16 v[40:43], v[144:147], v[176:179], v[40:43]
	v_mfma_f32_16x16x32_bf16 v[28:31], v[136:139], v[202:205], v[28:31]
	v_mfma_f32_16x16x32_bf16 v[24:27], v[144:147], v[202:205], v[24:27]
	v_mfma_f32_16x16x32_bf16 v[12:15], v[136:139], v[218:221], v[12:15]
	v_mfma_f32_16x16x32_bf16 v[8:11], v[144:147], v[218:221], v[8:11]
	v_mfma_f32_16x16x32_bf16 v[52:55], v[148:151], v[164:167], v[52:55]
	v_mfma_f32_16x16x32_bf16 v[48:51], v[156:159], v[164:167], v[48:51]
	v_mfma_f32_16x16x32_bf16 v[36:39], v[148:151], v[172:175], v[36:39]
	v_mfma_f32_16x16x32_bf16 v[32:35], v[156:159], v[172:175], v[32:35]
	v_mfma_f32_16x16x32_bf16 v[20:23], v[148:151], v[198:201], v[20:23]
	v_mfma_f32_16x16x32_bf16 v[16:19], v[156:159], v[198:201], v[16:19]
	v_mfma_f32_16x16x32_bf16 v[4:7], v[148:151], v[214:217], v[4:7]
	v_mfma_f32_16x16x32_bf16 v[0:3], v[156:159], v[214:217], v[0:3]
	v_mfma_f32_16x16x32_bf16 v[52:55], v[152:155], v[168:171], v[52:55]
	v_mfma_f32_16x16x32_bf16 v[48:51], v[160:163], v[168:171], v[48:51]
	v_mfma_f32_16x16x32_bf16 v[36:39], v[152:155], v[176:179], v[36:39]
	v_mfma_f32_16x16x32_bf16 v[32:35], v[160:163], v[176:179], v[32:35]
	v_mfma_f32_16x16x32_bf16 v[20:23], v[152:155], v[202:205], v[20:23]
	v_mfma_f32_16x16x32_bf16 v[16:19], v[160:163], v[202:205], v[16:19]
	v_mfma_f32_16x16x32_bf16 v[4:7], v[152:155], v[218:221], v[4:7]
	v_mfma_f32_16x16x32_bf16 v[0:3], v[160:163], v[218:221], v[0:3]
	s_barrier
	s_add_i32 s65, 0, 0x18000
	s_add_i32 s66, 0, 0x1c000
	v_add_u32_e32 v144, s65, v209
	v_add_u32_e32 v160, s66, v209
	ds_read_b128 v[132:135], v144
	ds_read_b128 v[136:139], v144 offset:1024
	ds_read_b128 v[140:143], v144 offset:2048
	ds_read_b128 v[144:147], v144 offset:3072
	ds_read_b128 v[148:151], v160
	ds_read_b128 v[152:155], v160 offset:1024
	ds_read_b128 v[156:159], v160 offset:2048
	ds_read_b128 v[160:163], v160 offset:3072
	s_add_u32 s42, s42, 0x40000
	s_addc_u32 s43, s43, 0
	s_mov_b32 m0, s50
	v_lshl_add_u64 v[228:229], s[42:43], 0, v[180:181]
	ds_read_b128 v[164:167], v211 offset:32768
	ds_read_b128 v[168:171], v211 offset:33792
	ds_read_b128 v[172:175], v211 offset:34816
	ds_read_b128 v[176:179], v211 offset:35840
	ds_read_b128 v[198:201], v211 offset:36864
	ds_read_b128 v[202:205], v211 offset:37888
	ds_read_b128 v[214:217], v211 offset:38912
	ds_read_b128 v[218:221], v211 offset:39936
	global_load_lds_dwordx4 v[228:229], off
	v_lshl_add_u64 v[228:229], s[42:43], 0, v[184:185]
	s_mov_b32 m0, s51
	s_nop 0
	global_load_lds_dwordx4 v[228:229], off
	s_waitcnt vmcnt(8)
	s_waitcnt lgkmcnt(0)
	s_barrier
	v_mfma_f32_16x16x32_bf16 v[124:127], v[132:135], v[164:167], v[124:127]
	v_mfma_f32_16x16x32_bf16 v[120:123], v[140:143], v[164:167], v[120:123]
	v_mfma_f32_16x16x32_bf16 v[108:111], v[132:135], v[172:175], v[108:111]
	v_mfma_f32_16x16x32_bf16 v[104:107], v[140:143], v[172:175], v[104:107]
	v_mfma_f32_16x16x32_bf16 v[92:95], v[132:135], v[198:201], v[92:95]
	v_mfma_f32_16x16x32_bf16 v[88:91], v[140:143], v[198:201], v[88:91]
	v_mfma_f32_16x16x32_bf16 v[76:79], v[132:135], v[214:217], v[76:79]
	v_mfma_f32_16x16x32_bf16 v[72:75], v[140:143], v[214:217], v[72:75]
	v_mfma_f32_16x16x32_bf16 v[124:127], v[136:139], v[168:171], v[124:127]
	v_mfma_f32_16x16x32_bf16 v[120:123], v[144:147], v[168:171], v[120:123]
	v_mfma_f32_16x16x32_bf16 v[108:111], v[136:139], v[176:179], v[108:111]
	v_mfma_f32_16x16x32_bf16 v[104:107], v[144:147], v[176:179], v[104:107]
	v_mfma_f32_16x16x32_bf16 v[92:95], v[136:139], v[202:205], v[92:95]
	v_mfma_f32_16x16x32_bf16 v[88:91], v[144:147], v[202:205], v[88:91]
	v_mfma_f32_16x16x32_bf16 v[76:79], v[136:139], v[218:221], v[76:79]
	v_mfma_f32_16x16x32_bf16 v[72:75], v[144:147], v[218:221], v[72:75]
	v_mfma_f32_16x16x32_bf16 v[116:119], v[148:151], v[164:167], v[116:119]
	v_mfma_f32_16x16x32_bf16 v[112:115], v[156:159], v[164:167], v[112:115]
	v_mfma_f32_16x16x32_bf16 v[100:103], v[148:151], v[172:175], v[100:103]
	v_mfma_f32_16x16x32_bf16 v[96:99], v[156:159], v[172:175], v[96:99]
	v_mfma_f32_16x16x32_bf16 v[84:87], v[148:151], v[198:201], v[84:87]
	v_mfma_f32_16x16x32_bf16 v[80:83], v[156:159], v[198:201], v[80:83]
	v_mfma_f32_16x16x32_bf16 v[68:71], v[148:151], v[214:217], v[68:71]
	v_mfma_f32_16x16x32_bf16 v[64:67], v[156:159], v[214:217], v[64:67]
	v_mfma_f32_16x16x32_bf16 v[116:119], v[152:155], v[168:171], v[116:119]
	v_mfma_f32_16x16x32_bf16 v[112:115], v[160:163], v[168:171], v[112:115]
	v_mfma_f32_16x16x32_bf16 v[100:103], v[152:155], v[176:179], v[100:103]
	v_mfma_f32_16x16x32_bf16 v[96:99], v[160:163], v[176:179], v[96:99]
	v_mfma_f32_16x16x32_bf16 v[84:87], v[152:155], v[202:205], v[84:87]
	v_mfma_f32_16x16x32_bf16 v[80:83], v[160:163], v[202:205], v[80:83]
	v_mfma_f32_16x16x32_bf16 v[68:71], v[152:155], v[218:221], v[68:71]
	v_mfma_f32_16x16x32_bf16 v[64:67], v[160:163], v[218:221], v[64:67]
	s_barrier
; #define PG8_STAGE(bufoff, gbase, voff) do { _Pragma("unroll") for (int _i = 0; _i < 2; ++_i) \
;         __builtin_amdgcn_global_load_lds((const unsigned*)((const char*)(gbase) + (voff)[_i]), (LAS unsigned*)(lds + (bufoff) + ldsw + _i * 8192), 16, 0, 0); } while (0)
; #define PG8_LDA(dst, b, h) do { _Pragma("unroll") for (int m = 0; m < 4; ++m) _Pragma("unroll") for (int k = 0; k < 2; ++k) dst[m][k] = *(const LAS bf16x8*)(lds + PG8_SA(b, h) + aoff + m * 2048 + k * 1024); } while (0)
; #define PG8_MMA(ai, bj, At, Bt) do { __builtin_amdgcn_s_setprio(1); _Pragma("unroll") for (int m = 0; m < 4; ++m) _Pragma("unroll") for (int n = 0; n < 2; ++n) _Pragma("unroll") for (int k = 0; k < 2; ++k) \
;         acc[ai][bj][m][n] = __builtin_amdgcn_mfma_f32_16x16x32_bf16(Bt[n][k], At[m][k], acc[ai][bj][m][n], 0, 0, 0); __builtin_amdgcn_s_setprio(0); } while (0)
; #define PG8_WAIT_V(n) asm volatile("s_waitcnt vmcnt(" #n ")" ::: "memory")
; #define PG8_WAIT_L(n) asm volatile("s_waitcnt lgkmcnt(" #n ")" ::: "memory")
; #define PG8_BAR __builtin_amdgcn_s_barrier()
; #define PG8_SCHED __builtin_amdgcn_sched_barrier(0)
; template <class Epi>
; __device__ __forceinline__ void gemm_phase(LAS unsigned char* lds, const int tid, const Gemm g, const StaticOrder& S, const Epi& E) {
;     ...
;             PG8_LDA(At, 1, 1); PG8_STAGE(PG8_SB(1, 0), b3, voffB); PG8_STAGE(PG8_SB(1, 1), b3 + hstepB, voffB); PG8_STAGE(PG8_SA(1, 0), a3, voffA);
;             PG8_WAIT_V(8); PG8_WAIT_L(0); PG8_BAR; PG8_MMA(1, 0, At, B0); PG8_MMA(1, 1, At, B1); PG8_BAR; PG8_SCHED;
	s_add_i32 s42, s65, s47
	v_lshl_add_u64 v[206:207], v[206:207], 0, s[20:21]
	s_mov_b32 m0, s42
	ds_read_b128 v[164:167], v211 offset:49152
	ds_read_b128 v[168:171], v211 offset:50176
	ds_read_b128 v[172:175], v211 offset:51200
	ds_read_b128 v[176:179], v211 offset:52224
	ds_read_b128 v[198:201], v211 offset:53248
	ds_read_b128 v[202:205], v211 offset:54272
	ds_read_b128 v[214:217], v211 offset:55296
	ds_read_b128 v[218:221], v211 offset:56320
	global_load_lds_dwordx4 v[206:207], off
	s_add_i32 m0, s42, 0x2000
	s_add_u32 s40, s40, 0x40080
	v_lshl_add_u64 v[206:207], v[222:223], 0, s[20:21]
	s_addc_u32 s41, s41, 0
	s_add_i32 s42, s66, s47
	global_load_lds_dwordx4 v[206:207], off
	v_lshl_add_u64 v[206:207], s[40:41], 0, v[182:183]
	s_mov_b32 m0, s42
	s_nop 0
	global_load_lds_dwordx4 v[206:207], off
	v_lshl_add_u64 v[206:207], s[40:41], 0, v[186:187]
	s_add_i32 m0, s42, 0x2000
	s_nop 0
	global_load_lds_dwordx4 v[206:207], off
	v_lshl_add_u64 v[206:207], v[224:225], 0, s[20:21]
	s_mov_b32 m0, s54
	s_nop 0
	global_load_lds_dwordx4 v[206:207], off
	v_lshl_add_u64 v[206:207], v[226:227], 0, s[20:21]
	s_mov_b32 m0, s55
	s_nop 0
	global_load_lds_dwordx4 v[206:207], off
	s_waitcnt vmcnt(8)
	s_waitcnt lgkmcnt(0)
	s_barrier
	v_mfma_f32_16x16x32_bf16 v[60:63], v[132:135], v[164:167], v[60:63]
	v_mfma_f32_16x16x32_bf16 v[56:59], v[140:143], v[164:167], v[56:59]
	v_mfma_f32_16x16x32_bf16 v[44:47], v[132:135], v[172:175], v[44:47]
	v_mfma_f32_16x16x32_bf16 v[40:43], v[140:143], v[172:175], v[40:43]
	v_mfma_f32_16x16x32_bf16 v[28:31], v[132:135], v[198:201], v[28:31]
	v_mfma_f32_16x16x32_bf16 v[24:27], v[140:143], v[198:201], v[24:27]
	v_mfma_f32_16x16x32_bf16 v[12:15], v[132:135], v[214:217], v[12:15]
	v_mfma_f32_16x16x32_bf16 v[8:11], v[140:143], v[214:217], v[8:11]
	v_mfma_f32_16x16x32_bf16 v[60:63], v[136:139], v[168:171], v[60:63]
	v_mfma_f32_16x16x32_bf16 v[56:59], v[144:147], v[168:171], v[56:59]
	v_mfma_f32_16x16x32_bf16 v[44:47], v[136:139], v[176:179], v[44:47]
	v_mfma_f32_16x16x32_bf16 v[40:43], v[144:147], v[176:179], v[40:43]
	v_mfma_f32_16x16x32_bf16 v[28:31], v[136:139], v[202:205], v[28:31]
	v_mfma_f32_16x16x32_bf16 v[24:27], v[144:147], v[202:205], v[24:27]
	v_mfma_f32_16x16x32_bf16 v[12:15], v[136:139], v[218:221], v[12:15]
	v_mfma_f32_16x16x32_bf16 v[8:11], v[144:147], v[218:221], v[8:11]
	v_mfma_f32_16x16x32_bf16 v[52:55], v[148:151], v[164:167], v[52:55]
	v_mfma_f32_16x16x32_bf16 v[48:51], v[156:159], v[164:167], v[48:51]
	v_mfma_f32_16x16x32_bf16 v[36:39], v[148:151], v[172:175], v[36:39]
	v_mfma_f32_16x16x32_bf16 v[32:35], v[156:159], v[172:175], v[32:35]
	v_mfma_f32_16x16x32_bf16 v[20:23], v[148:151], v[198:201], v[20:23]
	v_mfma_f32_16x16x32_bf16 v[16:19], v[156:159], v[198:201], v[16:19]
	v_mfma_f32_16x16x32_bf16 v[4:7], v[148:151], v[214:217], v[4:7]
	v_mfma_f32_16x16x32_bf16 v[0:3], v[156:159], v[214:217], v[0:3]
	v_mfma_f32_16x16x32_bf16 v[52:55], v[152:155], v[168:171], v[52:55]
	v_mfma_f32_16x16x32_bf16 v[48:51], v[160:163], v[168:171], v[48:51]
	v_mfma_f32_16x16x32_bf16 v[36:39], v[152:155], v[176:179], v[36:39]
	v_mfma_f32_16x16x32_bf16 v[32:35], v[160:163], v[176:179], v[32:35]
	v_mfma_f32_16x16x32_bf16 v[20:23], v[152:155], v[202:205], v[20:23]
	v_mfma_f32_16x16x32_bf16 v[16:19], v[160:163], v[202:205], v[16:19]
	v_mfma_f32_16x16x32_bf16 v[4:7], v[152:155], v[218:221], v[4:7]
	v_mfma_f32_16x16x32_bf16 v[0:3], v[160:163], v[218:221], v[0:3]
	s_barrier
	s_add_u32 s37, s37, 0x100
	s_addc_u32 s63, s63, 0
	s_add_u32 s38, s38, 0x100
	s_addc_u32 s39, s39, 0
	s_cmp_ge_i32 s64, s53
	s_cbranch_scc1 .LBB0_1035

; #define LAS __attribute__((address_space(3)))
; #define PG8_STAGE(bufoff, gbase, voff) do { _Pragma("unroll") for (int _i = 0; _i < 2; ++_i) \
;         __builtin_amdgcn_global_load_lds((const unsigned*)((const char*)(gbase) + (voff)[_i]), (LAS unsigned*)(lds + (bufoff) + ldsw + _i * 8192), 16, 0, 0); } while (0)
; #define PG8_LDA(dst, b, h) do { _Pragma("unroll") for (int m = 0; m < 4; ++m) _Pragma("unroll") for (int k = 0; k < 2; ++k) dst[m][k] = *(const LAS bf16x8*)(lds + PG8_SA(b, h) + aoff + m * 2048 + k * 1024); } while (0)
; #define PG8_LDB(dst, b, h) do { _Pragma("unroll") for (int n = 0; n < 2; ++n) _Pragma("unroll") for (int k = 0; k < 2; ++k) dst[n][k] = *(const LAS bf16x8*)(lds + PG8_SB(b, h) + boff + n * 2048 + k * 1024); } while (0)
; #define PG8_WAIT_V(n) asm volatile("s_waitcnt vmcnt(" #n ")" ::: "memory")
; #define PG8_WAIT_L(n) asm volatile("s_waitcnt lgkmcnt(" #n ")" ::: "memory")
; #define PG8_BAR __builtin_amdgcn_s_barrier()
; #define PG8_SCHED __builtin_amdgcn_sched_barrier(0)
; template <class Epi>
; __device__ __forceinline__ void gemm_phase(LAS unsigned char* lds, const int tid, const Gemm g, const StaticOrder& S, const Epi& E) {
;     ...
;             const char* a1 = cA + (size_t)(t + 1) * kstep;
;             const char* a2 = last ? nA : cA + (size_t)(t + 2) * kstep; const char* b2 = last ? nB : cB + (size_t)(t + 2) * kstep;
;             const char* a3 = a2 + kstep; const char* b3 = b2 + kstep;
;             if constexpr (Epi::SS_LDS) { if (last) {
;                 const char* sp = (const char*)E.ss + (size_t)cur.pm * (256 * 64) + (size_t)tid * 16;
;                 __builtin_amdgcn_global_load_lds((const unsigned*)sp, (LAS unsigned*)(lds + RS_OFF + ldsw), 16, 0, 0);
;                 __builtin_amdgcn_global_load_lds((const unsigned*)(sp + 8192), (LAS unsigned*)(lds + RS_OFF + 8192 + ldsw), 16, 0, 0); } }
;     ...
;             PG8_LDB(B0, 0, 0); PG8_LDB(B1, 0, 1); PG8_SCHED; PG8_LDA(At, 0, 0); PG8_STAGE(PG8_SA(1, 1), a1 + hstepA, voffA);
;             PG8_WAIT_V(8); PG8_WAIT_L(0); PG8_BAR; PG8_MMA(0, 0, At, B0); PG8_MMA(0, 1, At, B1); PG8_BAR; PG8_SCHED;
;             PG8_LDA(At, 0, 1); PG8_STAGE(PG8_SB(0, 0), b2, voffB); PG8_STAGE(PG8_SB(0, 1), b2 + hstepB, voffB); PG8_STAGE(PG8_SA(0, 0), a2, voffA);
;             PG8_WAIT_V(8); PG8_WAIT_L(0); PG8_BAR; PG8_MMA(1, 0, At, B0); PG8_MMA(1, 1, At, B1); PG8_BAR; PG8_SCHED;
.LBB0_1312:
	v_add_u32_e32 v161, s52, v157
	ds_read_b128 v[152:155], v161
	ds_read_b128 v[162:165], v161 offset:1024
	ds_read_b128 v[166:169], v161 offset:2048
	ds_read_b128 v[170:173], v161 offset:3072
	v_add_u32_e32 v161, s53, v157
	ds_read_b128 v[174:177], v161
	ds_read_b128 v[178:181], v161 offset:1024
	ds_read_b128 v[182:185], v161 offset:2048
	ds_read_b128 v[186:189], v161 offset:3072
	s_add_i32 s58, s58, 2
	s_add_u32 s34, s28, 0xfffc0080
	s_addc_u32 s35, s29, -1
	s_and_b64 s[30:31], s[30:31], exec
	s_cselect_b32 s35, s19, s35
	s_cselect_b32 s34, s21, s34
	s_cselect_b32 s31, s33, s57
	s_cselect_b32 s30, s56, s5
	v_lshl_add_u64 v[222:223], s[28:29], 0, v[142:143]
	s_add_i32 m0, s27, 0xc000
	ds_read_b128 v[190:193], v158
	ds_read_b128 v[194:197], v158 offset:1024
	ds_read_b128 v[198:201], v158 offset:2048
	ds_read_b128 v[202:205], v158 offset:3072
	ds_read_b128 v[206:209], v158 offset:4096
	ds_read_b128 v[210:213], v158 offset:5120
	ds_read_b128 v[214:217], v158 offset:6144
	ds_read_b128 v[218:221], v158 offset:7168
	global_load_lds_dwordx4 v[222:223], off
	v_lshl_add_u64 v[222:223], s[28:29], 0, v[140:141]
	s_add_i32 m0, s27, 0xe000
	s_nop 0
	global_load_lds_dwordx4 v[222:223], off
	s_waitcnt vmcnt(8)
	s_waitcnt lgkmcnt(0)
	s_barrier
	v_mfma_f32_16x16x32_bf16 v[124:127], v[152:155], v[190:193], v[124:127]
	v_mfma_f32_16x16x32_bf16 v[120:123], v[166:169], v[190:193], v[120:123]
	v_mfma_f32_16x16x32_bf16 v[108:111], v[152:155], v[198:201], v[108:111]
	v_mfma_f32_16x16x32_bf16 v[104:107], v[166:169], v[198:201], v[104:107]
	v_mfma_f32_16x16x32_bf16 v[92:95], v[152:155], v[206:209], v[92:95]
	v_mfma_f32_16x16x32_bf16 v[88:91], v[166:169], v[206:209], v[88:91]
	v_mfma_f32_16x16x32_bf16 v[76:79], v[152:155], v[214:217], v[76:79]
	v_mfma_f32_16x16x32_bf16 v[72:75], v[166:169], v[214:217], v[72:75]
	v_mfma_f32_16x16x32_bf16 v[124:127], v[162:165], v[194:197], v[124:127]
	v_mfma_f32_16x16x32_bf16 v[120:123], v[170:173], v[194:197], v[120:123]
	v_mfma_f32_16x16x32_bf16 v[108:111], v[162:165], v[202:205], v[108:111]
	v_mfma_f32_16x16x32_bf16 v[104:107], v[170:173], v[202:205], v[104:107]
	v_mfma_f32_16x16x32_bf16 v[92:95], v[162:165], v[210:213], v[92:95]
	v_mfma_f32_16x16x32_bf16 v[88:91], v[170:173], v[210:213], v[88:91]
	v_mfma_f32_16x16x32_bf16 v[76:79], v[162:165], v[218:221], v[76:79]
	v_mfma_f32_16x16x32_bf16 v[72:75], v[170:173], v[218:221], v[72:75]
	v_mfma_f32_16x16x32_bf16 v[116:119], v[174:177], v[190:193], v[116:119]
	v_mfma_f32_16x16x32_bf16 v[112:115], v[182:185], v[190:193], v[112:115]
	v_mfma_f32_16x16x32_bf16 v[100:103], v[174:177], v[198:201], v[100:103]
	v_mfma_f32_16x16x32_bf16 v[96:99], v[182:185], v[198:201], v[96:99]
	v_mfma_f32_16x16x32_bf16 v[84:87], v[174:177], v[206:209], v[84:87]
	v_mfma_f32_16x16x32_bf16 v[80:83], v[182:185], v[206:209], v[80:83]
	v_mfma_f32_16x16x32_bf16 v[68:71], v[174:177], v[214:217], v[68:71]
	v_mfma_f32_16x16x32_bf16 v[64:67], v[182:185], v[214:217], v[64:67]
	v_mfma_f32_16x16x32_bf16 v[116:119], v[178:181], v[194:197], v[116:119]
	v_mfma_f32_16x16x32_bf16 v[112:115], v[186:189], v[194:197], v[112:115]
	v_mfma_f32_16x16x32_bf16 v[100:103], v[178:181], v[202:205], v[100:103]
	v_mfma_f32_16x16x32_bf16 v[96:99], v[186:189], v[202:205], v[96:99]
	v_mfma_f32_16x16x32_bf16 v[84:87], v[178:181], v[210:213], v[84:87]
	v_mfma_f32_16x16x32_bf16 v[80:83], v[186:189], v[210:213], v[80:83]
	v_mfma_f32_16x16x32_bf16 v[68:71], v[178:181], v[218:221], v[68:71]
	v_mfma_f32_16x16x32_bf16 v[64:67], v[186:189], v[218:221], v[64:67]
	s_barrier
	s_add_i32 s59, s52, s41
	v_lshl_add_u64 v[222:223], s[30:31], 0, v[130:131]
	s_mov_b32 m0, s59
	ds_read_b128 v[190:193], v158 offset:16384
	ds_read_b128 v[194:197], v158 offset:17408
	ds_read_b128 v[198:201], v158 offset:18432
	ds_read_b128 v[202:205], v158 offset:19456
	ds_read_b128 v[206:209], v158 offset:20480
	ds_read_b128 v[210:213], v158 offset:21504
	ds_read_b128 v[214:217], v158 offset:22528
	ds_read_b128 v[218:221], v158 offset:23552
	global_load_lds_dwordx4 v[222:223], off
	s_add_i32 m0, s59, 0x2000
	s_add_u32 s60, s30, 0x40000
	v_lshl_add_u64 v[224:225], s[30:31], 0, v[134:135]
	s_addc_u32 s61, s31, 0
	s_add_i32 s59, s53, s41
	global_load_lds_dwordx4 v[224:225], off
	v_lshl_add_u64 v[226:227], s[60:61], 0, v[130:131]
	s_mov_b32 m0, s59
	v_lshl_add_u64 v[228:229], s[34:35], 0, v[132:133]
	global_load_lds_dwordx4 v[226:227], off
	v_lshl_add_u64 v[226:227], s[60:61], 0, v[134:135]
	s_add_i32 m0, s59, 0x2000
	s_nop 0
	global_load_lds_dwordx4 v[226:227], off
	v_lshl_add_u64 v[226:227], s[34:35], 0, v[128:129]
	s_mov_b32 m0, s27
	s_nop 0
	global_load_lds_dwordx4 v[226:227], off
	s_mov_b32 m0, s42
	s_nop 0
	global_load_lds_dwordx4 v[228:229], off
	s_waitcnt vmcnt(8)
	s_waitcnt lgkmcnt(0)
	s_barrier
; #define PG8_STAGE(bufoff, gbase, voff) do { _Pragma("unroll") for (int _i = 0; _i < 2; ++_i) \
;         __builtin_amdgcn_global_load_lds((const unsigned*)((const char*)(gbase) + (voff)[_i]), (LAS unsigned*)(lds + (bufoff) + ldsw + _i * 8192), 16, 0, 0); } while (0)
; #define PG8_LDA(dst, b, h) do { _Pragma("unroll") for (int m = 0; m < 4; ++m) _Pragma("unroll") for (int k = 0; k < 2; ++k) dst[m][k] = *(const LAS bf16x8*)(lds + PG8_SA(b, h) + aoff + m * 2048 + k * 1024); } while (0)
; #define PG8_LDB(dst, b, h) do { _Pragma("unroll") for (int n = 0; n < 2; ++n) _Pragma("unroll") for (int k = 0; k < 2; ++k) dst[n][k] = *(const LAS bf16x8*)(lds + PG8_SB(b, h) + boff + n * 2048 + k * 1024); } while (0)
; #define PG8_MMA(ai, bj, At, Bt) do { __builtin_amdgcn_s_setprio(1); _Pragma("unroll") for (int m = 0; m < 4; ++m) _Pragma("unroll") for (int n = 0; n < 2; ++n) _Pragma("unroll") for (int k = 0; k < 2; ++k) \
;         acc[ai][bj][m][n] = __builtin_amdgcn_mfma_f32_16x16x32_bf16(Bt[n][k], At[m][k], acc[ai][bj][m][n], 0, 0, 0); __builtin_amdgcn_s_setprio(0); } while (0)
; #define PG8_WAIT_V(n) asm volatile("s_waitcnt vmcnt(" #n ")" ::: "memory")
; #define PG8_WAIT_L(n) asm volatile("s_waitcnt lgkmcnt(" #n ")" ::: "memory")
; #define PG8_BAR __builtin_amdgcn_s_barrier()
; #define PG8_SCHED __builtin_amdgcn_sched_barrier(0)
; template <class Epi>
; __device__ __forceinline__ void gemm_phase(LAS unsigned char* lds, const int tid, const Gemm g, const StaticOrder& S, const Epi& E) {
;     ...
;             PG8_WAIT_V(8); PG8_WAIT_L(0); PG8_BAR; PG8_MMA(1, 0, At, B0); PG8_MMA(1, 1, At, B1); PG8_BAR; PG8_SCHED;
;             PG8_LDB(B0, 1, 0); PG8_LDB(B1, 1, 1); PG8_SCHED; PG8_LDA(At, 1, 0); PG8_STAGE(PG8_SA(0, 1), a2 + hstepA, voffA);
;             PG8_WAIT_V(8); PG8_WAIT_L(0); PG8_BAR; PG8_MMA(0, 0, At, B0); PG8_MMA(0, 1, At, B1); PG8_BAR; PG8_SCHED;
	v_mfma_f32_16x16x32_bf16 v[60:63], v[152:155], v[190:193], v[60:63]
	v_mfma_f32_16x16x32_bf16 v[56:59], v[166:169], v[190:193], v[56:59]
	v_mfma_f32_16x16x32_bf16 v[44:47], v[152:155], v[198:201], v[44:47]
	v_mfma_f32_16x16x32_bf16 v[40:43], v[166:169], v[198:201], v[40:43]
	v_mfma_f32_16x16x32_bf16 v[28:31], v[152:155], v[206:209], v[28:31]
	v_mfma_f32_16x16x32_bf16 v[24:27], v[166:169], v[206:209], v[24:27]
	v_mfma_f32_16x16x32_bf16 v[12:15], v[152:155], v[214:217], v[12:15]
	v_mfma_f32_16x16x32_bf16 v[8:11], v[166:169], v[214:217], v[8:11]
	v_mfma_f32_16x16x32_bf16 v[60:63], v[162:165], v[194:197], v[60:63]
	v_mfma_f32_16x16x32_bf16 v[56:59], v[170:173], v[194:197], v[56:59]
	v_mfma_f32_16x16x32_bf16 v[44:47], v[162:165], v[202:205], v[44:47]
	v_mfma_f32_16x16x32_bf16 v[40:43], v[170:173], v[202:205], v[40:43]
	v_mfma_f32_16x16x32_bf16 v[28:31], v[162:165], v[210:213], v[28:31]
	v_mfma_f32_16x16x32_bf16 v[24:27], v[170:173], v[210:213], v[24:27]
	v_mfma_f32_16x16x32_bf16 v[12:15], v[162:165], v[218:221], v[12:15]
	v_mfma_f32_16x16x32_bf16 v[8:11], v[170:173], v[218:221], v[8:11]
	v_mfma_f32_16x16x32_bf16 v[52:55], v[174:177], v[190:193], v[52:55]
	v_mfma_f32_16x16x32_bf16 v[48:51], v[182:185], v[190:193], v[48:51]
	v_mfma_f32_16x16x32_bf16 v[36:39], v[174:177], v[198:201], v[36:39]
	v_mfma_f32_16x16x32_bf16 v[32:35], v[182:185], v[198:201], v[32:35]
	v_mfma_f32_16x16x32_bf16 v[20:23], v[174:177], v[206:209], v[20:23]
	v_mfma_f32_16x16x32_bf16 v[16:19], v[182:185], v[206:209], v[16:19]
	v_mfma_f32_16x16x32_bf16 v[4:7], v[174:177], v[214:217], v[4:7]
	v_mfma_f32_16x16x32_bf16 v[0:3], v[182:185], v[214:217], v[0:3]
	v_mfma_f32_16x16x32_bf16 v[52:55], v[178:181], v[194:197], v[52:55]
	v_mfma_f32_16x16x32_bf16 v[48:51], v[186:189], v[194:197], v[48:51]
	v_mfma_f32_16x16x32_bf16 v[36:39], v[178:181], v[202:205], v[36:39]
	v_mfma_f32_16x16x32_bf16 v[32:35], v[186:189], v[202:205], v[32:35]
	v_mfma_f32_16x16x32_bf16 v[20:23], v[178:181], v[210:213], v[20:23]
	v_mfma_f32_16x16x32_bf16 v[16:19], v[186:189], v[210:213], v[16:19]
	v_mfma_f32_16x16x32_bf16 v[4:7], v[178:181], v[218:221], v[4:7]
	v_mfma_f32_16x16x32_bf16 v[0:3], v[186:189], v[218:221], v[0:3]
	s_barrier
	s_add_i32 s59, 0, 0x18000
	v_add_u32_e32 v161, s59, v157
	s_add_i32 s60, 0, 0x1c000
	ds_read_b128 v[152:155], v161
	ds_read_b128 v[162:165], v161 offset:1024
	ds_read_b128 v[166:169], v161 offset:2048
	ds_read_b128 v[170:173], v161 offset:3072
	v_add_u32_e32 v161, s60, v157
	ds_read_b128 v[174:177], v161
	ds_read_b128 v[178:181], v161 offset:1024
	ds_read_b128 v[182:185], v161 offset:2048
	ds_read_b128 v[186:189], v161 offset:3072
	s_add_u32 s34, s34, 0x40000
	s_addc_u32 s35, s35, 0
	s_mov_b32 m0, s43
	v_lshl_add_u64 v[230:231], s[34:35], 0, v[128:129]
	ds_read_b128 v[190:193], v158 offset:32768
	ds_read_b128 v[194:197], v158 offset:33792
	ds_read_b128 v[198:201], v158 offset:34816
	ds_read_b128 v[202:205], v158 offset:35840
	ds_read_b128 v[206:209], v158 offset:36864
	ds_read_b128 v[210:213], v158 offset:37888
	ds_read_b128 v[214:217], v158 offset:38912
	ds_read_b128 v[218:221], v158 offset:39936
	global_load_lds_dwordx4 v[230:231], off
	v_lshl_add_u64 v[230:231], s[34:35], 0, v[132:133]
	s_mov_b32 m0, s44
	s_nop 0
	global_load_lds_dwordx4 v[230:231], off
	s_waitcnt vmcnt(8)
	s_waitcnt lgkmcnt(0)
	s_barrier
	v_mfma_f32_16x16x32_bf16 v[124:127], v[152:155], v[190:193], v[124:127]
	v_mfma_f32_16x16x32_bf16 v[120:123], v[166:169], v[190:193], v[120:123]
	v_mfma_f32_16x16x32_bf16 v[108:111], v[152:155], v[198:201], v[108:111]
	v_mfma_f32_16x16x32_bf16 v[104:107], v[166:169], v[198:201], v[104:107]
	v_mfma_f32_16x16x32_bf16 v[92:95], v[152:155], v[206:209], v[92:95]
	v_mfma_f32_16x16x32_bf16 v[88:91], v[166:169], v[206:209], v[88:91]
	v_mfma_f32_16x16x32_bf16 v[76:79], v[152:155], v[214:217], v[76:79]
	v_mfma_f32_16x16x32_bf16 v[72:75], v[166:169], v[214:217], v[72:75]
	v_mfma_f32_16x16x32_bf16 v[124:127], v[162:165], v[194:197], v[124:127]
	v_mfma_f32_16x16x32_bf16 v[120:123], v[170:173], v[194:197], v[120:123]
	v_mfma_f32_16x16x32_bf16 v[108:111], v[162:165], v[202:205], v[108:111]
	v_mfma_f32_16x16x32_bf16 v[104:107], v[170:173], v[202:205], v[104:107]
	v_mfma_f32_16x16x32_bf16 v[92:95], v[162:165], v[210:213], v[92:95]
	v_mfma_f32_16x16x32_bf16 v[88:91], v[170:173], v[210:213], v[88:91]
	v_mfma_f32_16x16x32_bf16 v[76:79], v[162:165], v[218:221], v[76:79]
	v_mfma_f32_16x16x32_bf16 v[72:75], v[170:173], v[218:221], v[72:75]
	v_mfma_f32_16x16x32_bf16 v[116:119], v[174:177], v[190:193], v[116:119]
	v_mfma_f32_16x16x32_bf16 v[112:115], v[182:185], v[190:193], v[112:115]
	v_mfma_f32_16x16x32_bf16 v[100:103], v[174:177], v[198:201], v[100:103]
	v_mfma_f32_16x16x32_bf16 v[96:99], v[182:185], v[198:201], v[96:99]
	v_mfma_f32_16x16x32_bf16 v[84:87], v[174:177], v[206:209], v[84:87]
	v_mfma_f32_16x16x32_bf16 v[80:83], v[182:185], v[206:209], v[80:83]
	v_mfma_f32_16x16x32_bf16 v[68:71], v[174:177], v[214:217], v[68:71]
	v_mfma_f32_16x16x32_bf16 v[64:67], v[182:185], v[214:217], v[64:67]
	v_mfma_f32_16x16x32_bf16 v[116:119], v[178:181], v[194:197], v[116:119]
	v_mfma_f32_16x16x32_bf16 v[112:115], v[186:189], v[194:197], v[112:115]
	v_mfma_f32_16x16x32_bf16 v[100:103], v[178:181], v[202:205], v[100:103]
	v_mfma_f32_16x16x32_bf16 v[96:99], v[186:189], v[202:205], v[96:99]
	v_mfma_f32_16x16x32_bf16 v[84:87], v[178:181], v[210:213], v[84:87]
	v_mfma_f32_16x16x32_bf16 v[80:83], v[186:189], v[210:213], v[80:83]
	v_mfma_f32_16x16x32_bf16 v[68:71], v[178:181], v[218:221], v[68:71]
	v_mfma_f32_16x16x32_bf16 v[64:67], v[186:189], v[218:221], v[64:67]
	s_barrier
; #define PG8_STAGE(bufoff, gbase, voff) do { _Pragma("unroll") for (int _i = 0; _i < 2; ++_i) \
;         __builtin_amdgcn_global_load_lds((const unsigned*)((const char*)(gbase) + (voff)[_i]), (LAS unsigned*)(lds + (bufoff) + ldsw + _i * 8192), 16, 0, 0); } while (0)
; #define PG8_LDA(dst, b, h) do { _Pragma("unroll") for (int m = 0; m < 4; ++m) _Pragma("unroll") for (int k = 0; k < 2; ++k) dst[m][k] = *(const LAS bf16x8*)(lds + PG8_SA(b, h) + aoff + m * 2048 + k * 1024); } while (0)
; #define PG8_MMA(ai, bj, At, Bt) do { __builtin_amdgcn_s_setprio(1); _Pragma("unroll") for (int m = 0; m < 4; ++m) _Pragma("unroll") for (int n = 0; n < 2; ++n) _Pragma("unroll") for (int k = 0; k < 2; ++k) \
;         acc[ai][bj][m][n] = __builtin_amdgcn_mfma_f32_16x16x32_bf16(Bt[n][k], At[m][k], acc[ai][bj][m][n], 0, 0, 0); __builtin_amdgcn_s_setprio(0); } while (0)
; #define PG8_WAIT_V(n) asm volatile("s_waitcnt vmcnt(" #n ")" ::: "memory")
; #define PG8_WAIT_L(n) asm volatile("s_waitcnt lgkmcnt(" #n ")" ::: "memory")
; #define PG8_BAR __builtin_amdgcn_s_barrier()
; #define PG8_SCHED __builtin_amdgcn_sched_barrier(0)
; template <class Epi>
; __device__ __forceinline__ void gemm_phase(LAS unsigned char* lds, const int tid, const Gemm g, const StaticOrder& S, const Epi& E) {
;     ...
;         for (int t = 0; t < nt; t += 2) {
;     ...
;             PG8_LDA(At, 1, 1); PG8_STAGE(PG8_SB(1, 0), b3, voffB); PG8_STAGE(PG8_SB(1, 1), b3 + hstepB, voffB); PG8_STAGE(PG8_SA(1, 0), a3, voffA);
;             PG8_WAIT_V(8); PG8_WAIT_L(0); PG8_BAR; PG8_MMA(1, 0, At, B0); PG8_MMA(1, 1, At, B1); PG8_BAR; PG8_SCHED;
	s_add_i32 s34, s59, s41
	v_lshl_add_u64 v[222:223], v[222:223], 0, s[10:11]
	s_mov_b32 m0, s34
	ds_read_b128 v[190:193], v158 offset:49152
	ds_read_b128 v[194:197], v158 offset:50176
	ds_read_b128 v[198:201], v158 offset:51200
	ds_read_b128 v[202:205], v158 offset:52224
	ds_read_b128 v[206:209], v158 offset:53248
	ds_read_b128 v[210:213], v158 offset:54272
	ds_read_b128 v[214:217], v158 offset:55296
	ds_read_b128 v[218:221], v158 offset:56320
	global_load_lds_dwordx4 v[222:223], off
	s_add_i32 m0, s34, 0x2000
	s_add_u32 s30, s30, 0x40080
	v_lshl_add_u64 v[222:223], v[224:225], 0, s[10:11]
	s_addc_u32 s31, s31, 0
	s_add_i32 s34, s60, s41
	global_load_lds_dwordx4 v[222:223], off
	v_lshl_add_u64 v[222:223], s[30:31], 0, v[130:131]
	s_mov_b32 m0, s34
	s_nop 0
	global_load_lds_dwordx4 v[222:223], off
	v_lshl_add_u64 v[222:223], s[30:31], 0, v[134:135]
	s_add_i32 m0, s34, 0x2000
	s_nop 0
	global_load_lds_dwordx4 v[222:223], off
	v_lshl_add_u64 v[222:223], v[226:227], 0, s[10:11]
	s_mov_b32 m0, s47
	s_nop 0
	global_load_lds_dwordx4 v[222:223], off
	v_lshl_add_u64 v[222:223], v[228:229], 0, s[10:11]
	s_mov_b32 m0, s48
	s_nop 0
	global_load_lds_dwordx4 v[222:223], off
	s_waitcnt vmcnt(8)
	s_waitcnt lgkmcnt(0)
	s_barrier
	v_mfma_f32_16x16x32_bf16 v[60:63], v[152:155], v[190:193], v[60:63]
	v_mfma_f32_16x16x32_bf16 v[56:59], v[166:169], v[190:193], v[56:59]
	v_mfma_f32_16x16x32_bf16 v[44:47], v[152:155], v[198:201], v[44:47]
	v_mfma_f32_16x16x32_bf16 v[40:43], v[166:169], v[198:201], v[40:43]
	v_mfma_f32_16x16x32_bf16 v[28:31], v[152:155], v[206:209], v[28:31]
	v_mfma_f32_16x16x32_bf16 v[24:27], v[166:169], v[206:209], v[24:27]
	v_mfma_f32_16x16x32_bf16 v[12:15], v[152:155], v[214:217], v[12:15]
	v_mfma_f32_16x16x32_bf16 v[8:11], v[166:169], v[214:217], v[8:11]
	v_mfma_f32_16x16x32_bf16 v[60:63], v[162:165], v[194:197], v[60:63]
	v_mfma_f32_16x16x32_bf16 v[56:59], v[170:173], v[194:197], v[56:59]
	v_mfma_f32_16x16x32_bf16 v[44:47], v[162:165], v[202:205], v[44:47]
	v_mfma_f32_16x16x32_bf16 v[40:43], v[170:173], v[202:205], v[40:43]
	v_mfma_f32_16x16x32_bf16 v[28:31], v[162:165], v[210:213], v[28:31]
	v_mfma_f32_16x16x32_bf16 v[24:27], v[170:173], v[210:213], v[24:27]
	v_mfma_f32_16x16x32_bf16 v[12:15], v[162:165], v[218:221], v[12:15]
	v_mfma_f32_16x16x32_bf16 v[8:11], v[170:173], v[218:221], v[8:11]
	v_mfma_f32_16x16x32_bf16 v[52:55], v[174:177], v[190:193], v[52:55]
	v_mfma_f32_16x16x32_bf16 v[48:51], v[182:185], v[190:193], v[48:51]
	v_mfma_f32_16x16x32_bf16 v[36:39], v[174:177], v[198:201], v[36:39]
	v_mfma_f32_16x16x32_bf16 v[32:35], v[182:185], v[198:201], v[32:35]
	v_mfma_f32_16x16x32_bf16 v[20:23], v[174:177], v[206:209], v[20:23]
	v_mfma_f32_16x16x32_bf16 v[16:19], v[182:185], v[206:209], v[16:19]
	v_mfma_f32_16x16x32_bf16 v[4:7], v[174:177], v[214:217], v[4:7]
	v_mfma_f32_16x16x32_bf16 v[0:3], v[182:185], v[214:217], v[0:3]
	v_mfma_f32_16x16x32_bf16 v[52:55], v[178:181], v[194:197], v[52:55]
	v_mfma_f32_16x16x32_bf16 v[48:51], v[186:189], v[194:197], v[48:51]
	v_mfma_f32_16x16x32_bf16 v[36:39], v[178:181], v[202:205], v[36:39]
	v_mfma_f32_16x16x32_bf16 v[32:35], v[186:189], v[202:205], v[32:35]
	v_mfma_f32_16x16x32_bf16 v[20:23], v[178:181], v[210:213], v[20:23]
	v_mfma_f32_16x16x32_bf16 v[16:19], v[186:189], v[210:213], v[16:19]
	v_mfma_f32_16x16x32_bf16 v[4:7], v[178:181], v[218:221], v[4:7]
	v_mfma_f32_16x16x32_bf16 v[0:3], v[186:189], v[218:221], v[0:3]
	s_barrier
	s_add_u32 s5, s5, 0x100
	s_addc_u32 s57, s57, 0
	s_add_u32 s28, s28, 0x100
	s_addc_u32 s29, s29, 0
	s_cmp_ge_i32 s58, s46
	s_cbranch_scc1 .LBB0_1315

; #define LAS __attribute__((address_space(3)))
; #define PG8_STAGE(bufoff, gbase, voff) do { _Pragma("unroll") for (int _i = 0; _i < 2; ++_i) \
;         __builtin_amdgcn_global_load_lds((const unsigned*)((const char*)(gbase) + (voff)[_i]), (LAS unsigned*)(lds + (bufoff) + ldsw + _i * 8192), 16, 0, 0); } while (0)
; #define PG8_LDA(dst, b, h) do { _Pragma("unroll") for (int m = 0; m < 4; ++m) _Pragma("unroll") for (int k = 0; k < 2; ++k) dst[m][k] = *(const LAS bf16x8*)(lds + PG8_SA(b, h) + aoff + m * 2048 + k * 1024); } while (0)
; #define PG8_LDB(dst, b, h) do { _Pragma("unroll") for (int n = 0; n < 2; ++n) _Pragma("unroll") for (int k = 0; k < 2; ++k) dst[n][k] = *(const LAS bf16x8*)(lds + PG8_SB(b, h) + boff + n * 2048 + k * 1024); } while (0)
; #define PG8_WAIT_V(n) asm volatile("s_waitcnt vmcnt(" #n ")" ::: "memory")
; #define PG8_WAIT_L(n) asm volatile("s_waitcnt lgkmcnt(" #n ")" ::: "memory")
; #define PG8_BAR __builtin_amdgcn_s_barrier()
; #define PG8_SCHED __builtin_amdgcn_sched_barrier(0)
; template <class Epi>
; __device__ __forceinline__ void gemm_phase(LAS unsigned char* lds, const int tid, const Gemm g, const StaticOrder& S, const Epi& E) {
;     ...
;             const char* a1 = cA + (size_t)(t + 1) * kstep;
;             const char* a2 = last ? nA : cA + (size_t)(t + 2) * kstep; const char* b2 = last ? nB : cB + (size_t)(t + 2) * kstep;
;             const char* a3 = a2 + kstep; const char* b3 = b2 + kstep;
;             if constexpr (Epi::SS_LDS) { if (last) {
;                 const char* sp = (const char*)E.ss + (size_t)cur.pm * (256 * 64) + (size_t)tid * 16;
;                 __builtin_amdgcn_global_load_lds((const unsigned*)sp, (LAS unsigned*)(lds + RS_OFF + ldsw), 16, 0, 0);
;                 __builtin_amdgcn_global_load_lds((const unsigned*)(sp + 8192), (LAS unsigned*)(lds + RS_OFF + 8192 + ldsw), 16, 0, 0); } }
;     ...
;             PG8_LDB(B0, 0, 0); PG8_LDB(B1, 0, 1); PG8_SCHED; PG8_LDA(At, 0, 0); PG8_STAGE(PG8_SA(1, 1), a1 + hstepA, voffA);
;             PG8_WAIT_V(8); PG8_WAIT_L(0); PG8_BAR; PG8_MMA(0, 0, At, B0); PG8_MMA(0, 1, At, B1); PG8_BAR; PG8_SCHED;
;             PG8_LDA(At, 0, 1); PG8_STAGE(PG8_SB(0, 0), b2, voffB); PG8_STAGE(PG8_SB(0, 1), b2 + hstepB, voffB); PG8_STAGE(PG8_SA(0, 0), a2, voffA);
;             PG8_WAIT_V(8); PG8_WAIT_L(0); PG8_BAR; PG8_MMA(1, 0, At, B0); PG8_MMA(1, 1, At, B1); PG8_BAR; PG8_SCHED;
.LBB0_1525:
	ds_read_b128 v[40:43], v217
	ds_read_b128 v[48:51], v217 offset:1024
	ds_read_b128 v[52:55], v217 offset:2048
	ds_read_b128 v[60:63], v217 offset:3072
	ds_read_b128 v[64:67], v218
	ds_read_b128 v[68:71], v218 offset:1024
	ds_read_b128 v[80:83], v218 offset:2048
	ds_read_b128 v[100:103], v218 offset:3072
	s_add_i32 s64, s38, 2
	s_add_u32 s39, s36, 0xfffc0080
	s_addc_u32 s40, s37, -1
	s_cmp_eq_u32 s55, s38
	s_cselect_b32 s38, s61, s62
	s_cselect_b32 s41, s27, s40
	s_cselect_b32 s40, s29, s39
	s_cselect_b32 s39, s33, s63
	v_lshl_add_u64 v[208:209], s[36:37], 0, v[190:191]
	s_add_i32 m0, s47, 0xc000
	ds_read_b128 v[120:123], v219
	ds_read_b128 v[140:143], v219 offset:1024
	ds_read_b128 v[160:163], v219 offset:2048
	ds_read_b128 v[172:175], v219 offset:3072
	ds_read_b128 v[176:179], v219 offset:4096
	ds_read_b128 v[196:199], v219 offset:5120
	ds_read_b128 v[200:203], v219 offset:6144
	ds_read_b128 v[204:207], v219 offset:7168
	global_load_lds_dwordx4 v[208:209], off
	v_lshl_add_u64 v[208:209], s[36:37], 0, v[188:189]
	s_add_i32 m0, s47, 0xe000
	s_nop 0
	global_load_lds_dwordx4 v[208:209], off
	s_waitcnt vmcnt(8)
	s_waitcnt lgkmcnt(0)
	s_barrier
	v_mfma_f32_16x16x32_bf16 v[168:171], v[40:43], v[120:123], v[168:171]
	v_mfma_f32_16x16x32_bf16 v[156:159], v[52:55], v[120:123], v[156:159]
	v_mfma_f32_16x16x32_bf16 v[148:151], v[40:43], v[160:163], v[148:151]
	v_mfma_f32_16x16x32_bf16 v[136:139], v[52:55], v[160:163], v[136:139]
	v_mfma_f32_16x16x32_bf16 v[128:131], v[40:43], v[176:179], v[128:131]
	v_mfma_f32_16x16x32_bf16 v[116:119], v[52:55], v[176:179], v[116:119]
	v_mfma_f32_16x16x32_bf16 v[108:111], v[40:43], v[200:203], v[108:111]
	v_mfma_f32_16x16x32_bf16 v[96:99], v[52:55], v[200:203], v[96:99]
	v_mfma_f32_16x16x32_bf16 v[168:171], v[48:51], v[140:143], v[168:171]
	v_mfma_f32_16x16x32_bf16 v[156:159], v[60:63], v[140:143], v[156:159]
	v_mfma_f32_16x16x32_bf16 v[148:151], v[48:51], v[172:175], v[148:151]
	v_mfma_f32_16x16x32_bf16 v[136:139], v[60:63], v[172:175], v[136:139]
	v_mfma_f32_16x16x32_bf16 v[128:131], v[48:51], v[196:199], v[128:131]
	v_mfma_f32_16x16x32_bf16 v[116:119], v[60:63], v[196:199], v[116:119]
	v_mfma_f32_16x16x32_bf16 v[108:111], v[48:51], v[204:207], v[108:111]
	v_mfma_f32_16x16x32_bf16 v[96:99], v[60:63], v[204:207], v[96:99]
	v_mfma_f32_16x16x32_bf16 v[164:167], v[64:67], v[120:123], v[164:167]
	v_mfma_f32_16x16x32_bf16 v[120:123], v[80:83], v[120:123], v[152:155]
	v_mfma_f32_16x16x32_bf16 v[132:135], v[80:83], v[160:163], v[132:135]
	v_mfma_f32_16x16x32_bf16 v[124:127], v[64:67], v[176:179], v[124:127]
	v_mfma_f32_16x16x32_bf16 v[112:115], v[80:83], v[176:179], v[112:115]
	v_mfma_f32_16x16x32_bf16 v[104:107], v[64:67], v[200:203], v[104:107]
	v_mfma_f32_16x16x32_bf16 v[92:95], v[80:83], v[200:203], v[92:95]
	v_mfma_f32_16x16x32_bf16 v[164:167], v[68:71], v[140:143], v[164:167]
	v_mfma_f32_16x16x32_bf16 v[120:123], v[100:103], v[140:143], v[120:123]
	v_mfma_f32_16x16x32_bf16 v[140:143], v[64:67], v[160:163], v[144:147]
	v_mfma_f32_16x16x32_bf16 v[132:135], v[100:103], v[172:175], v[132:135]
	v_mfma_f32_16x16x32_bf16 v[124:127], v[68:71], v[196:199], v[124:127]
	v_mfma_f32_16x16x32_bf16 v[112:115], v[100:103], v[196:199], v[112:115]
	v_mfma_f32_16x16x32_bf16 v[104:107], v[68:71], v[204:207], v[104:107]
	v_mfma_f32_16x16x32_bf16 v[92:95], v[100:103], v[204:207], v[92:95]
	v_mfma_f32_16x16x32_bf16 v[140:143], v[68:71], v[172:175], v[140:143]
	s_barrier
	s_add_i32 s65, s57, s46
	v_lshl_add_u64 v[212:213], s[38:39], 0, v[182:183]
	s_mov_b32 m0, s65
	ds_read_b128 v[144:147], v219 offset:16384
	ds_read_b128 v[152:155], v219 offset:17408
	ds_read_b128 v[160:163], v219 offset:18432
	ds_read_b128 v[172:175], v219 offset:19456
	ds_read_b128 v[176:179], v219 offset:20480
	ds_read_b128 v[196:199], v219 offset:21504
	ds_read_b128 v[200:203], v219 offset:22528
	ds_read_b128 v[204:207], v219 offset:23552
	global_load_lds_dwordx4 v[212:213], off
	s_add_i32 m0, s65, 0x2000
	s_add_u32 s66, s38, 0x10000
	v_lshl_add_u64 v[226:227], s[38:39], 0, v[186:187]
	s_addc_u32 s67, s39, 0
	s_add_i32 s65, s58, s46
	global_load_lds_dwordx4 v[226:227], off
	v_lshl_add_u64 v[208:209], s[66:67], 0, v[182:183]
	s_mov_b32 m0, s65
	v_lshl_add_u64 v[228:229], s[40:41], 0, v[180:181]
	global_load_lds_dwordx4 v[208:209], off
	v_lshl_add_u64 v[208:209], s[66:67], 0, v[186:187]
	s_add_i32 m0, s65, 0x2000
	v_lshl_add_u64 v[230:231], s[40:41], 0, v[184:185]
	global_load_lds_dwordx4 v[208:209], off
	s_mov_b32 m0, s47
	s_nop 0
	global_load_lds_dwordx4 v[228:229], off
	s_mov_b32 m0, s48
	s_nop 0
	global_load_lds_dwordx4 v[230:231], off
	s_waitcnt vmcnt(8)
	s_waitcnt lgkmcnt(0)
	s_barrier
; #define PG8_STAGE(bufoff, gbase, voff) do { _Pragma("unroll") for (int _i = 0; _i < 2; ++_i) \
;         __builtin_amdgcn_global_load_lds((const unsigned*)((const char*)(gbase) + (voff)[_i]), (LAS unsigned*)(lds + (bufoff) + ldsw + _i * 8192), 16, 0, 0); } while (0)
; #define PG8_LDA(dst, b, h) do { _Pragma("unroll") for (int m = 0; m < 4; ++m) _Pragma("unroll") for (int k = 0; k < 2; ++k) dst[m][k] = *(const LAS bf16x8*)(lds + PG8_SA(b, h) + aoff + m * 2048 + k * 1024); } while (0)
; #define PG8_LDB(dst, b, h) do { _Pragma("unroll") for (int n = 0; n < 2; ++n) _Pragma("unroll") for (int k = 0; k < 2; ++k) dst[n][k] = *(const LAS bf16x8*)(lds + PG8_SB(b, h) + boff + n * 2048 + k * 1024); } while (0)
; #define PG8_MMA(ai, bj, At, Bt) do { __builtin_amdgcn_s_setprio(1); _Pragma("unroll") for (int m = 0; m < 4; ++m) _Pragma("unroll") for (int n = 0; n < 2; ++n) _Pragma("unroll") for (int k = 0; k < 2; ++k) \
;         acc[ai][bj][m][n] = __builtin_amdgcn_mfma_f32_16x16x32_bf16(Bt[n][k], At[m][k], acc[ai][bj][m][n], 0, 0, 0); __builtin_amdgcn_s_setprio(0); } while (0)
; #define PG8_WAIT_V(n) asm volatile("s_waitcnt vmcnt(" #n ")" ::: "memory")
; #define PG8_WAIT_L(n) asm volatile("s_waitcnt lgkmcnt(" #n ")" ::: "memory")
; #define PG8_BAR __builtin_amdgcn_s_barrier()
; #define PG8_SCHED __builtin_amdgcn_sched_barrier(0)
; template <class Epi>
; __device__ __forceinline__ void gemm_phase(LAS unsigned char* lds, const int tid, const Gemm g, const StaticOrder& S, const Epi& E) {
;     ...
;             PG8_WAIT_V(8); PG8_WAIT_L(0); PG8_BAR; PG8_MMA(1, 0, At, B0); PG8_MMA(1, 1, At, B1); PG8_BAR; PG8_SCHED;
;             PG8_LDB(B0, 1, 0); PG8_LDB(B1, 1, 1); PG8_SCHED; PG8_LDA(At, 1, 0); PG8_STAGE(PG8_SA(0, 1), a2 + hstepA, voffA);
;             PG8_WAIT_V(8); PG8_WAIT_L(0); PG8_BAR; PG8_MMA(0, 0, At, B0); PG8_MMA(0, 1, At, B1); PG8_BAR; PG8_SCHED;
	v_mfma_f32_16x16x32_bf16 v[88:91], v[40:43], v[144:147], v[88:91]
	v_mfma_f32_16x16x32_bf16 v[76:79], v[52:55], v[144:147], v[76:79]
	v_mfma_f32_16x16x32_bf16 v[56:59], v[40:43], v[160:163], v[56:59]
	v_mfma_f32_16x16x32_bf16 v[36:39], v[52:55], v[160:163], v[36:39]
	v_mfma_f32_16x16x32_bf16 v[28:31], v[40:43], v[176:179], v[28:31]
	v_mfma_f32_16x16x32_bf16 v[20:23], v[52:55], v[176:179], v[20:23]
	v_mfma_f32_16x16x32_bf16 v[12:15], v[40:43], v[200:203], v[12:15]
	v_mfma_f32_16x16x32_bf16 v[4:7], v[52:55], v[200:203], v[4:7]
	v_mfma_f32_16x16x32_bf16 v[88:91], v[48:51], v[152:155], v[88:91]
	v_mfma_f32_16x16x32_bf16 v[76:79], v[60:63], v[152:155], v[76:79]
	v_mfma_f32_16x16x32_bf16 v[56:59], v[48:51], v[172:175], v[56:59]
	v_mfma_f32_16x16x32_bf16 v[36:39], v[60:63], v[172:175], v[36:39]
	v_mfma_f32_16x16x32_bf16 v[28:31], v[48:51], v[196:199], v[28:31]
	v_mfma_f32_16x16x32_bf16 v[20:23], v[60:63], v[196:199], v[20:23]
	v_mfma_f32_16x16x32_bf16 v[12:15], v[48:51], v[204:207], v[12:15]
	v_mfma_f32_16x16x32_bf16 v[4:7], v[60:63], v[204:207], v[4:7]
	v_mfma_f32_16x16x32_bf16 v[44:47], v[64:67], v[160:163], v[44:47]
	v_mfma_f32_16x16x32_bf16 v[32:35], v[80:83], v[160:163], v[32:35]
	v_mfma_f32_16x16x32_bf16 v[24:27], v[64:67], v[176:179], v[24:27]
	v_mfma_f32_16x16x32_bf16 v[16:19], v[80:83], v[176:179], v[16:19]
	v_mfma_f32_16x16x32_bf16 v[8:11], v[64:67], v[200:203], v[8:11]
	v_mfma_f32_16x16x32_bf16 v[0:3], v[80:83], v[200:203], v[0:3]
	v_mfma_f32_16x16x32_bf16 v[40:43], v[64:67], v[144:147], v[84:87]
	v_mfma_f32_16x16x32_bf16 v[48:51], v[80:83], v[144:147], v[72:75]
	v_mfma_f32_16x16x32_bf16 v[44:47], v[68:71], v[172:175], v[44:47]
	v_mfma_f32_16x16x32_bf16 v[32:35], v[100:103], v[172:175], v[32:35]
	v_mfma_f32_16x16x32_bf16 v[24:27], v[68:71], v[196:199], v[24:27]
	v_mfma_f32_16x16x32_bf16 v[16:19], v[100:103], v[196:199], v[16:19]
	v_mfma_f32_16x16x32_bf16 v[8:11], v[68:71], v[204:207], v[8:11]
	v_mfma_f32_16x16x32_bf16 v[0:3], v[100:103], v[204:207], v[0:3]
	v_mfma_f32_16x16x32_bf16 v[40:43], v[68:71], v[152:155], v[40:43]
	v_mfma_f32_16x16x32_bf16 v[48:51], v[100:103], v[152:155], v[48:51]
	s_barrier
	s_add_i32 s65, 0, 0x18000
	s_add_i32 s66, 0, 0x1c000
	v_add_u32_e32 v68, s65, v215
	v_add_u32_e32 v72, s66, v215
	ds_read_b128 v[52:55], v68
	ds_read_b128 v[60:63], v68 offset:1024
	ds_read_b128 v[64:67], v68 offset:2048
	ds_read_b128 v[68:71], v68 offset:3072
	ds_read_b128 v[80:83], v72
	ds_read_b128 v[100:103], v72 offset:1024
	ds_read_b128 v[160:163], v72 offset:2048
	ds_read_b128 v[172:175], v72 offset:3072
	s_add_u32 s40, s40, 0x40000
	s_addc_u32 s41, s41, 0
	s_mov_b32 m0, s49
	v_lshl_add_u64 v[144:145], s[40:41], 0, v[180:181]
	ds_read_b128 v[72:75], v219 offset:32768
	ds_read_b128 v[84:87], v219 offset:33792
	ds_read_b128 v[176:179], v219 offset:34816
	ds_read_b128 v[196:199], v219 offset:35840
	ds_read_b128 v[200:203], v219 offset:36864
	ds_read_b128 v[204:207], v219 offset:37888
	ds_read_b128 v[208:211], v219 offset:38912
	ds_read_b128 v[222:225], v219 offset:39936
	global_load_lds_dwordx4 v[144:145], off
	v_lshl_add_u64 v[144:145], s[40:41], 0, v[184:185]
	s_mov_b32 m0, s50
	s_nop 0
	global_load_lds_dwordx4 v[144:145], off
	s_waitcnt vmcnt(8)
	s_waitcnt lgkmcnt(0)
	s_barrier
	v_mfma_f32_16x16x32_bf16 v[144:147], v[52:55], v[72:75], v[168:171]
	v_mfma_f32_16x16x32_bf16 v[168:171], v[60:63], v[84:87], v[144:147]
	v_mfma_f32_16x16x32_bf16 v[144:147], v[64:67], v[72:75], v[156:159]
	v_mfma_f32_16x16x32_bf16 v[156:159], v[68:71], v[84:87], v[144:147]
	v_mfma_f32_16x16x32_bf16 v[144:147], v[52:55], v[176:179], v[148:151]
	v_mfma_f32_16x16x32_bf16 v[136:139], v[64:67], v[176:179], v[136:139]
	v_mfma_f32_16x16x32_bf16 v[128:131], v[52:55], v[200:203], v[128:131]
	v_mfma_f32_16x16x32_bf16 v[116:119], v[64:67], v[200:203], v[116:119]
	v_mfma_f32_16x16x32_bf16 v[108:111], v[52:55], v[208:211], v[108:111]
	v_mfma_f32_16x16x32_bf16 v[96:99], v[64:67], v[208:211], v[96:99]
	v_mfma_f32_16x16x32_bf16 v[148:151], v[60:63], v[196:199], v[144:147]
	v_mfma_f32_16x16x32_bf16 v[136:139], v[68:71], v[196:199], v[136:139]
	v_mfma_f32_16x16x32_bf16 v[128:131], v[60:63], v[204:207], v[128:131]
	v_mfma_f32_16x16x32_bf16 v[116:119], v[68:71], v[204:207], v[116:119]
	v_mfma_f32_16x16x32_bf16 v[108:111], v[60:63], v[222:225], v[108:111]
	v_mfma_f32_16x16x32_bf16 v[96:99], v[68:71], v[222:225], v[96:99]
	v_mfma_f32_16x16x32_bf16 v[144:147], v[80:83], v[72:75], v[164:167]
	v_mfma_f32_16x16x32_bf16 v[72:75], v[160:163], v[72:75], v[120:123]
	v_mfma_f32_16x16x32_bf16 v[152:155], v[172:175], v[84:87], v[72:75]
	v_mfma_f32_16x16x32_bf16 v[72:75], v[80:83], v[176:179], v[140:143]
	v_mfma_f32_16x16x32_bf16 v[164:167], v[100:103], v[84:87], v[144:147]
	v_mfma_f32_16x16x32_bf16 v[144:147], v[100:103], v[196:199], v[72:75]
	v_mfma_f32_16x16x32_bf16 v[72:75], v[160:163], v[176:179], v[132:135]
	v_mfma_f32_16x16x32_bf16 v[132:135], v[172:175], v[196:199], v[72:75]
	v_mfma_f32_16x16x32_bf16 v[72:75], v[80:83], v[200:203], v[124:127]
	v_mfma_f32_16x16x32_bf16 v[124:127], v[100:103], v[204:207], v[72:75]
	v_mfma_f32_16x16x32_bf16 v[72:75], v[160:163], v[200:203], v[112:115]
	v_mfma_f32_16x16x32_bf16 v[112:115], v[172:175], v[204:207], v[72:75]
	v_mfma_f32_16x16x32_bf16 v[72:75], v[80:83], v[208:211], v[104:107]
	v_mfma_f32_16x16x32_bf16 v[104:107], v[100:103], v[222:225], v[72:75]
	v_mfma_f32_16x16x32_bf16 v[72:75], v[160:163], v[208:211], v[92:95]
	v_mfma_f32_16x16x32_bf16 v[92:95], v[172:175], v[222:225], v[72:75]
	s_barrier
; #define PG8_STAGE(bufoff, gbase, voff) do { _Pragma("unroll") for (int _i = 0; _i < 2; ++_i) \
;         __builtin_amdgcn_global_load_lds((const unsigned*)((const char*)(gbase) + (voff)[_i]), (LAS unsigned*)(lds + (bufoff) + ldsw + _i * 8192), 16, 0, 0); } while (0)
; #define PG8_LDA(dst, b, h) do { _Pragma("unroll") for (int m = 0; m < 4; ++m) _Pragma("unroll") for (int k = 0; k < 2; ++k) dst[m][k] = *(const LAS bf16x8*)(lds + PG8_SA(b, h) + aoff + m * 2048 + k * 1024); } while (0)
; #define PG8_MMA(ai, bj, At, Bt) do { __builtin_amdgcn_s_setprio(1); _Pragma("unroll") for (int m = 0; m < 4; ++m) _Pragma("unroll") for (int n = 0; n < 2; ++n) _Pragma("unroll") for (int k = 0; k < 2; ++k) \
;         acc[ai][bj][m][n] = __builtin_amdgcn_mfma_f32_16x16x32_bf16(Bt[n][k], At[m][k], acc[ai][bj][m][n], 0, 0, 0); __builtin_amdgcn_s_setprio(0); } while (0)
; #define PG8_WAIT_V(n) asm volatile("s_waitcnt vmcnt(" #n ")" ::: "memory")
; #define PG8_WAIT_L(n) asm volatile("s_waitcnt lgkmcnt(" #n ")" ::: "memory")
; #define PG8_BAR __builtin_amdgcn_s_barrier()
; #define PG8_SCHED __builtin_amdgcn_sched_barrier(0)
; template <class Epi>
; __device__ __forceinline__ void gemm_phase(LAS unsigned char* lds, const int tid, const Gemm g, const StaticOrder& S, const Epi& E) {
;     ...
;         for (int t = 0; t < nt; t += 2) {
;     ...
;             PG8_LDA(At, 1, 1); PG8_STAGE(PG8_SB(1, 0), b3, voffB); PG8_STAGE(PG8_SB(1, 1), b3 + hstepB, voffB); PG8_STAGE(PG8_SA(1, 0), a3, voffA);
;             PG8_WAIT_V(8); PG8_WAIT_L(0); PG8_BAR; PG8_MMA(1, 0, At, B0); PG8_MMA(1, 1, At, B1); PG8_BAR; PG8_SCHED;
	s_add_i32 s40, s65, s46
	v_lshl_add_u64 v[84:85], v[212:213], 0, s[16:17]
	s_mov_b32 m0, s40
	s_nop 1
	ds_read_b128 v[72:75], v219 offset:49152
	ds_read_b128 v[120:123], v219 offset:50176
	ds_read_b128 v[140:143], v219 offset:51200
	ds_read_b128 v[176:179], v219 offset:52224
	ds_read_b128 v[196:199], v219 offset:53248
	ds_read_b128 v[200:203], v219 offset:54272
	ds_read_b128 v[204:207], v219 offset:55296
	ds_read_b128 v[208:211], v219 offset:56320
	global_load_lds_dwordx4 v[84:85], off
	s_add_i32 m0, s40, 0x2000
	s_add_u32 s38, s38, 0x10080
	v_lshl_add_u64 v[84:85], v[226:227], 0, s[16:17]
	s_addc_u32 s39, s39, 0
	s_add_i32 s40, s66, s46
	global_load_lds_dwordx4 v[84:85], off
	v_lshl_add_u64 v[84:85], s[38:39], 0, v[182:183]
	s_mov_b32 m0, s40
	s_nop 0
	global_load_lds_dwordx4 v[84:85], off
	v_lshl_add_u64 v[84:85], s[38:39], 0, v[186:187]
	s_add_i32 m0, s40, 0x2000
	s_nop 0
	global_load_lds_dwordx4 v[84:85], off
	v_lshl_add_u64 v[84:85], v[228:229], 0, s[16:17]
	s_mov_b32 m0, s53
	s_nop 0
	global_load_lds_dwordx4 v[84:85], off
	v_lshl_add_u64 v[84:85], v[230:231], 0, s[16:17]
	s_mov_b32 m0, s54
	s_nop 0
	global_load_lds_dwordx4 v[84:85], off
	s_waitcnt vmcnt(8)
	s_waitcnt lgkmcnt(0)
	s_barrier
	v_mfma_f32_16x16x32_bf16 v[84:87], v[52:55], v[72:75], v[88:91]
	v_mfma_f32_16x16x32_bf16 v[76:79], v[64:67], v[72:75], v[76:79]
	v_mfma_f32_16x16x32_bf16 v[56:59], v[52:55], v[140:143], v[56:59]
	v_mfma_f32_16x16x32_bf16 v[36:39], v[64:67], v[140:143], v[36:39]
	v_mfma_f32_16x16x32_bf16 v[28:31], v[52:55], v[196:199], v[28:31]
	v_mfma_f32_16x16x32_bf16 v[20:23], v[64:67], v[196:199], v[20:23]
	v_mfma_f32_16x16x32_bf16 v[12:15], v[52:55], v[204:207], v[12:15]
	v_mfma_f32_16x16x32_bf16 v[4:7], v[64:67], v[204:207], v[4:7]
	v_mfma_f32_16x16x32_bf16 v[88:91], v[60:63], v[120:123], v[84:87]
	v_mfma_f32_16x16x32_bf16 v[76:79], v[68:71], v[120:123], v[76:79]
	v_mfma_f32_16x16x32_bf16 v[56:59], v[60:63], v[176:179], v[56:59]
	v_mfma_f32_16x16x32_bf16 v[36:39], v[68:71], v[176:179], v[36:39]
	v_mfma_f32_16x16x32_bf16 v[28:31], v[60:63], v[200:203], v[28:31]
	v_mfma_f32_16x16x32_bf16 v[20:23], v[68:71], v[200:203], v[20:23]
	v_mfma_f32_16x16x32_bf16 v[12:15], v[60:63], v[208:211], v[12:15]
	v_mfma_f32_16x16x32_bf16 v[4:7], v[68:71], v[208:211], v[4:7]
	v_mfma_f32_16x16x32_bf16 v[40:43], v[80:83], v[72:75], v[40:43]
	v_mfma_f32_16x16x32_bf16 v[84:87], v[100:103], v[120:123], v[40:43]
	v_mfma_f32_16x16x32_bf16 v[40:43], v[160:163], v[72:75], v[48:51]
	v_mfma_f32_16x16x32_bf16 v[72:75], v[172:175], v[120:123], v[40:43]
	v_mfma_f32_16x16x32_bf16 v[40:43], v[80:83], v[140:143], v[44:47]
	v_mfma_f32_16x16x32_bf16 v[32:35], v[160:163], v[140:143], v[32:35]
	v_mfma_f32_16x16x32_bf16 v[24:27], v[80:83], v[196:199], v[24:27]
	v_mfma_f32_16x16x32_bf16 v[16:19], v[160:163], v[196:199], v[16:19]
	v_mfma_f32_16x16x32_bf16 v[8:11], v[80:83], v[204:207], v[8:11]
	v_mfma_f32_16x16x32_bf16 v[0:3], v[160:163], v[204:207], v[0:3]
	v_mfma_f32_16x16x32_bf16 v[44:47], v[100:103], v[176:179], v[40:43]
	v_mfma_f32_16x16x32_bf16 v[32:35], v[172:175], v[176:179], v[32:35]
	v_mfma_f32_16x16x32_bf16 v[24:27], v[100:103], v[200:203], v[24:27]
	v_mfma_f32_16x16x32_bf16 v[16:19], v[172:175], v[200:203], v[16:19]
	v_mfma_f32_16x16x32_bf16 v[8:11], v[100:103], v[208:211], v[8:11]
	v_mfma_f32_16x16x32_bf16 v[0:3], v[172:175], v[208:211], v[0:3]
	s_barrier
	s_add_u32 s62, s62, 0x100
	s_addc_u32 s63, s63, 0
	s_add_u32 s36, s36, 0x100
	s_addc_u32 s37, s37, 0
	s_cmp_ge_i32 s64, s52
	s_mov_b32 s38, s64
	s_cbranch_scc0 .LBB0_1525

; #define LAS __attribute__((address_space(3)))
; #define PG8_STAGE(bufoff, gbase, voff) do { _Pragma("unroll") for (int _i = 0; _i < 2; ++_i) \
;         __builtin_amdgcn_global_load_lds((const unsigned*)((const char*)(gbase) + (voff)[_i]), (LAS unsigned*)(lds + (bufoff) + ldsw + _i * 8192), 16, 0, 0); } while (0)
; #define PG8_LDA(dst, b, h) do { _Pragma("unroll") for (int m = 0; m < 4; ++m) _Pragma("unroll") for (int k = 0; k < 2; ++k) dst[m][k] = *(const LAS bf16x8*)(lds + PG8_SA(b, h) + aoff + m * 2048 + k * 1024); } while (0)
; #define PG8_LDB(dst, b, h) do { _Pragma("unroll") for (int n = 0; n < 2; ++n) _Pragma("unroll") for (int k = 0; k < 2; ++k) dst[n][k] = *(const LAS bf16x8*)(lds + PG8_SB(b, h) + boff + n * 2048 + k * 1024); } while (0)
; #define PG8_WAIT_V(n) asm volatile("s_waitcnt vmcnt(" #n ")" ::: "memory")
; #define PG8_WAIT_L(n) asm volatile("s_waitcnt lgkmcnt(" #n ")" ::: "memory")
; #define PG8_BAR __builtin_amdgcn_s_barrier()
; #define PG8_SCHED __builtin_amdgcn_sched_barrier(0)
; template <class Epi>
; __device__ __forceinline__ void gemm_phase(LAS unsigned char* lds, const int tid, const Gemm g, const StaticOrder& S, const Epi& E) {
;     ...
;             const char* a1 = cA + (size_t)(t + 1) * kstep;
;             const char* a2 = last ? nA : cA + (size_t)(t + 2) * kstep; const char* b2 = last ? nB : cB + (size_t)(t + 2) * kstep;
;             const char* a3 = a2 + kstep; const char* b3 = b2 + kstep;
;             if constexpr (Epi::SS_LDS) { if (last) {
;                 const char* sp = (const char*)E.ss + (size_t)cur.pm * (256 * 64) + (size_t)tid * 16;
;                 __builtin_amdgcn_global_load_lds((const unsigned*)sp, (LAS unsigned*)(lds + RS_OFF + ldsw), 16, 0, 0);
;                 __builtin_amdgcn_global_load_lds((const unsigned*)(sp + 8192), (LAS unsigned*)(lds + RS_OFF + 8192 + ldsw), 16, 0, 0); } }
;     ...
;             PG8_LDB(B0, 0, 0); PG8_LDB(B1, 0, 1); PG8_SCHED; PG8_LDA(At, 0, 0); PG8_STAGE(PG8_SA(1, 1), a1 + hstepA, voffA);
;             PG8_WAIT_V(8); PG8_WAIT_L(0); PG8_BAR; PG8_MMA(0, 0, At, B0); PG8_MMA(0, 1, At, B1); PG8_BAR; PG8_SCHED;
;             PG8_LDA(At, 0, 1); PG8_STAGE(PG8_SB(0, 0), b2, voffB); PG8_STAGE(PG8_SB(0, 1), b2 + hstepB, voffB); PG8_STAGE(PG8_SA(0, 0), a2, voffA);
;             PG8_WAIT_V(8); PG8_WAIT_L(0); PG8_BAR; PG8_MMA(1, 0, At, B0); PG8_MMA(1, 1, At, B1); PG8_BAR; PG8_SCHED;
.LBB0_1734:
	ds_read_b128 v[128:131], v189
	ds_read_b128 v[132:135], v189 offset:1024
	ds_read_b128 v[136:139], v189 offset:2048
	ds_read_b128 v[140:143], v189 offset:3072
	ds_read_b128 v[144:147], v190
	ds_read_b128 v[148:151], v190 offset:1024
	ds_read_b128 v[168:171], v190 offset:2048
	ds_read_b128 v[172:175], v190 offset:3072
	s_add_i32 s62, s38, 2
	s_add_u32 s39, s36, 0xfffc0080
	s_addc_u32 s40, s37, -1
	s_cmp_eq_u32 s53, s38
	s_cselect_b32 s38, s59, s60
	s_cselect_b32 s41, s25, s40
	s_cselect_b32 s40, s27, s39
	s_cselect_b32 s39, s35, s61
	v_lshl_add_u64 v[184:185], s[36:37], 0, v[162:163]
	s_add_i32 m0, s45, 0xc000
	ds_read_b128 v[176:179], v191
	ds_read_b128 v[180:183], v191 offset:1024
	ds_read_b128 v[192:195], v191 offset:2048
	ds_read_b128 v[196:199], v191 offset:3072
	ds_read_b128 v[200:203], v191 offset:4096
	ds_read_b128 v[204:207], v191 offset:5120
	ds_read_b128 v[208:211], v191 offset:6144
	ds_read_b128 v[212:215], v191 offset:7168
	global_load_lds_dwordx4 v[184:185], off
	v_lshl_add_u64 v[184:185], s[36:37], 0, v[160:161]
	s_add_i32 m0, s45, 0xe000
	s_nop 0
	global_load_lds_dwordx4 v[184:185], off
	s_waitcnt vmcnt(8)
	s_waitcnt lgkmcnt(0)
	s_barrier
	v_mfma_f32_16x16x32_bf16 v[120:123], v[128:131], v[176:179], v[120:123]
	v_mfma_f32_16x16x32_bf16 v[124:127], v[136:139], v[176:179], v[124:127]
	v_mfma_f32_16x16x32_bf16 v[108:111], v[128:131], v[192:195], v[108:111]
	v_mfma_f32_16x16x32_bf16 v[104:107], v[136:139], v[192:195], v[104:107]
	v_mfma_f32_16x16x32_bf16 v[92:95], v[128:131], v[200:203], v[92:95]
	v_mfma_f32_16x16x32_bf16 v[88:91], v[136:139], v[200:203], v[88:91]
	v_mfma_f32_16x16x32_bf16 v[76:79], v[128:131], v[208:211], v[76:79]
	v_mfma_f32_16x16x32_bf16 v[72:75], v[136:139], v[208:211], v[72:75]
	v_mfma_f32_16x16x32_bf16 v[120:123], v[132:135], v[180:183], v[120:123]
	v_mfma_f32_16x16x32_bf16 v[124:127], v[140:143], v[180:183], v[124:127]
	v_mfma_f32_16x16x32_bf16 v[108:111], v[132:135], v[196:199], v[108:111]
	v_mfma_f32_16x16x32_bf16 v[104:107], v[140:143], v[196:199], v[104:107]
	v_mfma_f32_16x16x32_bf16 v[92:95], v[132:135], v[204:207], v[92:95]
	v_mfma_f32_16x16x32_bf16 v[88:91], v[140:143], v[204:207], v[88:91]
	v_mfma_f32_16x16x32_bf16 v[76:79], v[132:135], v[212:215], v[76:79]
	v_mfma_f32_16x16x32_bf16 v[72:75], v[140:143], v[212:215], v[72:75]
	v_mfma_f32_16x16x32_bf16 v[116:119], v[144:147], v[176:179], v[116:119]
	v_mfma_f32_16x16x32_bf16 v[112:115], v[168:171], v[176:179], v[112:115]
	v_mfma_f32_16x16x32_bf16 v[100:103], v[144:147], v[192:195], v[100:103]
	v_mfma_f32_16x16x32_bf16 v[96:99], v[168:171], v[192:195], v[96:99]
	v_mfma_f32_16x16x32_bf16 v[84:87], v[144:147], v[200:203], v[84:87]
	v_mfma_f32_16x16x32_bf16 v[80:83], v[168:171], v[200:203], v[80:83]
	v_mfma_f32_16x16x32_bf16 v[68:71], v[144:147], v[208:211], v[68:71]
	v_mfma_f32_16x16x32_bf16 v[64:67], v[168:171], v[208:211], v[64:67]
	v_mfma_f32_16x16x32_bf16 v[116:119], v[148:151], v[180:183], v[116:119]
	v_mfma_f32_16x16x32_bf16 v[112:115], v[172:175], v[180:183], v[112:115]
	v_mfma_f32_16x16x32_bf16 v[100:103], v[148:151], v[196:199], v[100:103]
	v_mfma_f32_16x16x32_bf16 v[96:99], v[172:175], v[196:199], v[96:99]
	v_mfma_f32_16x16x32_bf16 v[84:87], v[148:151], v[204:207], v[84:87]
	v_mfma_f32_16x16x32_bf16 v[80:83], v[172:175], v[204:207], v[80:83]
	v_mfma_f32_16x16x32_bf16 v[68:71], v[148:151], v[212:215], v[68:71]
	v_mfma_f32_16x16x32_bf16 v[64:67], v[172:175], v[212:215], v[64:67]
	s_barrier
	s_add_i32 s63, s56, s44
	v_lshl_add_u64 v[184:185], s[38:39], 0, v[154:155]
	s_mov_b32 m0, s63
	ds_read_b128 v[176:179], v191 offset:16384
	ds_read_b128 v[180:183], v191 offset:17408
	ds_read_b128 v[192:195], v191 offset:18432
	ds_read_b128 v[196:199], v191 offset:19456
	ds_read_b128 v[200:203], v191 offset:20480
	ds_read_b128 v[204:207], v191 offset:21504
	ds_read_b128 v[208:211], v191 offset:22528
	ds_read_b128 v[212:215], v191 offset:23552
	global_load_lds_dwordx4 v[184:185], off
	s_add_i32 m0, s63, 0x2000
	s_add_u32 s64, s38, 0x40000
	v_lshl_add_u64 v[216:217], s[38:39], 0, v[158:159]
	s_addc_u32 s65, s39, 0
	s_add_i32 s63, s57, s44
	global_load_lds_dwordx4 v[216:217], off
	v_lshl_add_u64 v[218:219], s[64:65], 0, v[154:155]
	s_mov_b32 m0, s63
	v_lshl_add_u64 v[220:221], s[40:41], 0, v[156:157]
	global_load_lds_dwordx4 v[218:219], off
	v_lshl_add_u64 v[218:219], s[64:65], 0, v[158:159]
	s_add_i32 m0, s63, 0x2000
	s_nop 0
	global_load_lds_dwordx4 v[218:219], off
	v_lshl_add_u64 v[218:219], s[40:41], 0, v[152:153]
	s_mov_b32 m0, s45
	s_nop 0
	global_load_lds_dwordx4 v[218:219], off
	s_mov_b32 m0, s46
	s_nop 0
	global_load_lds_dwordx4 v[220:221], off
	s_waitcnt vmcnt(8)
	s_waitcnt lgkmcnt(0)
	s_barrier
; #define PG8_STAGE(bufoff, gbase, voff) do { _Pragma("unroll") for (int _i = 0; _i < 2; ++_i) \
;         __builtin_amdgcn_global_load_lds((const unsigned*)((const char*)(gbase) + (voff)[_i]), (LAS unsigned*)(lds + (bufoff) + ldsw + _i * 8192), 16, 0, 0); } while (0)
; #define PG8_LDA(dst, b, h) do { _Pragma("unroll") for (int m = 0; m < 4; ++m) _Pragma("unroll") for (int k = 0; k < 2; ++k) dst[m][k] = *(const LAS bf16x8*)(lds + PG8_SA(b, h) + aoff + m * 2048 + k * 1024); } while (0)
; #define PG8_LDB(dst, b, h) do { _Pragma("unroll") for (int n = 0; n < 2; ++n) _Pragma("unroll") for (int k = 0; k < 2; ++k) dst[n][k] = *(const LAS bf16x8*)(lds + PG8_SB(b, h) + boff + n * 2048 + k * 1024); } while (0)
; #define PG8_MMA(ai, bj, At, Bt) do { __builtin_amdgcn_s_setprio(1); _Pragma("unroll") for (int m = 0; m < 4; ++m) _Pragma("unroll") for (int n = 0; n < 2; ++n) _Pragma("unroll") for (int k = 0; k < 2; ++k) \
;         acc[ai][bj][m][n] = __builtin_amdgcn_mfma_f32_16x16x32_bf16(Bt[n][k], At[m][k], acc[ai][bj][m][n], 0, 0, 0); __builtin_amdgcn_s_setprio(0); } while (0)
; #define PG8_WAIT_V(n) asm volatile("s_waitcnt vmcnt(" #n ")" ::: "memory")
; #define PG8_WAIT_L(n) asm volatile("s_waitcnt lgkmcnt(" #n ")" ::: "memory")
; #define PG8_BAR __builtin_amdgcn_s_barrier()
; #define PG8_SCHED __builtin_amdgcn_sched_barrier(0)
; template <class Epi>
; __device__ __forceinline__ void gemm_phase(LAS unsigned char* lds, const int tid, const Gemm g, const StaticOrder& S, const Epi& E) {
;     ...
;             PG8_WAIT_V(8); PG8_WAIT_L(0); PG8_BAR; PG8_MMA(1, 0, At, B0); PG8_MMA(1, 1, At, B1); PG8_BAR; PG8_SCHED;
;             PG8_LDB(B0, 1, 0); PG8_LDB(B1, 1, 1); PG8_SCHED; PG8_LDA(At, 1, 0); PG8_STAGE(PG8_SA(0, 1), a2 + hstepA, voffA);
;             PG8_WAIT_V(8); PG8_WAIT_L(0); PG8_BAR; PG8_MMA(0, 0, At, B0); PG8_MMA(0, 1, At, B1); PG8_BAR; PG8_SCHED;
	v_mfma_f32_16x16x32_bf16 v[60:63], v[128:131], v[176:179], v[60:63]
	v_mfma_f32_16x16x32_bf16 v[56:59], v[136:139], v[176:179], v[56:59]
	v_mfma_f32_16x16x32_bf16 v[44:47], v[128:131], v[192:195], v[44:47]
	v_mfma_f32_16x16x32_bf16 v[40:43], v[136:139], v[192:195], v[40:43]
	v_mfma_f32_16x16x32_bf16 v[28:31], v[128:131], v[200:203], v[28:31]
	v_mfma_f32_16x16x32_bf16 v[24:27], v[136:139], v[200:203], v[24:27]
	v_mfma_f32_16x16x32_bf16 v[12:15], v[128:131], v[208:211], v[12:15]
	v_mfma_f32_16x16x32_bf16 v[8:11], v[136:139], v[208:211], v[8:11]
	v_mfma_f32_16x16x32_bf16 v[60:63], v[132:135], v[180:183], v[60:63]
	v_mfma_f32_16x16x32_bf16 v[56:59], v[140:143], v[180:183], v[56:59]
	v_mfma_f32_16x16x32_bf16 v[44:47], v[132:135], v[196:199], v[44:47]
	v_mfma_f32_16x16x32_bf16 v[40:43], v[140:143], v[196:199], v[40:43]
	v_mfma_f32_16x16x32_bf16 v[28:31], v[132:135], v[204:207], v[28:31]
	v_mfma_f32_16x16x32_bf16 v[24:27], v[140:143], v[204:207], v[24:27]
	v_mfma_f32_16x16x32_bf16 v[12:15], v[132:135], v[212:215], v[12:15]
	v_mfma_f32_16x16x32_bf16 v[8:11], v[140:143], v[212:215], v[8:11]
	v_mfma_f32_16x16x32_bf16 v[52:55], v[144:147], v[176:179], v[52:55]
	v_mfma_f32_16x16x32_bf16 v[48:51], v[168:171], v[176:179], v[48:51]
	v_mfma_f32_16x16x32_bf16 v[36:39], v[144:147], v[192:195], v[36:39]
	v_mfma_f32_16x16x32_bf16 v[32:35], v[168:171], v[192:195], v[32:35]
	v_mfma_f32_16x16x32_bf16 v[20:23], v[144:147], v[200:203], v[20:23]
	v_mfma_f32_16x16x32_bf16 v[16:19], v[168:171], v[200:203], v[16:19]
	v_mfma_f32_16x16x32_bf16 v[4:7], v[144:147], v[208:211], v[4:7]
	v_mfma_f32_16x16x32_bf16 v[0:3], v[168:171], v[208:211], v[0:3]
	v_mfma_f32_16x16x32_bf16 v[52:55], v[148:151], v[180:183], v[52:55]
	v_mfma_f32_16x16x32_bf16 v[48:51], v[172:175], v[180:183], v[48:51]
	v_mfma_f32_16x16x32_bf16 v[36:39], v[148:151], v[196:199], v[36:39]
	v_mfma_f32_16x16x32_bf16 v[32:35], v[172:175], v[196:199], v[32:35]
	v_mfma_f32_16x16x32_bf16 v[20:23], v[148:151], v[204:207], v[20:23]
	v_mfma_f32_16x16x32_bf16 v[16:19], v[172:175], v[204:207], v[16:19]
	v_mfma_f32_16x16x32_bf16 v[4:7], v[148:151], v[212:215], v[4:7]
	v_mfma_f32_16x16x32_bf16 v[0:3], v[172:175], v[212:215], v[0:3]
	s_barrier
	s_add_i32 s63, 0, 0x18000
	s_add_i32 s64, 0, 0x1c000
	v_add_u32_e32 v140, s63, v187
	v_add_u32_e32 v172, s64, v187
	ds_read_b128 v[128:131], v140
	ds_read_b128 v[132:135], v140 offset:1024
	ds_read_b128 v[136:139], v140 offset:2048
	ds_read_b128 v[140:143], v140 offset:3072
	ds_read_b128 v[144:147], v172
	ds_read_b128 v[148:151], v172 offset:1024
	ds_read_b128 v[168:171], v172 offset:2048
	ds_read_b128 v[172:175], v172 offset:3072
	s_add_u32 s40, s40, 0x40000
	s_addc_u32 s41, s41, 0
	s_mov_b32 m0, s47
	v_lshl_add_u64 v[222:223], s[40:41], 0, v[152:153]
	ds_read_b128 v[176:179], v191 offset:32768
	ds_read_b128 v[180:183], v191 offset:33792
	ds_read_b128 v[192:195], v191 offset:34816
	ds_read_b128 v[196:199], v191 offset:35840
	ds_read_b128 v[200:203], v191 offset:36864
	ds_read_b128 v[204:207], v191 offset:37888
	ds_read_b128 v[208:211], v191 offset:38912
	ds_read_b128 v[212:215], v191 offset:39936
	global_load_lds_dwordx4 v[222:223], off
	v_lshl_add_u64 v[222:223], s[40:41], 0, v[156:157]
	s_mov_b32 m0, s48
	s_nop 0
	global_load_lds_dwordx4 v[222:223], off
	s_waitcnt vmcnt(8)
	s_waitcnt lgkmcnt(0)
	s_barrier
	v_mfma_f32_16x16x32_bf16 v[120:123], v[128:131], v[176:179], v[120:123]
	v_mfma_f32_16x16x32_bf16 v[124:127], v[136:139], v[176:179], v[124:127]
	v_mfma_f32_16x16x32_bf16 v[108:111], v[128:131], v[192:195], v[108:111]
	v_mfma_f32_16x16x32_bf16 v[104:107], v[136:139], v[192:195], v[104:107]
	v_mfma_f32_16x16x32_bf16 v[92:95], v[128:131], v[200:203], v[92:95]
	v_mfma_f32_16x16x32_bf16 v[88:91], v[136:139], v[200:203], v[88:91]
	v_mfma_f32_16x16x32_bf16 v[76:79], v[128:131], v[208:211], v[76:79]
	v_mfma_f32_16x16x32_bf16 v[72:75], v[136:139], v[208:211], v[72:75]
	v_mfma_f32_16x16x32_bf16 v[120:123], v[132:135], v[180:183], v[120:123]
	v_mfma_f32_16x16x32_bf16 v[124:127], v[140:143], v[180:183], v[124:127]
	v_mfma_f32_16x16x32_bf16 v[108:111], v[132:135], v[196:199], v[108:111]
	v_mfma_f32_16x16x32_bf16 v[104:107], v[140:143], v[196:199], v[104:107]
	v_mfma_f32_16x16x32_bf16 v[92:95], v[132:135], v[204:207], v[92:95]
	v_mfma_f32_16x16x32_bf16 v[88:91], v[140:143], v[204:207], v[88:91]
	v_mfma_f32_16x16x32_bf16 v[76:79], v[132:135], v[212:215], v[76:79]
	v_mfma_f32_16x16x32_bf16 v[72:75], v[140:143], v[212:215], v[72:75]
	v_mfma_f32_16x16x32_bf16 v[116:119], v[144:147], v[176:179], v[116:119]
	v_mfma_f32_16x16x32_bf16 v[112:115], v[168:171], v[176:179], v[112:115]
	v_mfma_f32_16x16x32_bf16 v[100:103], v[144:147], v[192:195], v[100:103]
	v_mfma_f32_16x16x32_bf16 v[96:99], v[168:171], v[192:195], v[96:99]
	v_mfma_f32_16x16x32_bf16 v[84:87], v[144:147], v[200:203], v[84:87]
	v_mfma_f32_16x16x32_bf16 v[80:83], v[168:171], v[200:203], v[80:83]
	v_mfma_f32_16x16x32_bf16 v[68:71], v[144:147], v[208:211], v[68:71]
	v_mfma_f32_16x16x32_bf16 v[64:67], v[168:171], v[208:211], v[64:67]
	v_mfma_f32_16x16x32_bf16 v[116:119], v[148:151], v[180:183], v[116:119]
	v_mfma_f32_16x16x32_bf16 v[112:115], v[172:175], v[180:183], v[112:115]
	v_mfma_f32_16x16x32_bf16 v[100:103], v[148:151], v[196:199], v[100:103]
	v_mfma_f32_16x16x32_bf16 v[96:99], v[172:175], v[196:199], v[96:99]
	v_mfma_f32_16x16x32_bf16 v[84:87], v[148:151], v[204:207], v[84:87]
	v_mfma_f32_16x16x32_bf16 v[80:83], v[172:175], v[204:207], v[80:83]
	v_mfma_f32_16x16x32_bf16 v[68:71], v[148:151], v[212:215], v[68:71]
	v_mfma_f32_16x16x32_bf16 v[64:67], v[172:175], v[212:215], v[64:67]
	s_barrier
; #define PG8_STAGE(bufoff, gbase, voff) do { _Pragma("unroll") for (int _i = 0; _i < 2; ++_i) \
;         __builtin_amdgcn_global_load_lds((const unsigned*)((const char*)(gbase) + (voff)[_i]), (LAS unsigned*)(lds + (bufoff) + ldsw + _i * 8192), 16, 0, 0); } while (0)
; #define PG8_LDA(dst, b, h) do { _Pragma("unroll") for (int m = 0; m < 4; ++m) _Pragma("unroll") for (int k = 0; k < 2; ++k) dst[m][k] = *(const LAS bf16x8*)(lds + PG8_SA(b, h) + aoff + m * 2048 + k * 1024); } while (0)
; #define PG8_MMA(ai, bj, At, Bt) do { __builtin_amdgcn_s_setprio(1); _Pragma("unroll") for (int m = 0; m < 4; ++m) _Pragma("unroll") for (int n = 0; n < 2; ++n) _Pragma("unroll") for (int k = 0; k < 2; ++k) \
;         acc[ai][bj][m][n] = __builtin_amdgcn_mfma_f32_16x16x32_bf16(Bt[n][k], At[m][k], acc[ai][bj][m][n], 0, 0, 0); __builtin_amdgcn_s_setprio(0); } while (0)
; #define PG8_WAIT_V(n) asm volatile("s_waitcnt vmcnt(" #n ")" ::: "memory")
; #define PG8_WAIT_L(n) asm volatile("s_waitcnt lgkmcnt(" #n ")" ::: "memory")
; #define PG8_BAR __builtin_amdgcn_s_barrier()
; #define PG8_SCHED __builtin_amdgcn_sched_barrier(0)
; template <class Epi>
; __device__ __forceinline__ void gemm_phase(LAS unsigned char* lds, const int tid, const Gemm g, const StaticOrder& S, const Epi& E) {
;     ...
;         for (int t = 0; t < nt; t += 2) {
;     ...
;             PG8_LDA(At, 1, 1); PG8_STAGE(PG8_SB(1, 0), b3, voffB); PG8_STAGE(PG8_SB(1, 1), b3 + hstepB, voffB); PG8_STAGE(PG8_SA(1, 0), a3, voffA);
;             PG8_WAIT_V(8); PG8_WAIT_L(0); PG8_BAR; PG8_MMA(1, 0, At, B0); PG8_MMA(1, 1, At, B1); PG8_BAR; PG8_SCHED;
	s_add_i32 s40, s63, s44
	v_lshl_add_u64 v[184:185], v[184:185], 0, s[18:19]
	s_mov_b32 m0, s40
	ds_read_b128 v[176:179], v191 offset:49152
	ds_read_b128 v[180:183], v191 offset:50176
	ds_read_b128 v[192:195], v191 offset:51200
	ds_read_b128 v[196:199], v191 offset:52224
	ds_read_b128 v[200:203], v191 offset:53248
	ds_read_b128 v[204:207], v191 offset:54272
	ds_read_b128 v[208:211], v191 offset:55296
	ds_read_b128 v[212:215], v191 offset:56320
	global_load_lds_dwordx4 v[184:185], off
	s_add_i32 m0, s40, 0x2000
	s_add_u32 s38, s38, 0x40080
	v_lshl_add_u64 v[184:185], v[216:217], 0, s[18:19]
	s_addc_u32 s39, s39, 0
	s_add_i32 s40, s64, s44
	global_load_lds_dwordx4 v[184:185], off
	v_lshl_add_u64 v[184:185], s[38:39], 0, v[154:155]
	s_mov_b32 m0, s40
	s_nop 0
	global_load_lds_dwordx4 v[184:185], off
	v_lshl_add_u64 v[184:185], s[38:39], 0, v[158:159]
	s_add_i32 m0, s40, 0x2000
	s_nop 0
	global_load_lds_dwordx4 v[184:185], off
	v_lshl_add_u64 v[184:185], v[218:219], 0, s[18:19]
	s_mov_b32 m0, s51
	s_nop 0
	global_load_lds_dwordx4 v[184:185], off
	v_lshl_add_u64 v[184:185], v[220:221], 0, s[18:19]
	s_mov_b32 m0, s52
	s_nop 0
	global_load_lds_dwordx4 v[184:185], off
	s_waitcnt vmcnt(8)
	s_waitcnt lgkmcnt(0)
	s_barrier
	v_mfma_f32_16x16x32_bf16 v[60:63], v[128:131], v[176:179], v[60:63]
	v_mfma_f32_16x16x32_bf16 v[56:59], v[136:139], v[176:179], v[56:59]
	v_mfma_f32_16x16x32_bf16 v[44:47], v[128:131], v[192:195], v[44:47]
	v_mfma_f32_16x16x32_bf16 v[40:43], v[136:139], v[192:195], v[40:43]
	v_mfma_f32_16x16x32_bf16 v[28:31], v[128:131], v[200:203], v[28:31]
	v_mfma_f32_16x16x32_bf16 v[24:27], v[136:139], v[200:203], v[24:27]
	v_mfma_f32_16x16x32_bf16 v[12:15], v[128:131], v[208:211], v[12:15]
	v_mfma_f32_16x16x32_bf16 v[8:11], v[136:139], v[208:211], v[8:11]
	v_mfma_f32_16x16x32_bf16 v[60:63], v[132:135], v[180:183], v[60:63]
	v_mfma_f32_16x16x32_bf16 v[56:59], v[140:143], v[180:183], v[56:59]
	v_mfma_f32_16x16x32_bf16 v[44:47], v[132:135], v[196:199], v[44:47]
	v_mfma_f32_16x16x32_bf16 v[40:43], v[140:143], v[196:199], v[40:43]
	v_mfma_f32_16x16x32_bf16 v[28:31], v[132:135], v[204:207], v[28:31]
	v_mfma_f32_16x16x32_bf16 v[24:27], v[140:143], v[204:207], v[24:27]
	v_mfma_f32_16x16x32_bf16 v[12:15], v[132:135], v[212:215], v[12:15]
	v_mfma_f32_16x16x32_bf16 v[8:11], v[140:143], v[212:215], v[8:11]
	v_mfma_f32_16x16x32_bf16 v[52:55], v[144:147], v[176:179], v[52:55]
	v_mfma_f32_16x16x32_bf16 v[48:51], v[168:171], v[176:179], v[48:51]
	v_mfma_f32_16x16x32_bf16 v[36:39], v[144:147], v[192:195], v[36:39]
	v_mfma_f32_16x16x32_bf16 v[32:35], v[168:171], v[192:195], v[32:35]
	v_mfma_f32_16x16x32_bf16 v[20:23], v[144:147], v[200:203], v[20:23]
	v_mfma_f32_16x16x32_bf16 v[16:19], v[168:171], v[200:203], v[16:19]
	v_mfma_f32_16x16x32_bf16 v[4:7], v[144:147], v[208:211], v[4:7]
	v_mfma_f32_16x16x32_bf16 v[0:3], v[168:171], v[208:211], v[0:3]
	v_mfma_f32_16x16x32_bf16 v[52:55], v[148:151], v[180:183], v[52:55]
	v_mfma_f32_16x16x32_bf16 v[48:51], v[172:175], v[180:183], v[48:51]
	v_mfma_f32_16x16x32_bf16 v[36:39], v[148:151], v[196:199], v[36:39]
	v_mfma_f32_16x16x32_bf16 v[32:35], v[172:175], v[196:199], v[32:35]
	v_mfma_f32_16x16x32_bf16 v[20:23], v[148:151], v[204:207], v[20:23]
	v_mfma_f32_16x16x32_bf16 v[16:19], v[172:175], v[204:207], v[16:19]
	v_mfma_f32_16x16x32_bf16 v[4:7], v[148:151], v[212:215], v[4:7]
	v_mfma_f32_16x16x32_bf16 v[0:3], v[172:175], v[212:215], v[0:3]
	s_barrier
	s_add_u32 s60, s60, 0x100
	s_addc_u32 s61, s61, 0
	s_add_u32 s36, s36, 0x100
	s_addc_u32 s37, s37, 0
	s_cmp_ge_i32 s62, s50
	s_mov_b32 s38, s62
	s_cbranch_scc0 .LBB0_1734

; #define LAS __attribute__((address_space(3)))
; #define PG8_STAGE(bufoff, gbase, voff) do { _Pragma("unroll") for (int _i = 0; _i < 2; ++_i) \
;         __builtin_amdgcn_global_load_lds((const unsigned*)((const char*)(gbase) + (voff)[_i]), (LAS unsigned*)(lds + (bufoff) + ldsw + _i * 8192), 16, 0, 0); } while (0)
; #define PG8_LDA(dst, b, h) do { _Pragma("unroll") for (int m = 0; m < 4; ++m) _Pragma("unroll") for (int k = 0; k < 2; ++k) dst[m][k] = *(const LAS bf16x8*)(lds + PG8_SA(b, h) + aoff + m * 2048 + k * 1024); } while (0)
; #define PG8_LDB(dst, b, h) do { _Pragma("unroll") for (int n = 0; n < 2; ++n) _Pragma("unroll") for (int k = 0; k < 2; ++k) dst[n][k] = *(const LAS bf16x8*)(lds + PG8_SB(b, h) + boff + n * 2048 + k * 1024); } while (0)
; #define PG8_WAIT_V(n) asm volatile("s_waitcnt vmcnt(" #n ")" ::: "memory")
; #define PG8_WAIT_L(n) asm volatile("s_waitcnt lgkmcnt(" #n ")" ::: "memory")
; #define PG8_BAR __builtin_amdgcn_s_barrier()
; #define PG8_SCHED __builtin_amdgcn_sched_barrier(0)
; template <class Epi>
; __device__ __forceinline__ void gemm_phase(LAS unsigned char* lds, const int tid, const Gemm g, const StaticOrder& S, const Epi& E) {
;     ...
;             const char* a1 = cA + (size_t)(t + 1) * kstep;
;             const char* a2 = last ? nA : cA + (size_t)(t + 2) * kstep; const char* b2 = last ? nB : cB + (size_t)(t + 2) * kstep;
;             const char* a3 = a2 + kstep; const char* b3 = b2 + kstep;
;             if constexpr (Epi::SS_LDS) { if (last) {
;                 const char* sp = (const char*)E.ss + (size_t)cur.pm * (256 * 64) + (size_t)tid * 16;
;                 __builtin_amdgcn_global_load_lds((const unsigned*)sp, (LAS unsigned*)(lds + RS_OFF + ldsw), 16, 0, 0);
;                 __builtin_amdgcn_global_load_lds((const unsigned*)(sp + 8192), (LAS unsigned*)(lds + RS_OFF + 8192 + ldsw), 16, 0, 0); } }
;     ...
;             PG8_LDB(B0, 0, 0); PG8_LDB(B1, 0, 1); PG8_SCHED; PG8_LDA(At, 0, 0); PG8_STAGE(PG8_SA(1, 1), a1 + hstepA, voffA);
;             PG8_WAIT_V(8); PG8_WAIT_L(0); PG8_BAR; PG8_MMA(0, 0, At, B0); PG8_MMA(0, 1, At, B1); PG8_BAR; PG8_SCHED;
;             PG8_LDA(At, 0, 1); PG8_STAGE(PG8_SB(0, 0), b2, voffB); PG8_STAGE(PG8_SB(0, 1), b2 + hstepB, voffB); PG8_STAGE(PG8_SA(0, 0), a2, voffA);
;             PG8_WAIT_V(8); PG8_WAIT_L(0); PG8_BAR; PG8_MMA(1, 0, At, B0); PG8_MMA(1, 1, At, B1); PG8_BAR; PG8_SCHED;
.LBB0_2036:
	v_add_u32_e32 v144, s50, v213
	v_add_u32_e32 v160, s51, v213
	ds_read_b128 v[132:135], v144
	ds_read_b128 v[136:139], v144 offset:1024
	ds_read_b128 v[140:143], v144 offset:2048
	ds_read_b128 v[144:147], v144 offset:3072
	ds_read_b128 v[148:151], v160
	ds_read_b128 v[152:155], v160 offset:1024
	ds_read_b128 v[156:159], v160 offset:2048
	ds_read_b128 v[160:163], v160 offset:3072
	s_add_i32 s55, s55, 2
	s_add_u32 s34, s28, 0xfffc0080
	s_addc_u32 s35, s29, -1
	s_and_b64 s[30:31], s[30:31], exec
	s_cselect_b32 s35, s19, s35
	s_cselect_b32 s34, s21, s34
	s_cselect_b32 s31, s52, s54
	s_cselect_b32 s30, s53, s27
	v_lshl_add_u64 v[210:211], s[28:29], 0, v[196:197]
	s_add_i32 m0, s40, 0xc000
	ds_read_b128 v[164:167], v215
	ds_read_b128 v[168:171], v215 offset:1024
	ds_read_b128 v[172:175], v215 offset:2048
	ds_read_b128 v[176:179], v215 offset:3072
	ds_read_b128 v[180:183], v215 offset:4096
	ds_read_b128 v[202:205], v215 offset:5120
	ds_read_b128 v[206:209], v215 offset:6144
	ds_read_b128 v[218:221], v215 offset:7168
	global_load_lds_dwordx4 v[210:211], off
	v_lshl_add_u64 v[210:211], s[28:29], 0, v[194:195]
	s_add_i32 m0, s40, 0xe000
	s_nop 0
	global_load_lds_dwordx4 v[210:211], off
	s_waitcnt vmcnt(8)
	s_waitcnt lgkmcnt(0)
	s_barrier
	v_mfma_f32_16x16x32_bf16 v[124:127], v[132:135], v[164:167], v[124:127]
	v_mfma_f32_16x16x32_bf16 v[120:123], v[140:143], v[164:167], v[120:123]
	v_mfma_f32_16x16x32_bf16 v[108:111], v[132:135], v[172:175], v[108:111]
	v_mfma_f32_16x16x32_bf16 v[104:107], v[140:143], v[172:175], v[104:107]
	v_mfma_f32_16x16x32_bf16 v[92:95], v[132:135], v[180:183], v[92:95]
	v_mfma_f32_16x16x32_bf16 v[88:91], v[140:143], v[180:183], v[88:91]
	v_mfma_f32_16x16x32_bf16 v[76:79], v[132:135], v[206:209], v[76:79]
	v_mfma_f32_16x16x32_bf16 v[72:75], v[140:143], v[206:209], v[72:75]
	v_mfma_f32_16x16x32_bf16 v[124:127], v[136:139], v[168:171], v[124:127]
	v_mfma_f32_16x16x32_bf16 v[120:123], v[144:147], v[168:171], v[120:123]
	v_mfma_f32_16x16x32_bf16 v[108:111], v[136:139], v[176:179], v[108:111]
	v_mfma_f32_16x16x32_bf16 v[104:107], v[144:147], v[176:179], v[104:107]
	v_mfma_f32_16x16x32_bf16 v[92:95], v[136:139], v[202:205], v[92:95]
	v_mfma_f32_16x16x32_bf16 v[88:91], v[144:147], v[202:205], v[88:91]
	v_mfma_f32_16x16x32_bf16 v[76:79], v[136:139], v[218:221], v[76:79]
	v_mfma_f32_16x16x32_bf16 v[72:75], v[144:147], v[218:221], v[72:75]
	v_mfma_f32_16x16x32_bf16 v[116:119], v[148:151], v[164:167], v[116:119]
	v_mfma_f32_16x16x32_bf16 v[112:115], v[156:159], v[164:167], v[112:115]
	v_mfma_f32_16x16x32_bf16 v[100:103], v[148:151], v[172:175], v[100:103]
	v_mfma_f32_16x16x32_bf16 v[96:99], v[156:159], v[172:175], v[96:99]
	v_mfma_f32_16x16x32_bf16 v[84:87], v[148:151], v[180:183], v[84:87]
	v_mfma_f32_16x16x32_bf16 v[80:83], v[156:159], v[180:183], v[80:83]
	v_mfma_f32_16x16x32_bf16 v[68:71], v[148:151], v[206:209], v[68:71]
	v_mfma_f32_16x16x32_bf16 v[64:67], v[156:159], v[206:209], v[64:67]
	v_mfma_f32_16x16x32_bf16 v[116:119], v[152:155], v[168:171], v[116:119]
	v_mfma_f32_16x16x32_bf16 v[112:115], v[160:163], v[168:171], v[112:115]
	v_mfma_f32_16x16x32_bf16 v[100:103], v[152:155], v[176:179], v[100:103]
	v_mfma_f32_16x16x32_bf16 v[96:99], v[160:163], v[176:179], v[96:99]
	v_mfma_f32_16x16x32_bf16 v[84:87], v[152:155], v[202:205], v[84:87]
	v_mfma_f32_16x16x32_bf16 v[80:83], v[160:163], v[202:205], v[80:83]
	v_mfma_f32_16x16x32_bf16 v[68:71], v[152:155], v[218:221], v[68:71]
	v_mfma_f32_16x16x32_bf16 v[64:67], v[160:163], v[218:221], v[64:67]
	s_barrier
	s_add_i32 s56, s50, s39
	v_lshl_add_u64 v[210:211], s[30:31], 0, v[186:187]
	s_mov_b32 m0, s56
	ds_read_b128 v[164:167], v215 offset:16384
	ds_read_b128 v[168:171], v215 offset:17408
	ds_read_b128 v[172:175], v215 offset:18432
	ds_read_b128 v[176:179], v215 offset:19456
	ds_read_b128 v[180:183], v215 offset:20480
	ds_read_b128 v[202:205], v215 offset:21504
	ds_read_b128 v[206:209], v215 offset:22528
	ds_read_b128 v[218:221], v215 offset:23552
	global_load_lds_dwordx4 v[210:211], off
	s_add_i32 m0, s56, 0x2000
	s_add_u32 s56, s30, 0x40000
	v_lshl_add_u64 v[222:223], s[30:31], 0, v[190:191]
	s_addc_u32 s57, s31, 0
	s_add_i32 s58, s51, s39
	global_load_lds_dwordx4 v[222:223], off
	v_lshl_add_u64 v[224:225], s[56:57], 0, v[186:187]
	s_mov_b32 m0, s58
	v_lshl_add_u64 v[226:227], s[34:35], 0, v[188:189]
	global_load_lds_dwordx4 v[224:225], off
	v_lshl_add_u64 v[224:225], s[56:57], 0, v[190:191]
	s_add_i32 m0, s58, 0x2000
	s_nop 0
	global_load_lds_dwordx4 v[224:225], off
	v_lshl_add_u64 v[224:225], s[34:35], 0, v[184:185]
	s_mov_b32 m0, s40
	s_nop 0
	global_load_lds_dwordx4 v[224:225], off
	s_mov_b32 m0, s41
	s_nop 0
	global_load_lds_dwordx4 v[226:227], off
	s_waitcnt vmcnt(8)
	s_waitcnt lgkmcnt(0)
	s_barrier
; #define PG8_STAGE(bufoff, gbase, voff) do { _Pragma("unroll") for (int _i = 0; _i < 2; ++_i) \
;         __builtin_amdgcn_global_load_lds((const unsigned*)((const char*)(gbase) + (voff)[_i]), (LAS unsigned*)(lds + (bufoff) + ldsw + _i * 8192), 16, 0, 0); } while (0)
; #define PG8_LDA(dst, b, h) do { _Pragma("unroll") for (int m = 0; m < 4; ++m) _Pragma("unroll") for (int k = 0; k < 2; ++k) dst[m][k] = *(const LAS bf16x8*)(lds + PG8_SA(b, h) + aoff + m * 2048 + k * 1024); } while (0)
; #define PG8_LDB(dst, b, h) do { _Pragma("unroll") for (int n = 0; n < 2; ++n) _Pragma("unroll") for (int k = 0; k < 2; ++k) dst[n][k] = *(const LAS bf16x8*)(lds + PG8_SB(b, h) + boff + n * 2048 + k * 1024); } while (0)
; #define PG8_MMA(ai, bj, At, Bt) do { __builtin_amdgcn_s_setprio(1); _Pragma("unroll") for (int m = 0; m < 4; ++m) _Pragma("unroll") for (int n = 0; n < 2; ++n) _Pragma("unroll") for (int k = 0; k < 2; ++k) \
;         acc[ai][bj][m][n] = __builtin_amdgcn_mfma_f32_16x16x32_bf16(Bt[n][k], At[m][k], acc[ai][bj][m][n], 0, 0, 0); __builtin_amdgcn_s_setprio(0); } while (0)
; #define PG8_WAIT_V(n) asm volatile("s_waitcnt vmcnt(" #n ")" ::: "memory")
; #define PG8_WAIT_L(n) asm volatile("s_waitcnt lgkmcnt(" #n ")" ::: "memory")
; #define PG8_BAR __builtin_amdgcn_s_barrier()
; #define PG8_SCHED __builtin_amdgcn_sched_barrier(0)
; template <class Epi>
; __device__ __forceinline__ void gemm_phase(LAS unsigned char* lds, const int tid, const Gemm g, const StaticOrder& S, const Epi& E) {
;     ...
;             PG8_WAIT_V(8); PG8_WAIT_L(0); PG8_BAR; PG8_MMA(1, 0, At, B0); PG8_MMA(1, 1, At, B1); PG8_BAR; PG8_SCHED;
;             PG8_LDB(B0, 1, 0); PG8_LDB(B1, 1, 1); PG8_SCHED; PG8_LDA(At, 1, 0); PG8_STAGE(PG8_SA(0, 1), a2 + hstepA, voffA);
;             PG8_WAIT_V(8); PG8_WAIT_L(0); PG8_BAR; PG8_MMA(0, 0, At, B0); PG8_MMA(0, 1, At, B1); PG8_BAR; PG8_SCHED;
	v_mfma_f32_16x16x32_bf16 v[60:63], v[132:135], v[164:167], v[60:63]
	v_mfma_f32_16x16x32_bf16 v[56:59], v[140:143], v[164:167], v[56:59]
	v_mfma_f32_16x16x32_bf16 v[44:47], v[132:135], v[172:175], v[44:47]
	v_mfma_f32_16x16x32_bf16 v[40:43], v[140:143], v[172:175], v[40:43]
	v_mfma_f32_16x16x32_bf16 v[28:31], v[132:135], v[180:183], v[28:31]
	v_mfma_f32_16x16x32_bf16 v[24:27], v[140:143], v[180:183], v[24:27]
	v_mfma_f32_16x16x32_bf16 v[12:15], v[132:135], v[206:209], v[12:15]
	v_mfma_f32_16x16x32_bf16 v[8:11], v[140:143], v[206:209], v[8:11]
	v_mfma_f32_16x16x32_bf16 v[60:63], v[136:139], v[168:171], v[60:63]
	v_mfma_f32_16x16x32_bf16 v[56:59], v[144:147], v[168:171], v[56:59]
	v_mfma_f32_16x16x32_bf16 v[44:47], v[136:139], v[176:179], v[44:47]
	v_mfma_f32_16x16x32_bf16 v[40:43], v[144:147], v[176:179], v[40:43]
	v_mfma_f32_16x16x32_bf16 v[28:31], v[136:139], v[202:205], v[28:31]
	v_mfma_f32_16x16x32_bf16 v[24:27], v[144:147], v[202:205], v[24:27]
	v_mfma_f32_16x16x32_bf16 v[12:15], v[136:139], v[218:221], v[12:15]
	v_mfma_f32_16x16x32_bf16 v[8:11], v[144:147], v[218:221], v[8:11]
	v_mfma_f32_16x16x32_bf16 v[52:55], v[148:151], v[164:167], v[52:55]
	v_mfma_f32_16x16x32_bf16 v[48:51], v[156:159], v[164:167], v[48:51]
	v_mfma_f32_16x16x32_bf16 v[36:39], v[148:151], v[172:175], v[36:39]
	v_mfma_f32_16x16x32_bf16 v[32:35], v[156:159], v[172:175], v[32:35]
	v_mfma_f32_16x16x32_bf16 v[20:23], v[148:151], v[180:183], v[20:23]
	v_mfma_f32_16x16x32_bf16 v[16:19], v[156:159], v[180:183], v[16:19]
	v_mfma_f32_16x16x32_bf16 v[4:7], v[148:151], v[206:209], v[4:7]
	v_mfma_f32_16x16x32_bf16 v[0:3], v[156:159], v[206:209], v[0:3]
	v_mfma_f32_16x16x32_bf16 v[52:55], v[152:155], v[168:171], v[52:55]
	v_mfma_f32_16x16x32_bf16 v[48:51], v[160:163], v[168:171], v[48:51]
	v_mfma_f32_16x16x32_bf16 v[36:39], v[152:155], v[176:179], v[36:39]
	v_mfma_f32_16x16x32_bf16 v[32:35], v[160:163], v[176:179], v[32:35]
	v_mfma_f32_16x16x32_bf16 v[20:23], v[152:155], v[202:205], v[20:23]
	v_mfma_f32_16x16x32_bf16 v[16:19], v[160:163], v[202:205], v[16:19]
	v_mfma_f32_16x16x32_bf16 v[4:7], v[152:155], v[218:221], v[4:7]
	v_mfma_f32_16x16x32_bf16 v[0:3], v[160:163], v[218:221], v[0:3]
	s_barrier
	s_add_i32 s56, 0, 0x18000
	s_add_i32 s57, 0, 0x1c000
	v_add_u32_e32 v144, s56, v213
	v_add_u32_e32 v160, s57, v213
	ds_read_b128 v[132:135], v144
	ds_read_b128 v[136:139], v144 offset:1024
	ds_read_b128 v[140:143], v144 offset:2048
	ds_read_b128 v[144:147], v144 offset:3072
	ds_read_b128 v[148:151], v160
	ds_read_b128 v[152:155], v160 offset:1024
	ds_read_b128 v[156:159], v160 offset:2048
	ds_read_b128 v[160:163], v160 offset:3072
	s_add_u32 s34, s34, 0x40000
	s_addc_u32 s35, s35, 0
	s_mov_b32 m0, s42
	v_lshl_add_u64 v[228:229], s[34:35], 0, v[184:185]
	ds_read_b128 v[164:167], v215 offset:32768
	ds_read_b128 v[168:171], v215 offset:33792
	ds_read_b128 v[172:175], v215 offset:34816
	ds_read_b128 v[176:179], v215 offset:35840
	ds_read_b128 v[180:183], v215 offset:36864
	ds_read_b128 v[202:205], v215 offset:37888
	ds_read_b128 v[206:209], v215 offset:38912
	ds_read_b128 v[218:221], v215 offset:39936
	global_load_lds_dwordx4 v[228:229], off
	v_lshl_add_u64 v[228:229], s[34:35], 0, v[188:189]
	s_mov_b32 m0, s43
	s_nop 0
	global_load_lds_dwordx4 v[228:229], off
	s_waitcnt vmcnt(8)
	s_waitcnt lgkmcnt(0)
	s_barrier
	v_mfma_f32_16x16x32_bf16 v[124:127], v[132:135], v[164:167], v[124:127]
	v_mfma_f32_16x16x32_bf16 v[120:123], v[140:143], v[164:167], v[120:123]
	v_mfma_f32_16x16x32_bf16 v[108:111], v[132:135], v[172:175], v[108:111]
	v_mfma_f32_16x16x32_bf16 v[104:107], v[140:143], v[172:175], v[104:107]
	v_mfma_f32_16x16x32_bf16 v[92:95], v[132:135], v[180:183], v[92:95]
	v_mfma_f32_16x16x32_bf16 v[88:91], v[140:143], v[180:183], v[88:91]
	v_mfma_f32_16x16x32_bf16 v[76:79], v[132:135], v[206:209], v[76:79]
	v_mfma_f32_16x16x32_bf16 v[72:75], v[140:143], v[206:209], v[72:75]
	v_mfma_f32_16x16x32_bf16 v[124:127], v[136:139], v[168:171], v[124:127]
	v_mfma_f32_16x16x32_bf16 v[120:123], v[144:147], v[168:171], v[120:123]
	v_mfma_f32_16x16x32_bf16 v[108:111], v[136:139], v[176:179], v[108:111]
	v_mfma_f32_16x16x32_bf16 v[104:107], v[144:147], v[176:179], v[104:107]
	v_mfma_f32_16x16x32_bf16 v[92:95], v[136:139], v[202:205], v[92:95]
	v_mfma_f32_16x16x32_bf16 v[88:91], v[144:147], v[202:205], v[88:91]
	v_mfma_f32_16x16x32_bf16 v[76:79], v[136:139], v[218:221], v[76:79]
	v_mfma_f32_16x16x32_bf16 v[72:75], v[144:147], v[218:221], v[72:75]
	v_mfma_f32_16x16x32_bf16 v[116:119], v[148:151], v[164:167], v[116:119]
	v_mfma_f32_16x16x32_bf16 v[112:115], v[156:159], v[164:167], v[112:115]
	v_mfma_f32_16x16x32_bf16 v[100:103], v[148:151], v[172:175], v[100:103]
	v_mfma_f32_16x16x32_bf16 v[96:99], v[156:159], v[172:175], v[96:99]
	v_mfma_f32_16x16x32_bf16 v[84:87], v[148:151], v[180:183], v[84:87]
	v_mfma_f32_16x16x32_bf16 v[80:83], v[156:159], v[180:183], v[80:83]
	v_mfma_f32_16x16x32_bf16 v[68:71], v[148:151], v[206:209], v[68:71]
	v_mfma_f32_16x16x32_bf16 v[64:67], v[156:159], v[206:209], v[64:67]
	v_mfma_f32_16x16x32_bf16 v[116:119], v[152:155], v[168:171], v[116:119]
	v_mfma_f32_16x16x32_bf16 v[112:115], v[160:163], v[168:171], v[112:115]
	v_mfma_f32_16x16x32_bf16 v[100:103], v[152:155], v[176:179], v[100:103]
	v_mfma_f32_16x16x32_bf16 v[96:99], v[160:163], v[176:179], v[96:99]
	v_mfma_f32_16x16x32_bf16 v[84:87], v[152:155], v[202:205], v[84:87]
	v_mfma_f32_16x16x32_bf16 v[80:83], v[160:163], v[202:205], v[80:83]
	v_mfma_f32_16x16x32_bf16 v[68:71], v[152:155], v[218:221], v[68:71]
	v_mfma_f32_16x16x32_bf16 v[64:67], v[160:163], v[218:221], v[64:67]
	s_barrier
; #define PG8_STAGE(bufoff, gbase, voff) do { _Pragma("unroll") for (int _i = 0; _i < 2; ++_i) \
;         __builtin_amdgcn_global_load_lds((const unsigned*)((const char*)(gbase) + (voff)[_i]), (LAS unsigned*)(lds + (bufoff) + ldsw + _i * 8192), 16, 0, 0); } while (0)
; #define PG8_LDA(dst, b, h) do { _Pragma("unroll") for (int m = 0; m < 4; ++m) _Pragma("unroll") for (int k = 0; k < 2; ++k) dst[m][k] = *(const LAS bf16x8*)(lds + PG8_SA(b, h) + aoff + m * 2048 + k * 1024); } while (0)
; #define PG8_MMA(ai, bj, At, Bt) do { __builtin_amdgcn_s_setprio(1); _Pragma("unroll") for (int m = 0; m < 4; ++m) _Pragma("unroll") for (int n = 0; n < 2; ++n) _Pragma("unroll") for (int k = 0; k < 2; ++k) \
;         acc[ai][bj][m][n] = __builtin_amdgcn_mfma_f32_16x16x32_bf16(Bt[n][k], At[m][k], acc[ai][bj][m][n], 0, 0, 0); __builtin_amdgcn_s_setprio(0); } while (0)
; #define PG8_WAIT_V(n) asm volatile("s_waitcnt vmcnt(" #n ")" ::: "memory")
; #define PG8_WAIT_L(n) asm volatile("s_waitcnt lgkmcnt(" #n ")" ::: "memory")
; #define PG8_BAR __builtin_amdgcn_s_barrier()
; #define PG8_SCHED __builtin_amdgcn_sched_barrier(0)
; template <class Epi>
; __device__ __forceinline__ void gemm_phase(LAS unsigned char* lds, const int tid, const Gemm g, const StaticOrder& S, const Epi& E) {
;     ...
;         for (int t = 0; t < nt; t += 2) {
;     ...
;             PG8_LDA(At, 1, 1); PG8_STAGE(PG8_SB(1, 0), b3, voffB); PG8_STAGE(PG8_SB(1, 1), b3 + hstepB, voffB); PG8_STAGE(PG8_SA(1, 0), a3, voffA);
;             PG8_WAIT_V(8); PG8_WAIT_L(0); PG8_BAR; PG8_MMA(1, 0, At, B0); PG8_MMA(1, 1, At, B1); PG8_BAR; PG8_SCHED;
	s_add_i32 s34, s56, s39
	v_lshl_add_u64 v[210:211], v[210:211], 0, s[12:13]
	s_mov_b32 m0, s34
	ds_read_b128 v[164:167], v215 offset:49152
	ds_read_b128 v[168:171], v215 offset:50176
	ds_read_b128 v[172:175], v215 offset:51200
	ds_read_b128 v[176:179], v215 offset:52224
	ds_read_b128 v[180:183], v215 offset:53248
	ds_read_b128 v[202:205], v215 offset:54272
	ds_read_b128 v[206:209], v215 offset:55296
	ds_read_b128 v[218:221], v215 offset:56320
	global_load_lds_dwordx4 v[210:211], off
	s_add_i32 m0, s34, 0x2000
	s_add_u32 s30, s30, 0x40080
	v_lshl_add_u64 v[210:211], v[222:223], 0, s[12:13]
	s_addc_u32 s31, s31, 0
	s_add_i32 s34, s57, s39
	global_load_lds_dwordx4 v[210:211], off
	v_lshl_add_u64 v[210:211], s[30:31], 0, v[186:187]
	s_mov_b32 m0, s34
	s_nop 0
	global_load_lds_dwordx4 v[210:211], off
	v_lshl_add_u64 v[210:211], s[30:31], 0, v[190:191]
	s_add_i32 m0, s34, 0x2000
	s_nop 0
	global_load_lds_dwordx4 v[210:211], off
	v_lshl_add_u64 v[210:211], v[224:225], 0, s[12:13]
	s_mov_b32 m0, s46
	s_nop 0
	global_load_lds_dwordx4 v[210:211], off
	v_lshl_add_u64 v[210:211], v[226:227], 0, s[12:13]
	s_mov_b32 m0, s47
	s_nop 0
	global_load_lds_dwordx4 v[210:211], off
	s_waitcnt vmcnt(8)
	s_waitcnt lgkmcnt(0)
	s_barrier
	v_mfma_f32_16x16x32_bf16 v[60:63], v[132:135], v[164:167], v[60:63]
	v_mfma_f32_16x16x32_bf16 v[56:59], v[140:143], v[164:167], v[56:59]
	v_mfma_f32_16x16x32_bf16 v[44:47], v[132:135], v[172:175], v[44:47]
	v_mfma_f32_16x16x32_bf16 v[40:43], v[140:143], v[172:175], v[40:43]
	v_mfma_f32_16x16x32_bf16 v[28:31], v[132:135], v[180:183], v[28:31]
	v_mfma_f32_16x16x32_bf16 v[24:27], v[140:143], v[180:183], v[24:27]
	v_mfma_f32_16x16x32_bf16 v[12:15], v[132:135], v[206:209], v[12:15]
	v_mfma_f32_16x16x32_bf16 v[8:11], v[140:143], v[206:209], v[8:11]
	v_mfma_f32_16x16x32_bf16 v[60:63], v[136:139], v[168:171], v[60:63]
	v_mfma_f32_16x16x32_bf16 v[56:59], v[144:147], v[168:171], v[56:59]
	v_mfma_f32_16x16x32_bf16 v[44:47], v[136:139], v[176:179], v[44:47]
	v_mfma_f32_16x16x32_bf16 v[40:43], v[144:147], v[176:179], v[40:43]
	v_mfma_f32_16x16x32_bf16 v[28:31], v[136:139], v[202:205], v[28:31]
	v_mfma_f32_16x16x32_bf16 v[24:27], v[144:147], v[202:205], v[24:27]
	v_mfma_f32_16x16x32_bf16 v[12:15], v[136:139], v[218:221], v[12:15]
	v_mfma_f32_16x16x32_bf16 v[8:11], v[144:147], v[218:221], v[8:11]
	v_mfma_f32_16x16x32_bf16 v[52:55], v[148:151], v[164:167], v[52:55]
	v_mfma_f32_16x16x32_bf16 v[48:51], v[156:159], v[164:167], v[48:51]
	v_mfma_f32_16x16x32_bf16 v[36:39], v[148:151], v[172:175], v[36:39]
	v_mfma_f32_16x16x32_bf16 v[32:35], v[156:159], v[172:175], v[32:35]
	v_mfma_f32_16x16x32_bf16 v[20:23], v[148:151], v[180:183], v[20:23]
	v_mfma_f32_16x16x32_bf16 v[16:19], v[156:159], v[180:183], v[16:19]
	v_mfma_f32_16x16x32_bf16 v[4:7], v[148:151], v[206:209], v[4:7]
	v_mfma_f32_16x16x32_bf16 v[0:3], v[156:159], v[206:209], v[0:3]
	v_mfma_f32_16x16x32_bf16 v[52:55], v[152:155], v[168:171], v[52:55]
	v_mfma_f32_16x16x32_bf16 v[48:51], v[160:163], v[168:171], v[48:51]
	v_mfma_f32_16x16x32_bf16 v[36:39], v[152:155], v[176:179], v[36:39]
	v_mfma_f32_16x16x32_bf16 v[32:35], v[160:163], v[176:179], v[32:35]
	v_mfma_f32_16x16x32_bf16 v[20:23], v[152:155], v[202:205], v[20:23]
	v_mfma_f32_16x16x32_bf16 v[16:19], v[160:163], v[202:205], v[16:19]
	v_mfma_f32_16x16x32_bf16 v[4:7], v[152:155], v[218:221], v[4:7]
	v_mfma_f32_16x16x32_bf16 v[0:3], v[160:163], v[218:221], v[0:3]
	s_barrier
	s_add_u32 s27, s27, 0x100
	s_addc_u32 s54, s54, 0
	s_add_u32 s28, s28, 0x100
	s_addc_u32 s29, s29, 0
	s_cmp_ge_i32 s55, s45
	s_cbranch_scc1 .LBB0_2039
